# v030 + all per-MFMA-block s_setprio 1/0 flips deleted from the eight GEMM K-loops (every wave stays at priority 0)
# speedup vs baseline: 1.0061x; 1.0061x over previous
; __device__ __forceinline__ int lane_id() { int l; asm volatile("v_mbcnt_lo_u32_b32 %0, -1, 0\n\tv_mbcnt_hi_u32_b32 %0, -1, %0" : "=v"(l)); return l; }
;     __device__ __forceinline__ bool next(int i, UnitG& u) const { if (!P.next(i, u)) return false; u.O = O + ((size_t)u.x0 * 256 * 2048 + (size_t)u.x1 * 256) * 2; u.ldo = 2048; u.kind = 0; return true; }
; template <class Epi, class Sched>
; __device__ __forceinline__ void gemm_phase(PG8_LAS unsigned char* lds, const Sched& S, const Epi& E, int tid_in) {
;     ...
;     for (;;) {
;         int aoff, boff; { const int l3 = lane_id(), fr3 = l3 & 15, fq3 = l3 >> 4; aoff = lds_byte(wr * 64 + fr3, fq3 * 8); boff = lds_byte(wc * 32 + fr3, fq3 * 8); }
;         const bool has_next = S.next(ui + 1, nxt);
;         const char* nA = has_next ? nxt.A : cA; const char* nB = has_next ? nxt.B : cB;
;         const int nlda = has_next ? nxt.lda : cur.lda, nldb = has_next ? nxt.ldb : cur.ldb;
;         unsigned nvA, nvB; { int r2, c2; stage_rc((wid * 64 + lane_id()) * 16, r2, c2); const int rb2 = Epi::PERM ? ((r2 & ~31) + perm32(r2 & 31)) : r2;
;             nvA = (unsigned)(r2 * nlda + c2) * 2u; nvB = (unsigned)(rb2 * nldb + c2) * 2u; }
;         const unsigned nqA = (unsigned)nlda * 128u, nqB = (unsigned)nldb * 128u;
;         const int nt = cur.K / BK;
.LBB0_206:
	v_and_b32_e32 v1, 15, v0
	v_or_b32_e32 v2, s50, v1
	v_ashrrev_i32_e32 v3, 6, v0
	v_lshlrev_b32_e32 v4, 6, v2
	v_and_b32_e32 v5, 48, v0
	s_movk_i32 s57, 0x3c0
	v_lshlrev_b32_e32 v2, 2, v2
	v_and_or_b32 v4, v4, s57, v5
	v_lshl_add_u32 v6, v3, 10, s51
	v_and_b32_e32 v2, 32, v2
	v_lshlrev_b32_e32 v0, 2, v0
	s_waitcnt vmcnt(0)
	v_bitop3_b32 v32, v4, v6, v2 bitop3:0xde
	v_lshl_or_b32 v1, v1, 6, v5
	v_add_lshl_u32 v2, v3, s53, 10
	v_and_b32_e32 v0, 32, v0
	v_bitop3_b32 v137, v1, v2, v0 bitop3:0xde
	v_mbcnt_lo_u32_b32 v0, -1, 0
	v_mbcnt_hi_u32_b32 v0, -1, v0
	s_mov_b32 s57, 0xfffe0
	v_add_u32_e32 v0, s54, v0
	v_ashrrev_i32_e32 v2, 31, v0
	v_lshrrev_b32_e32 v2, 26, v2
	v_lshlrev_b32_e32 v1, 4, v0
	v_add_u32_e32 v2, v0, v2
	v_bfe_i32 v0, v0, 27, 1
	v_lshrrev_b32_e32 v0, 22, v0
	v_add_u32_e32 v0, v1, v0
	v_and_b32_e32 v0, 0xfffffc00, v0
	v_sub_u32_e32 v0, v1, v0
	v_lshrrev_b32_e32 v1, 4, v0
	v_bitop3_b32 v0, v1, v0, 32 bitop3:0x6c
	v_ashrrev_i32_e32 v3, 31, v0
	v_lshrrev_b32_e32 v3, 26, v3
	v_ashrrev_i32_e32 v2, 6, v2
	v_add_u32_e32 v3, v0, v3
	v_lshlrev_b32_e32 v1, 3, v2
	v_ashrrev_i32_e32 v4, 6, v3
	v_and_b32_e32 v3, 0xc0, v3
	v_and_b32_e32 v1, -16, v1
	v_sub_u32_e32 v0, v0, v3
	v_add_u32_e32 v1, v4, v1
	v_lshlrev_b32_e32 v2, 5, v2
	v_ashrrev_i16_sdwa v0, v205, sext(v0) dst_sel:DWORD dst_unused:UNUSED_PAD src0_sel:DWORD src1_sel:BYTE_0
	v_and_b32_e32 v2, 32, v2
	v_bfe_i32 v0, v0, 0, 16
	v_lshlrev_b32_e32 v3, 1, v1
	v_lshrrev_b32_e32 v5, 2, v1
	v_and_b32_e32 v4, 3, v4
	s_add_i32 s59, 0, 0x10000
	s_add_i32 s61, 0, 0x14000
	v_and_b32_e32 v3, 24, v3
	v_and_b32_e32 v5, 4, v5
	v_and_or_b32 v4, v1, s57, v4
	v_add_lshl_u32 v34, v2, v0, 1
	v_add_u32_e32 v134, s59, v137
	v_add_u32_e32 v135, s61, v137
	v_or3_b32 v33, v4, v5, v3
	v_lshl_add_u32 v128, v1, 12, v34
	ds_read_b128 v[0:3], v134
	ds_read_b128 v[4:7], v134 offset:1024
	ds_read_b128 v[8:11], v134 offset:2048
	ds_read_b128 v[12:15], v134 offset:3072
	ds_read_b128 v[16:19], v135
	ds_read_b128 v[20:23], v135 offset:1024
	ds_read_b128 v[24:27], v135 offset:2048
	ds_read_b128 v[28:31], v135 offset:3072
	v_lshl_add_u32 v129, v33, 12, v34
	v_mov_b32_e32 v133, v185
	v_lshl_add_u64 v[182:183], s[20:21], 0, v[132:133]
	s_add_i32 s57, s7, 0xc000
	v_add_u32_e32 v136, 0, v32
	v_lshl_add_u64 v[64:65], v[182:183], 0, s[80:81]
	s_mov_b32 m0, s57
	s_add_i32 s58, s7, 0xe000
	ds_read_b128 v[32:35], v136
	ds_read_b128 v[36:39], v136 offset:1024
	ds_read_b128 v[40:43], v136 offset:2048
	ds_read_b128 v[44:47], v136 offset:3072
	ds_read_b128 v[48:51], v136 offset:4096
	ds_read_b128 v[52:55], v136 offset:5120
	ds_read_b128 v[56:59], v136 offset:6144
	ds_read_b128 v[60:63], v136 offset:7168
	global_load_lds_dwordx4 v[64:65], off
	v_lshl_add_u64 v[64:65], v[182:183], 0, s[78:79]
	s_mov_b32 m0, s58
	s_nop 0
	global_load_lds_dwordx4 v[64:65], off
	s_waitcnt vmcnt(16)
	s_waitcnt lgkmcnt(0)
	s_barrier
	s_waitcnt lgkmcnt(0)
	v_mfma_f32_16x16x32_bf16 v[64:67], v[0:3], v[32:35], 0
	v_mfma_f32_16x16x32_bf16 v[68:71], v[8:11], v[32:35], 0
	v_mfma_f32_16x16x32_bf16 v[72:75], v[0:3], v[40:43], 0
	v_mfma_f32_16x16x32_bf16 v[76:79], v[8:11], v[40:43], 0
	v_mfma_f32_16x16x32_bf16 v[80:83], v[0:3], v[48:51], 0
	v_mfma_f32_16x16x32_bf16 v[84:87], v[8:11], v[48:51], 0
	v_mfma_f32_16x16x32_bf16 v[88:91], v[0:3], v[56:59], 0
	v_mfma_f32_16x16x32_bf16 v[92:95], v[8:11], v[56:59], 0
	v_mfma_f32_16x16x32_bf16 v[64:67], v[4:7], v[36:39], v[64:67]
	v_mfma_f32_16x16x32_bf16 v[68:71], v[12:15], v[36:39], v[68:71]
	v_mfma_f32_16x16x32_bf16 v[72:75], v[4:7], v[44:47], v[72:75]
	v_mfma_f32_16x16x32_bf16 v[76:79], v[12:15], v[44:47], v[76:79]
	v_mfma_f32_16x16x32_bf16 v[80:83], v[4:7], v[52:55], v[80:83]
	v_mfma_f32_16x16x32_bf16 v[84:87], v[12:15], v[52:55], v[84:87]
	v_mfma_f32_16x16x32_bf16 v[88:91], v[4:7], v[60:63], v[88:91]
	v_mfma_f32_16x16x32_bf16 v[100:103], v[12:15], v[60:63], v[92:95]
	v_mfma_f32_16x16x32_bf16 v[92:95], v[16:19], v[32:35], 0
	v_mfma_f32_16x16x32_bf16 v[32:35], v[24:27], v[32:35], 0
	v_mfma_f32_16x16x32_bf16 v[104:107], v[20:23], v[36:39], v[92:95]
	v_mfma_f32_16x16x32_bf16 v[32:35], v[28:31], v[36:39], v[32:35]
	v_mfma_f32_16x16x32_bf16 v[36:39], v[16:19], v[40:43], 0
	v_mfma_f32_16x16x32_bf16 v[40:43], v[24:27], v[40:43], 0
	v_mfma_f32_16x16x32_bf16 v[36:39], v[20:23], v[44:47], v[36:39]
	v_mfma_f32_16x16x32_bf16 v[40:43], v[28:31], v[44:47], v[40:43]
	v_mfma_f32_16x16x32_bf16 v[44:47], v[16:19], v[48:51], 0
	v_mfma_f32_16x16x32_bf16 v[48:51], v[24:27], v[48:51], 0
	v_mfma_f32_16x16x32_bf16 v[44:47], v[20:23], v[52:55], v[44:47]
	v_mfma_f32_16x16x32_bf16 v[48:51], v[28:31], v[52:55], v[48:51]
	v_mfma_f32_16x16x32_bf16 v[52:55], v[16:19], v[56:59], 0
	v_mfma_f32_16x16x32_bf16 v[56:59], v[24:27], v[56:59], 0
	v_mfma_f32_16x16x32_bf16 v[52:55], v[20:23], v[60:63], v[52:55]
	v_mfma_f32_16x16x32_bf16 v[56:59], v[28:31], v[60:63], v[56:59]
	s_barrier
	v_mov_b32_e32 v131, v185
	v_lshl_add_u64 v[248:249], s[22:23], 0, v[130:131]
	s_mov_b64 s[64:65], 0x100
	s_add_i32 s59, s59, s30
	v_lshl_add_u64 v[138:139], v[248:249], 0, s[64:65]
	s_mov_b32 m0, s59
	s_mov_b64 s[66:67], 0x40100
	s_add_i32 s60, s59, 0x2000
	ds_read_b128 v[60:63], v136 offset:16384
	ds_read_b128 v[92:95], v136 offset:17408
	ds_read_b128 v[96:99], v136 offset:18432
	ds_read_b128 v[108:111], v136 offset:19456
	ds_read_b128 v[112:115], v136 offset:20480
	ds_read_b128 v[116:119], v136 offset:21504
	ds_read_b128 v[120:123], v136 offset:22528
	ds_read_b128 v[124:127], v136 offset:23552
	global_load_lds_dwordx4 v[138:139], off
	v_lshl_add_u64 v[138:139], v[248:249], 0, s[66:67]
	s_mov_b32 m0, s60
	s_mov_b64 s[70:71], 0x80100
	s_add_i32 s61, s61, s30
	global_load_lds_dwordx4 v[138:139], off
	v_lshl_add_u64 v[138:139], v[248:249], 0, s[70:71]
	s_mov_b32 m0, s61
	s_mov_b64 s[72:73], 0xc0100
	s_add_i32 s62, s61, 0x2000
	global_load_lds_dwordx4 v[138:139], off
	v_lshl_add_u64 v[138:139], v[248:249], 0, s[72:73]
	s_mov_b32 m0, s62
	s_nop 0
	global_load_lds_dwordx4 v[138:139], off
	v_lshl_add_u64 v[138:139], v[182:183], 0, s[64:65]
	s_mov_b32 m0, s7
	s_nop 0
	global_load_lds_dwordx4 v[138:139], off
	v_lshl_add_u64 v[138:139], v[182:183], 0, s[66:67]
	s_mov_b32 m0, s31
	s_nop 0
	global_load_lds_dwordx4 v[138:139], off
	s_waitcnt vmcnt(16)
	s_waitcnt lgkmcnt(0)
	s_barrier
	s_waitcnt lgkmcnt(0)
	v_mfma_f32_16x16x32_bf16 v[138:141], v[0:3], v[60:63], 0
	v_mfma_f32_16x16x32_bf16 v[146:149], v[0:3], v[96:99], 0
	v_mfma_f32_16x16x32_bf16 v[154:157], v[0:3], v[112:115], 0
	v_mfma_f32_16x16x32_bf16 v[0:3], v[0:3], v[120:123], 0
	v_mfma_f32_16x16x32_bf16 v[138:141], v[4:7], v[92:95], v[138:141]
	v_mfma_f32_16x16x32_bf16 v[146:149], v[4:7], v[108:111], v[146:149]
	v_mfma_f32_16x16x32_bf16 v[154:157], v[4:7], v[116:119], v[154:157]
	v_mfma_f32_16x16x32_bf16 v[0:3], v[4:7], v[124:127], v[0:3]
	v_mfma_f32_16x16x32_bf16 v[4:7], v[8:11], v[120:123], 0
	v_mfma_f32_16x16x32_bf16 v[142:145], v[8:11], v[60:63], 0
	v_mfma_f32_16x16x32_bf16 v[150:153], v[8:11], v[96:99], 0
	v_mfma_f32_16x16x32_bf16 v[158:161], v[8:11], v[112:115], 0
	v_mfma_f32_16x16x32_bf16 v[4:7], v[12:15], v[124:127], v[4:7]
	v_mfma_f32_16x16x32_bf16 v[142:145], v[12:15], v[92:95], v[142:145]
	v_mfma_f32_16x16x32_bf16 v[150:153], v[12:15], v[108:111], v[150:153]
	v_mfma_f32_16x16x32_bf16 v[158:161], v[12:15], v[116:119], v[158:161]
	v_mfma_f32_16x16x32_bf16 v[12:15], v[24:27], v[60:63], 0
	v_mfma_f32_16x16x32_bf16 v[162:165], v[28:31], v[92:95], v[12:15]
	v_mfma_f32_16x16x32_bf16 v[12:15], v[16:19], v[96:99], 0
	v_mfma_f32_16x16x32_bf16 v[166:169], v[20:23], v[108:111], v[12:15]
	v_mfma_f32_16x16x32_bf16 v[12:15], v[24:27], v[96:99], 0
	v_mfma_f32_16x16x32_bf16 v[170:173], v[28:31], v[108:111], v[12:15]
	v_mfma_f32_16x16x32_bf16 v[12:15], v[16:19], v[112:115], 0
	v_mfma_f32_16x16x32_bf16 v[174:177], v[20:23], v[116:119], v[12:15]
	v_mfma_f32_16x16x32_bf16 v[12:15], v[24:27], v[112:115], 0
	v_mfma_f32_16x16x32_bf16 v[8:11], v[16:19], v[60:63], 0
	v_mfma_f32_16x16x32_bf16 v[178:181], v[28:31], v[116:119], v[12:15]
	v_mfma_f32_16x16x32_bf16 v[12:15], v[16:19], v[120:123], 0
	v_mfma_f32_16x16x32_bf16 v[8:11], v[20:23], v[92:95], v[8:11]
	v_mfma_f32_16x16x32_bf16 v[188:191], v[20:23], v[124:127], v[12:15]
	v_mfma_f32_16x16x32_bf16 v[12:15], v[24:27], v[120:123], 0
	v_mfma_f32_16x16x32_bf16 v[192:195], v[28:31], v[124:127], v[12:15]
	s_barrier
	s_add_i32 s63, 0, 0x18000
	s_add_i32 s65, 0, 0x1c000
	v_add_u32_e32 v131, s63, v137
	v_add_u32_e32 v137, s65, v137
	s_nop 0
	ds_read_b128 v[12:15], v131
	ds_read_b128 v[20:23], v131 offset:1024
	ds_read_b128 v[24:27], v131 offset:2048
	ds_read_b128 v[196:199], v131 offset:3072
	ds_read_b128 v[200:203], v137
	ds_read_b128 v[212:215], v137 offset:1024
	ds_read_b128 v[216:219], v137 offset:2048
	ds_read_b128 v[220:223], v137 offset:3072
	s_mov_b32 m0, s34
	v_lshl_add_u64 v[92:93], v[182:183], 0, s[70:71]
	ds_read_b128 v[16:19], v136 offset:32768
	ds_read_b128 v[28:31], v136 offset:33792
	ds_read_b128 v[60:63], v136 offset:34816
	ds_read_b128 v[224:227], v136 offset:35840
	ds_read_b128 v[228:231], v136 offset:36864
	ds_read_b128 v[232:235], v136 offset:37888
	ds_read_b128 v[236:239], v136 offset:38912
	ds_read_b128 v[240:243], v136 offset:39936
	global_load_lds_dwordx4 v[92:93], off
	v_lshl_add_u64 v[92:93], v[182:183], 0, s[72:73]
	s_mov_b32 m0, s35
	s_nop 0
	global_load_lds_dwordx4 v[92:93], off
	s_waitcnt vmcnt(8)
	s_waitcnt lgkmcnt(0)
	s_barrier
	s_waitcnt lgkmcnt(0)
	v_mfma_f32_16x16x32_bf16 v[64:67], v[12:15], v[16:19], v[64:67]
	v_mfma_f32_16x16x32_bf16 v[124:127], v[20:23], v[28:31], v[64:67]
	v_mfma_f32_16x16x32_bf16 v[64:67], v[24:27], v[16:19], v[68:71]
	v_mfma_f32_16x16x32_bf16 v[112:115], v[196:199], v[28:31], v[64:67]
	v_mfma_f32_16x16x32_bf16 v[64:67], v[12:15], v[60:63], v[72:75]
	v_mfma_f32_16x16x32_bf16 v[108:111], v[20:23], v[224:227], v[64:67]
	v_mfma_f32_16x16x32_bf16 v[64:67], v[24:27], v[60:63], v[76:79]
	v_mfma_f32_16x16x32_bf16 v[96:99], v[196:199], v[224:227], v[64:67]
	v_mfma_f32_16x16x32_bf16 v[64:67], v[12:15], v[228:231], v[80:83]
	v_mfma_f32_16x16x32_bf16 v[92:95], v[20:23], v[232:235], v[64:67]
	v_mfma_f32_16x16x32_bf16 v[64:67], v[24:27], v[228:231], v[84:87]
	v_mfma_f32_16x16x32_bf16 v[80:83], v[196:199], v[232:235], v[64:67]
	v_mfma_f32_16x16x32_bf16 v[64:67], v[12:15], v[236:239], v[88:91]
	v_mfma_f32_16x16x32_bf16 v[76:79], v[20:23], v[240:243], v[64:67]
	v_mfma_f32_16x16x32_bf16 v[64:67], v[24:27], v[236:239], v[100:103]
	v_mfma_f32_16x16x32_bf16 v[64:67], v[196:199], v[240:243], v[64:67]
	v_mfma_f32_16x16x32_bf16 v[68:71], v[200:203], v[16:19], v[104:107]
	v_mfma_f32_16x16x32_bf16 v[16:19], v[216:219], v[16:19], v[32:35]
	v_mfma_f32_16x16x32_bf16 v[116:119], v[220:223], v[28:31], v[16:19]
	v_mfma_f32_16x16x32_bf16 v[16:19], v[200:203], v[60:63], v[36:39]
	v_mfma_f32_16x16x32_bf16 v[104:107], v[212:215], v[224:227], v[16:19]
	v_mfma_f32_16x16x32_bf16 v[16:19], v[216:219], v[60:63], v[40:43]
	v_mfma_f32_16x16x32_bf16 v[100:103], v[220:223], v[224:227], v[16:19]
	v_mfma_f32_16x16x32_bf16 v[16:19], v[200:203], v[228:231], v[44:47]
	v_mfma_f32_16x16x32_bf16 v[88:91], v[212:215], v[232:235], v[16:19]
	v_mfma_f32_16x16x32_bf16 v[16:19], v[216:219], v[228:231], v[48:51]
	v_mfma_f32_16x16x32_bf16 v[84:87], v[220:223], v[232:235], v[16:19]
	v_mfma_f32_16x16x32_bf16 v[16:19], v[200:203], v[236:239], v[52:55]
	v_mfma_f32_16x16x32_bf16 v[72:75], v[212:215], v[240:243], v[16:19]
	v_mfma_f32_16x16x32_bf16 v[16:19], v[216:219], v[236:239], v[56:59]
	v_mfma_f32_16x16x32_bf16 v[120:123], v[212:215], v[28:31], v[68:71]
	v_mfma_f32_16x16x32_bf16 v[68:71], v[220:223], v[240:243], v[16:19]
	s_barrier
; #define PG8_WAIT_V(n) asm volatile("s_waitcnt vmcnt(" #n ")" ::: "memory")
; #define PG8_WAIT_VP() asm volatile("s_waitcnt vmcnt(%0)" :: "n"(8 + Epi::NST) : "memory")
; template <class Epi, class Sched>
; __device__ __forceinline__ void gemm_phase(PG8_LAS unsigned char* lds, const Sched& S, const Epi& E, int tid_in) {
;     ...
;         { const int t = 0; PG8_KITER(PG8_WAIT_VP()); }
;         for (int t = 2; t < nt; t += 2) PG8_KITER(PG8_WAIT_V(8));
	s_mov_b64 s[70:71], 0x180
	s_add_i32 s63, s63, s30
	s_nop 1
	v_lshl_add_u64 v[16:17], v[248:249], 0, s[70:71]
	s_mov_b32 m0, s63
	s_mov_b64 s[72:73], 0x40180
	s_add_i32 s64, s63, 0x2000
	ds_read_b128 v[36:39], v136 offset:49152
	ds_read_b128 v[40:43], v136 offset:50176
	ds_read_b128 v[224:227], v136 offset:51200
	ds_read_b128 v[228:231], v136 offset:52224
	ds_read_b128 v[232:235], v136 offset:53248
	ds_read_b128 v[236:239], v136 offset:54272
	ds_read_b128 v[240:243], v136 offset:55296
	ds_read_b128 v[244:247], v136 offset:56320
	global_load_lds_dwordx4 v[16:17], off
	v_lshl_add_u64 v[16:17], v[248:249], 0, s[72:73]
	s_mov_b32 m0, s64
	s_add_i32 s65, s65, s30
	global_load_lds_dwordx4 v[16:17], off
	v_lshl_add_u64 v[16:17], v[248:249], 0, s[92:93]
	s_mov_b32 m0, s65
	s_add_i32 s66, s65, 0x2000
	global_load_lds_dwordx4 v[16:17], off
	v_lshl_add_u64 v[16:17], v[248:249], 0, vcc
	s_mov_b32 m0, s66
	s_nop 0
	global_load_lds_dwordx4 v[16:17], off
	v_lshl_add_u64 v[16:17], v[182:183], 0, s[70:71]
	s_mov_b32 m0, s48
	s_nop 0
	global_load_lds_dwordx4 v[16:17], off
	v_lshl_add_u64 v[16:17], v[182:183], 0, s[72:73]
	s_mov_b32 m0, s49
	s_nop 0
	global_load_lds_dwordx4 v[16:17], off
	s_waitcnt vmcnt(8)
	s_waitcnt lgkmcnt(0)
	s_barrier
	s_waitcnt lgkmcnt(0)
	v_mfma_f32_16x16x32_bf16 v[16:19], v[12:15], v[36:39], v[138:141]
	v_mfma_f32_16x16x32_bf16 v[60:63], v[20:23], v[40:43], v[16:19]
	v_mfma_f32_16x16x32_bf16 v[16:19], v[24:27], v[36:39], v[142:145]
	v_mfma_f32_16x16x32_bf16 v[48:51], v[196:199], v[40:43], v[16:19]
	v_mfma_f32_16x16x32_bf16 v[16:19], v[12:15], v[224:227], v[146:149]
	v_mfma_f32_16x16x32_bf16 v[44:47], v[20:23], v[228:231], v[16:19]
	v_mfma_f32_16x16x32_bf16 v[16:19], v[24:27], v[224:227], v[150:153]
	v_mfma_f32_16x16x32_bf16 v[32:35], v[196:199], v[228:231], v[16:19]
	v_mfma_f32_16x16x32_bf16 v[16:19], v[12:15], v[232:235], v[154:157]
	v_mfma_f32_16x16x32_bf16 v[0:3], v[12:15], v[240:243], v[0:3]
	v_mfma_f32_16x16x32_bf16 v[28:31], v[20:23], v[236:239], v[16:19]
	v_mfma_f32_16x16x32_bf16 v[16:19], v[24:27], v[232:235], v[158:161]
	v_mfma_f32_16x16x32_bf16 v[12:15], v[20:23], v[244:247], v[0:3]
	v_mfma_f32_16x16x32_bf16 v[0:3], v[24:27], v[240:243], v[4:7]
	v_mfma_f32_16x16x32_bf16 v[16:19], v[196:199], v[236:239], v[16:19]
	v_mfma_f32_16x16x32_bf16 v[0:3], v[196:199], v[244:247], v[0:3]
	v_mfma_f32_16x16x32_bf16 v[4:7], v[200:203], v[36:39], v[8:11]
	v_mfma_f32_16x16x32_bf16 v[56:59], v[212:215], v[40:43], v[4:7]
	v_mfma_f32_16x16x32_bf16 v[4:7], v[216:219], v[36:39], v[162:165]
	v_mfma_f32_16x16x32_bf16 v[52:55], v[220:223], v[40:43], v[4:7]
	v_mfma_f32_16x16x32_bf16 v[4:7], v[200:203], v[224:227], v[166:169]
	v_mfma_f32_16x16x32_bf16 v[40:43], v[212:215], v[228:231], v[4:7]
	v_mfma_f32_16x16x32_bf16 v[4:7], v[216:219], v[224:227], v[170:173]
	v_mfma_f32_16x16x32_bf16 v[36:39], v[220:223], v[228:231], v[4:7]
	v_mfma_f32_16x16x32_bf16 v[4:7], v[200:203], v[232:235], v[174:177]
	v_mfma_f32_16x16x32_bf16 v[24:27], v[212:215], v[236:239], v[4:7]
	v_mfma_f32_16x16x32_bf16 v[4:7], v[216:219], v[232:235], v[178:181]
	v_mfma_f32_16x16x32_bf16 v[20:23], v[220:223], v[236:239], v[4:7]
	v_mfma_f32_16x16x32_bf16 v[4:7], v[200:203], v[240:243], v[188:191]
	v_mfma_f32_16x16x32_bf16 v[8:11], v[212:215], v[244:247], v[4:7]
	v_mfma_f32_16x16x32_bf16 v[4:7], v[216:219], v[240:243], v[192:195]
	v_mfma_f32_16x16x32_bf16 v[4:7], v[220:223], v[244:247], v[4:7]
	s_barrier
	s_add_u32 s20, s20, 0x80180
	s_addc_u32 s21, s21, 0
	s_add_u32 s67, s22, 0x200
	s_addc_u32 s68, s23, 0
	s_mov_b32 s70, 0
.LBB0_207:
	ds_read_b128 v[138:141], v134
	ds_read_b128 v[142:145], v134 offset:1024
	ds_read_b128 v[146:149], v134 offset:2048
	ds_read_b128 v[150:153], v134 offset:3072
	ds_read_b128 v[154:157], v135
	ds_read_b128 v[158:161], v135 offset:1024
	ds_read_b128 v[162:165], v135 offset:2048
	ds_read_b128 v[166:169], v135 offset:3072
	s_add_u32 s71, s20, 0xfff80080
	s_addc_u32 s72, s21, -1
	s_cmp_eq_u32 s70, 28
	s_cselect_b64 vcc, -1, 0
	s_and_b64 s[22:23], vcc, exec
	v_cndmask_b32_e32 v184, v132, v128, vcc
	s_cselect_b32 s23, s15, s72
	s_cselect_b32 s22, s14, s71
	v_cndmask_b32_e32 v182, v130, v129, vcc
	s_cselect_b32 s73, s17, s68
	s_cselect_b32 s72, s16, s67
	s_mov_b32 m0, s57
	v_lshl_add_u64 v[216:217], s[20:21], 0, v[132:133]
	ds_read_b128 v[170:173], v136
	ds_read_b128 v[174:177], v136 offset:1024
	ds_read_b128 v[178:181], v136 offset:2048
	ds_read_b128 v[188:191], v136 offset:3072
	ds_read_b128 v[192:195], v136 offset:4096
	ds_read_b128 v[196:199], v136 offset:5120
	ds_read_b128 v[200:203], v136 offset:6144
	ds_read_b128 v[212:215], v136 offset:7168
	global_load_lds_dwordx4 v[216:217], off
	v_lshl_add_u64 v[216:217], v[216:217], 0, s[88:89]
	s_mov_b32 m0, s58
	s_nop 0
	global_load_lds_dwordx4 v[216:217], off
	s_waitcnt vmcnt(8)
	s_waitcnt lgkmcnt(0)
	s_barrier
	s_waitcnt lgkmcnt(0)
	v_mfma_f32_16x16x32_bf16 v[124:127], v[138:141], v[170:173], v[124:127]
	v_mfma_f32_16x16x32_bf16 v[112:115], v[146:149], v[170:173], v[112:115]
	v_mfma_f32_16x16x32_bf16 v[108:111], v[138:141], v[178:181], v[108:111]
	v_mfma_f32_16x16x32_bf16 v[96:99], v[146:149], v[178:181], v[96:99]
	v_mfma_f32_16x16x32_bf16 v[92:95], v[138:141], v[192:195], v[92:95]
	v_mfma_f32_16x16x32_bf16 v[80:83], v[146:149], v[192:195], v[80:83]
	v_mfma_f32_16x16x32_bf16 v[76:79], v[138:141], v[200:203], v[76:79]
	v_mfma_f32_16x16x32_bf16 v[64:67], v[146:149], v[200:203], v[64:67]
	v_mfma_f32_16x16x32_bf16 v[124:127], v[142:145], v[174:177], v[124:127]
	v_mfma_f32_16x16x32_bf16 v[112:115], v[150:153], v[174:177], v[112:115]
	v_mfma_f32_16x16x32_bf16 v[108:111], v[142:145], v[188:191], v[108:111]
	v_mfma_f32_16x16x32_bf16 v[96:99], v[150:153], v[188:191], v[96:99]
	v_mfma_f32_16x16x32_bf16 v[92:95], v[142:145], v[196:199], v[92:95]
	v_mfma_f32_16x16x32_bf16 v[80:83], v[150:153], v[196:199], v[80:83]
	v_mfma_f32_16x16x32_bf16 v[76:79], v[142:145], v[212:215], v[76:79]
	v_mfma_f32_16x16x32_bf16 v[64:67], v[150:153], v[212:215], v[64:67]
	v_mfma_f32_16x16x32_bf16 v[120:123], v[154:157], v[170:173], v[120:123]
	v_mfma_f32_16x16x32_bf16 v[116:119], v[162:165], v[170:173], v[116:119]
	v_mfma_f32_16x16x32_bf16 v[104:107], v[154:157], v[178:181], v[104:107]
	v_mfma_f32_16x16x32_bf16 v[100:103], v[162:165], v[178:181], v[100:103]
	v_mfma_f32_16x16x32_bf16 v[88:91], v[154:157], v[192:195], v[88:91]
	v_mfma_f32_16x16x32_bf16 v[84:87], v[162:165], v[192:195], v[84:87]
	v_mfma_f32_16x16x32_bf16 v[72:75], v[154:157], v[200:203], v[72:75]
	v_mfma_f32_16x16x32_bf16 v[68:71], v[162:165], v[200:203], v[68:71]
	v_mfma_f32_16x16x32_bf16 v[120:123], v[158:161], v[174:177], v[120:123]
	v_mfma_f32_16x16x32_bf16 v[116:119], v[166:169], v[174:177], v[116:119]
	v_mfma_f32_16x16x32_bf16 v[104:107], v[158:161], v[188:191], v[104:107]
	v_mfma_f32_16x16x32_bf16 v[100:103], v[166:169], v[188:191], v[100:103]
	v_mfma_f32_16x16x32_bf16 v[88:91], v[158:161], v[196:199], v[88:91]
	v_mfma_f32_16x16x32_bf16 v[84:87], v[166:169], v[196:199], v[84:87]
	v_mfma_f32_16x16x32_bf16 v[72:75], v[158:161], v[212:215], v[72:75]
	v_mfma_f32_16x16x32_bf16 v[68:71], v[166:169], v[212:215], v[68:71]
	s_barrier
	v_mov_b32_e32 v183, v185
	s_mov_b32 m0, s59
	v_lshl_add_u64 v[216:217], s[72:73], 0, v[182:183]
	ds_read_b128 v[170:173], v136 offset:16384
	ds_read_b128 v[174:177], v136 offset:17408
	ds_read_b128 v[178:181], v136 offset:18432
	ds_read_b128 v[188:191], v136 offset:19456
	ds_read_b128 v[192:195], v136 offset:20480
	ds_read_b128 v[196:199], v136 offset:21504
	ds_read_b128 v[200:203], v136 offset:22528
	ds_read_b128 v[212:215], v136 offset:23552
	global_load_lds_dwordx4 v182, s[72:73]
	v_lshl_add_u64 v[182:183], v[216:217], 0, s[88:89]
	s_mov_b32 m0, s60
	s_nop 0
	global_load_lds_dwordx4 v[182:183], off
	v_lshl_add_u64 v[182:183], v[216:217], 0, s[90:91]
	s_mov_b32 m0, s61
	s_nop 0
	global_load_lds_dwordx4 v[182:183], off
	v_lshl_add_u64 v[182:183], v[216:217], 0, s[96:97]
	s_mov_b32 m0, s62
	s_nop 0
	global_load_lds_dwordx4 v[182:183], off
	v_lshl_add_u64 v[182:183], s[22:23], 0, v[184:185]
	s_mov_b32 m0, s7
	v_lshl_add_u64 v[218:219], v[182:183], 0, s[88:89]
	global_load_lds_dwordx4 v[182:183], off
	s_mov_b32 m0, s31
	s_nop 0
	global_load_lds_dwordx4 v[218:219], off
	s_waitcnt vmcnt(8)
	s_waitcnt lgkmcnt(0)
	s_barrier
	s_waitcnt lgkmcnt(0)
	v_mfma_f32_16x16x32_bf16 v[60:63], v[138:141], v[170:173], v[60:63]
	v_mfma_f32_16x16x32_bf16 v[48:51], v[146:149], v[170:173], v[48:51]
	v_mfma_f32_16x16x32_bf16 v[44:47], v[138:141], v[178:181], v[44:47]
	v_mfma_f32_16x16x32_bf16 v[32:35], v[146:149], v[178:181], v[32:35]
	v_mfma_f32_16x16x32_bf16 v[28:31], v[138:141], v[192:195], v[28:31]
	v_mfma_f32_16x16x32_bf16 v[16:19], v[146:149], v[192:195], v[16:19]
	v_mfma_f32_16x16x32_bf16 v[12:15], v[138:141], v[200:203], v[12:15]
	v_mfma_f32_16x16x32_bf16 v[0:3], v[146:149], v[200:203], v[0:3]
	v_mfma_f32_16x16x32_bf16 v[60:63], v[142:145], v[174:177], v[60:63]
	v_mfma_f32_16x16x32_bf16 v[48:51], v[150:153], v[174:177], v[48:51]
	v_mfma_f32_16x16x32_bf16 v[44:47], v[142:145], v[188:191], v[44:47]
	v_mfma_f32_16x16x32_bf16 v[32:35], v[150:153], v[188:191], v[32:35]
	v_mfma_f32_16x16x32_bf16 v[28:31], v[142:145], v[196:199], v[28:31]
	v_mfma_f32_16x16x32_bf16 v[16:19], v[150:153], v[196:199], v[16:19]
	v_mfma_f32_16x16x32_bf16 v[12:15], v[142:145], v[212:215], v[12:15]
	v_mfma_f32_16x16x32_bf16 v[0:3], v[150:153], v[212:215], v[0:3]
	v_mfma_f32_16x16x32_bf16 v[56:59], v[154:157], v[170:173], v[56:59]
	v_mfma_f32_16x16x32_bf16 v[52:55], v[162:165], v[170:173], v[52:55]
	v_mfma_f32_16x16x32_bf16 v[40:43], v[154:157], v[178:181], v[40:43]
	v_mfma_f32_16x16x32_bf16 v[36:39], v[162:165], v[178:181], v[36:39]
	v_mfma_f32_16x16x32_bf16 v[24:27], v[154:157], v[192:195], v[24:27]
	v_mfma_f32_16x16x32_bf16 v[20:23], v[162:165], v[192:195], v[20:23]
	v_mfma_f32_16x16x32_bf16 v[8:11], v[154:157], v[200:203], v[8:11]
	v_mfma_f32_16x16x32_bf16 v[4:7], v[162:165], v[200:203], v[4:7]
	v_mfma_f32_16x16x32_bf16 v[56:59], v[158:161], v[174:177], v[56:59]
	v_mfma_f32_16x16x32_bf16 v[52:55], v[166:169], v[174:177], v[52:55]
	v_mfma_f32_16x16x32_bf16 v[40:43], v[158:161], v[188:191], v[40:43]
	v_mfma_f32_16x16x32_bf16 v[36:39], v[166:169], v[188:191], v[36:39]
	v_mfma_f32_16x16x32_bf16 v[24:27], v[158:161], v[196:199], v[24:27]
	v_mfma_f32_16x16x32_bf16 v[20:23], v[166:169], v[196:199], v[20:23]
	v_mfma_f32_16x16x32_bf16 v[8:11], v[158:161], v[212:215], v[8:11]
	v_mfma_f32_16x16x32_bf16 v[4:7], v[166:169], v[212:215], v[4:7]
	s_barrier
; #define PG8_WAIT_V(n) asm volatile("s_waitcnt vmcnt(" #n ")" ::: "memory")
; #define PG8_WAIT_VP() asm volatile("s_waitcnt vmcnt(%0)" :: "n"(8 + Epi::NST) : "memory")
; #define PG8_BAR __builtin_amdgcn_s_barrier()
; template <class Epi, class Sched>
; __device__ __forceinline__ void gemm_phase(PG8_LAS unsigned char* lds, const Sched& S, const Epi& E, int tid_in) {
;     ...
;         { const int t = 0; PG8_KITER(PG8_WAIT_VP()); }
;         for (int t = 2; t < nt; t += 2) PG8_KITER(PG8_WAIT_V(8));
;     ...
;         if (wr == 0) PG8_BAR;
	ds_read_b128 v[138:141], v131
	ds_read_b128 v[142:145], v131 offset:1024
	ds_read_b128 v[146:149], v131 offset:2048
	ds_read_b128 v[150:153], v131 offset:3072
	ds_read_b128 v[154:157], v137
	ds_read_b128 v[158:161], v137 offset:1024
	ds_read_b128 v[162:165], v137 offset:2048
	ds_read_b128 v[166:169], v137 offset:3072
	s_mov_b32 m0, s34
	v_lshl_add_u64 v[218:219], v[182:183], 0, s[90:91]
	ds_read_b128 v[170:173], v136 offset:32768
	ds_read_b128 v[174:177], v136 offset:33792
	ds_read_b128 v[178:181], v136 offset:34816
	ds_read_b128 v[188:191], v136 offset:35840
	ds_read_b128 v[192:195], v136 offset:36864
	ds_read_b128 v[196:199], v136 offset:37888
	ds_read_b128 v[200:203], v136 offset:38912
	ds_read_b128 v[212:215], v136 offset:39936
	global_load_lds_dwordx4 v[218:219], off
	v_lshl_add_u64 v[218:219], v[182:183], 0, s[96:97]
	s_mov_b32 m0, s35
	s_nop 0
	global_load_lds_dwordx4 v[218:219], off
	s_waitcnt vmcnt(8)
	s_waitcnt lgkmcnt(0)
	s_barrier
	s_waitcnt lgkmcnt(0)
	v_mfma_f32_16x16x32_bf16 v[124:127], v[138:141], v[170:173], v[124:127]
	v_mfma_f32_16x16x32_bf16 v[112:115], v[146:149], v[170:173], v[112:115]
	v_mfma_f32_16x16x32_bf16 v[108:111], v[138:141], v[178:181], v[108:111]
	v_mfma_f32_16x16x32_bf16 v[96:99], v[146:149], v[178:181], v[96:99]
	v_mfma_f32_16x16x32_bf16 v[92:95], v[138:141], v[192:195], v[92:95]
	v_mfma_f32_16x16x32_bf16 v[80:83], v[146:149], v[192:195], v[80:83]
	v_mfma_f32_16x16x32_bf16 v[76:79], v[138:141], v[200:203], v[76:79]
	v_mfma_f32_16x16x32_bf16 v[64:67], v[146:149], v[200:203], v[64:67]
	v_mfma_f32_16x16x32_bf16 v[124:127], v[142:145], v[174:177], v[124:127]
	v_mfma_f32_16x16x32_bf16 v[112:115], v[150:153], v[174:177], v[112:115]
	v_mfma_f32_16x16x32_bf16 v[108:111], v[142:145], v[188:191], v[108:111]
	v_mfma_f32_16x16x32_bf16 v[96:99], v[150:153], v[188:191], v[96:99]
	v_mfma_f32_16x16x32_bf16 v[92:95], v[142:145], v[196:199], v[92:95]
	v_mfma_f32_16x16x32_bf16 v[80:83], v[150:153], v[196:199], v[80:83]
	v_mfma_f32_16x16x32_bf16 v[76:79], v[142:145], v[212:215], v[76:79]
	v_mfma_f32_16x16x32_bf16 v[64:67], v[150:153], v[212:215], v[64:67]
	v_mfma_f32_16x16x32_bf16 v[120:123], v[154:157], v[170:173], v[120:123]
	v_mfma_f32_16x16x32_bf16 v[116:119], v[162:165], v[170:173], v[116:119]
	v_mfma_f32_16x16x32_bf16 v[104:107], v[154:157], v[178:181], v[104:107]
	v_mfma_f32_16x16x32_bf16 v[100:103], v[162:165], v[178:181], v[100:103]
	v_mfma_f32_16x16x32_bf16 v[88:91], v[154:157], v[192:195], v[88:91]
	v_mfma_f32_16x16x32_bf16 v[84:87], v[162:165], v[192:195], v[84:87]
	v_mfma_f32_16x16x32_bf16 v[72:75], v[154:157], v[200:203], v[72:75]
	v_mfma_f32_16x16x32_bf16 v[68:71], v[162:165], v[200:203], v[68:71]
	v_mfma_f32_16x16x32_bf16 v[120:123], v[158:161], v[174:177], v[120:123]
	v_mfma_f32_16x16x32_bf16 v[116:119], v[166:169], v[174:177], v[116:119]
	v_mfma_f32_16x16x32_bf16 v[104:107], v[158:161], v[188:191], v[104:107]
	v_mfma_f32_16x16x32_bf16 v[100:103], v[166:169], v[188:191], v[100:103]
	v_mfma_f32_16x16x32_bf16 v[88:91], v[158:161], v[196:199], v[88:91]
	v_mfma_f32_16x16x32_bf16 v[84:87], v[166:169], v[196:199], v[84:87]
	v_mfma_f32_16x16x32_bf16 v[72:75], v[158:161], v[212:215], v[72:75]
	v_mfma_f32_16x16x32_bf16 v[68:71], v[166:169], v[212:215], v[68:71]
	s_barrier
	s_mov_b32 m0, s63
	v_lshl_add_u64 v[218:219], v[216:217], 0, s[84:85]
	ds_read_b128 v[170:173], v136 offset:49152
	ds_read_b128 v[174:177], v136 offset:50176
	ds_read_b128 v[178:181], v136 offset:51200
	ds_read_b128 v[188:191], v136 offset:52224
	ds_read_b128 v[192:195], v136 offset:53248
	ds_read_b128 v[196:199], v136 offset:54272
	ds_read_b128 v[200:203], v136 offset:55296
	ds_read_b128 v[212:215], v136 offset:56320
	global_load_lds_dwordx4 v[218:219], off
	v_lshl_add_u64 v[218:219], v[216:217], 0, s[94:95]
	s_mov_b32 m0, s64
	s_nop 0
	global_load_lds_dwordx4 v[218:219], off
	v_lshl_add_u64 v[218:219], v[216:217], 0, s[80:81]
	s_mov_b32 m0, s65
	v_lshl_add_u64 v[216:217], v[216:217], 0, s[78:79]
	global_load_lds_dwordx4 v[218:219], off
	s_mov_b32 m0, s66
	s_nop 0
	global_load_lds_dwordx4 v[216:217], off
	v_lshl_add_u64 v[216:217], v[182:183], 0, s[84:85]
	s_mov_b32 m0, s48
	v_lshl_add_u64 v[182:183], v[182:183], 0, s[94:95]
	global_load_lds_dwordx4 v[216:217], off
	s_mov_b32 m0, s49
	s_nop 0
	global_load_lds_dwordx4 v[182:183], off
	s_waitcnt vmcnt(8)
	s_waitcnt lgkmcnt(0)
	s_barrier
	s_waitcnt lgkmcnt(0)
	v_mfma_f32_16x16x32_bf16 v[60:63], v[138:141], v[170:173], v[60:63]
	v_mfma_f32_16x16x32_bf16 v[48:51], v[146:149], v[170:173], v[48:51]
	v_mfma_f32_16x16x32_bf16 v[44:47], v[138:141], v[178:181], v[44:47]
	v_mfma_f32_16x16x32_bf16 v[32:35], v[146:149], v[178:181], v[32:35]
	v_mfma_f32_16x16x32_bf16 v[28:31], v[138:141], v[192:195], v[28:31]
	v_mfma_f32_16x16x32_bf16 v[16:19], v[146:149], v[192:195], v[16:19]
	v_mfma_f32_16x16x32_bf16 v[12:15], v[138:141], v[200:203], v[12:15]
	v_mfma_f32_16x16x32_bf16 v[0:3], v[146:149], v[200:203], v[0:3]
	v_mfma_f32_16x16x32_bf16 v[60:63], v[142:145], v[174:177], v[60:63]
	v_mfma_f32_16x16x32_bf16 v[48:51], v[150:153], v[174:177], v[48:51]
	v_mfma_f32_16x16x32_bf16 v[44:47], v[142:145], v[188:191], v[44:47]
	v_mfma_f32_16x16x32_bf16 v[32:35], v[150:153], v[188:191], v[32:35]
	v_mfma_f32_16x16x32_bf16 v[28:31], v[142:145], v[196:199], v[28:31]
	v_mfma_f32_16x16x32_bf16 v[16:19], v[150:153], v[196:199], v[16:19]
	v_mfma_f32_16x16x32_bf16 v[12:15], v[142:145], v[212:215], v[12:15]
	v_mfma_f32_16x16x32_bf16 v[0:3], v[150:153], v[212:215], v[0:3]
	v_mfma_f32_16x16x32_bf16 v[56:59], v[154:157], v[170:173], v[56:59]
	v_mfma_f32_16x16x32_bf16 v[52:55], v[162:165], v[170:173], v[52:55]
	v_mfma_f32_16x16x32_bf16 v[40:43], v[154:157], v[178:181], v[40:43]
	v_mfma_f32_16x16x32_bf16 v[36:39], v[162:165], v[178:181], v[36:39]
	v_mfma_f32_16x16x32_bf16 v[24:27], v[154:157], v[192:195], v[24:27]
	v_mfma_f32_16x16x32_bf16 v[20:23], v[162:165], v[192:195], v[20:23]
	v_mfma_f32_16x16x32_bf16 v[8:11], v[154:157], v[200:203], v[8:11]
	v_mfma_f32_16x16x32_bf16 v[4:7], v[162:165], v[200:203], v[4:7]
	v_mfma_f32_16x16x32_bf16 v[56:59], v[158:161], v[174:177], v[56:59]
	v_mfma_f32_16x16x32_bf16 v[52:55], v[166:169], v[174:177], v[52:55]
	v_mfma_f32_16x16x32_bf16 v[40:43], v[158:161], v[188:191], v[40:43]
	v_mfma_f32_16x16x32_bf16 v[36:39], v[166:169], v[188:191], v[36:39]
	v_mfma_f32_16x16x32_bf16 v[24:27], v[158:161], v[196:199], v[24:27]
	v_mfma_f32_16x16x32_bf16 v[20:23], v[166:169], v[196:199], v[20:23]
	v_mfma_f32_16x16x32_bf16 v[8:11], v[158:161], v[212:215], v[8:11]
	v_mfma_f32_16x16x32_bf16 v[4:7], v[166:169], v[212:215], v[4:7]
	s_barrier
	s_add_i32 s70, s70, 2
	s_add_u32 s20, s20, 0x100
	s_addc_u32 s21, s21, 0
	s_add_u32 s67, s67, 0x100
	s_addc_u32 s68, s68, 0
	s_cmp_gt_u32 s70, 29
	s_cbranch_scc0 .LBB0_207
	s_and_b64 vcc, exec, s[12:13]
	s_cbranch_vccz .LBB0_210
	s_barrier

; __device__ __forceinline__ int lane_id() { int l; asm volatile("v_mbcnt_lo_u32_b32 %0, -1, 0\n\tv_mbcnt_hi_u32_b32 %0, -1, %0" : "=v"(l)); return l; }
;     __device__ __forceinline__ bool next(int i, UnitG& u) const { if (!P.next(i, u)) return false; u.O = O + ((size_t)u.x0 * 256 * 2048 + (size_t)u.x1 * 256) * 2; u.ldo = 2048; u.kind = 0; return true; }
; template <class Epi, class Sched>
; __device__ __forceinline__ void gemm_phase(PG8_LAS unsigned char* lds, const Sched& S, const Epi& E, int tid_in) {
;     ...
;     for (;;) {
;         int aoff, boff; { const int l3 = lane_id(), fr3 = l3 & 15, fq3 = l3 >> 4; aoff = lds_byte(wr * 64 + fr3, fq3 * 8); boff = lds_byte(wc * 32 + fr3, fq3 * 8); }
;         const bool has_next = S.next(ui + 1, nxt);
;         const char* nA = has_next ? nxt.A : cA; const char* nB = has_next ? nxt.B : cB;
;         const int nlda = has_next ? nxt.lda : cur.lda, nldb = has_next ? nxt.ldb : cur.ldb;
;         unsigned nvA, nvB; { int r2, c2; stage_rc((wid * 64 + lane_id()) * 16, r2, c2); const int rb2 = Epi::PERM ? ((r2 & ~31) + perm32(r2 & 31)) : r2;
;             nvA = (unsigned)(r2 * nlda + c2) * 2u; nvB = (unsigned)(rb2 * nldb + c2) * 2u; }
;         const unsigned nqA = (unsigned)nlda * 128u, nqB = (unsigned)nldb * 128u;
;         const int nt = cur.K / BK;
.LBB0_273:
	v_and_b32_e32 v1, 15, v0
	v_or_b32_e32 v2, s50, v1
	v_ashrrev_i32_e32 v3, 6, v0
	v_lshlrev_b32_e32 v4, 6, v2
	v_and_b32_e32 v5, 48, v0
	s_movk_i32 s57, 0x3c0
	v_lshlrev_b32_e32 v2, 2, v2
	v_and_or_b32 v4, v4, s57, v5
	v_lshl_add_u32 v6, v3, 10, s51
	v_and_b32_e32 v2, 32, v2
	v_lshlrev_b32_e32 v0, 2, v0
	s_waitcnt vmcnt(0)
	v_bitop3_b32 v32, v4, v6, v2 bitop3:0xde
	v_lshl_or_b32 v1, v1, 6, v5
	v_add_lshl_u32 v2, v3, s53, 10
	v_and_b32_e32 v0, 32, v0
	v_bitop3_b32 v119, v1, v2, v0 bitop3:0xde
	v_mbcnt_lo_u32_b32 v0, -1, 0
	v_mbcnt_hi_u32_b32 v0, -1, v0
	s_mov_b32 s57, 0x7fffe0
	v_add_u32_e32 v0, s54, v0
	v_ashrrev_i32_e32 v2, 31, v0
	v_lshrrev_b32_e32 v2, 26, v2
	v_lshlrev_b32_e32 v1, 4, v0
	v_add_u32_e32 v2, v0, v2
	v_bfe_i32 v0, v0, 27, 1
	v_lshrrev_b32_e32 v0, 22, v0
	v_add_u32_e32 v0, v1, v0
	v_and_b32_e32 v0, 0xfffffc00, v0
	v_sub_u32_e32 v0, v1, v0
	v_lshrrev_b32_e32 v1, 4, v0
	v_bitop3_b32 v0, v1, v0, 32 bitop3:0x6c
	v_ashrrev_i32_e32 v3, 31, v0
	v_ashrrev_i32_e32 v2, 6, v2
	v_lshrrev_b32_e32 v3, 26, v3
	v_lshlrev_b32_e32 v1, 3, v2
	v_add_u32_e32 v3, v0, v3
	v_and_b32_e32 v1, -16, v1
	v_ashrrev_i32_e32 v4, 6, v3
	v_add_u32_e32 v33, v4, v1
	v_lshlrev_b32_e32 v1, 5, v2
	v_and_b32_e32 v2, 0xc0, v3
	v_sub_u32_e32 v0, v0, v2
	v_and_b32_e32 v1, 32, v1
	v_ashrrev_i16_sdwa v0, v205, sext(v0) dst_sel:DWORD dst_unused:UNUSED_PAD src0_sel:DWORD src1_sel:BYTE_0
	v_add_u32_sdwa v34, v1, sext(v0) dst_sel:DWORD dst_unused:UNUSED_PAD src0_sel:DWORD src1_sel:WORD_0
	v_lshlrev_b32_e32 v0, 1, v33
	v_lshrrev_b32_e32 v1, 2, v33
	v_and_b32_e32 v2, 3, v4
	s_add_i32 s59, 0, 0x10000
	s_add_i32 s61, 0, 0x14000
	v_and_b32_e32 v0, 24, v0
	v_and_b32_e32 v1, 4, v1
	v_and_or_b32 v2, v33, s57, v2
	v_add_u32_e32 v116, s59, v119
	v_add_u32_e32 v117, s61, v119
	v_or3_b32 v35, v2, v1, v0
	ds_read_b128 v[0:3], v116
	ds_read_b128 v[4:7], v116 offset:1024
	ds_read_b128 v[8:11], v116 offset:2048
	ds_read_b128 v[12:15], v116 offset:3072
	ds_read_b128 v[16:19], v117
	ds_read_b128 v[20:23], v117 offset:1024
	ds_read_b128 v[24:27], v117 offset:2048
	ds_read_b128 v[28:31], v117 offset:3072
	s_movk_i32 s57, 0x1600
	v_mul_lo_u32 v33, v33, s57
	v_add_lshl_u32 v186, v34, v33, 1
	v_mul_u32_u24_e32 v33, 0x1600, v35
	v_add_lshl_u32 v211, v33, v34, 1
	v_mov_b32_e32 v115, v185
	v_lshl_add_u64 v[244:245], s[20:21], 0, v[114:115]
	s_add_i32 s57, s31, 0xc000
	v_add_u32_e32 v118, 0, v32
	v_lshl_add_u64 v[64:65], v[244:245], 0, s[40:41]
	s_mov_b32 m0, s57
	s_add_i32 s58, s31, 0xe000
	ds_read_b128 v[32:35], v118
	ds_read_b128 v[36:39], v118 offset:1024
	ds_read_b128 v[40:43], v118 offset:2048
	ds_read_b128 v[44:47], v118 offset:3072
	ds_read_b128 v[48:51], v118 offset:4096
	ds_read_b128 v[52:55], v118 offset:5120
	ds_read_b128 v[56:59], v118 offset:6144
	ds_read_b128 v[60:63], v118 offset:7168
	global_load_lds_dwordx4 v[64:65], off
	v_lshl_add_u64 v[64:65], v[244:245], 0, s[42:43]
	s_mov_b32 m0, s58
	s_nop 0
	global_load_lds_dwordx4 v[64:65], off
	s_waitcnt vmcnt(24)
	s_waitcnt lgkmcnt(0)
	s_barrier
	s_waitcnt lgkmcnt(0)
	v_mfma_f32_16x16x32_bf16 v[88:91], v[0:3], v[56:59], 0
	v_mfma_f32_16x16x32_bf16 v[64:67], v[0:3], v[32:35], 0
	v_mfma_f32_16x16x32_bf16 v[68:71], v[8:11], v[32:35], 0
	v_mfma_f32_16x16x32_bf16 v[72:75], v[0:3], v[40:43], 0
	v_mfma_f32_16x16x32_bf16 v[76:79], v[8:11], v[40:43], 0
	v_mfma_f32_16x16x32_bf16 v[80:83], v[0:3], v[48:51], 0
	v_mfma_f32_16x16x32_bf16 v[84:87], v[8:11], v[48:51], 0
	v_mfma_f32_16x16x32_bf16 v[96:99], v[4:7], v[60:63], v[88:91]
	v_mfma_f32_16x16x32_bf16 v[88:91], v[8:11], v[56:59], 0
	v_mfma_f32_16x16x32_bf16 v[64:67], v[4:7], v[36:39], v[64:67]
	v_mfma_f32_16x16x32_bf16 v[68:71], v[12:15], v[36:39], v[68:71]
	v_mfma_f32_16x16x32_bf16 v[72:75], v[4:7], v[44:47], v[72:75]
	v_mfma_f32_16x16x32_bf16 v[76:79], v[12:15], v[44:47], v[76:79]
	v_mfma_f32_16x16x32_bf16 v[80:83], v[4:7], v[52:55], v[80:83]
	v_mfma_f32_16x16x32_bf16 v[84:87], v[12:15], v[52:55], v[84:87]
	v_mfma_f32_16x16x32_bf16 v[100:103], v[12:15], v[60:63], v[88:91]
	v_mfma_f32_16x16x32_bf16 v[88:91], v[16:19], v[32:35], 0
	v_mfma_f32_16x16x32_bf16 v[32:35], v[24:27], v[32:35], 0
	v_mfma_f32_16x16x32_bf16 v[120:123], v[20:23], v[36:39], v[88:91]
	v_mfma_f32_16x16x32_bf16 v[32:35], v[28:31], v[36:39], v[32:35]
	v_mfma_f32_16x16x32_bf16 v[36:39], v[16:19], v[40:43], 0
	v_mfma_f32_16x16x32_bf16 v[40:43], v[24:27], v[40:43], 0
	v_mfma_f32_16x16x32_bf16 v[36:39], v[20:23], v[44:47], v[36:39]
	v_mfma_f32_16x16x32_bf16 v[40:43], v[28:31], v[44:47], v[40:43]
	v_mfma_f32_16x16x32_bf16 v[44:47], v[16:19], v[48:51], 0
	v_mfma_f32_16x16x32_bf16 v[48:51], v[24:27], v[48:51], 0
	v_mfma_f32_16x16x32_bf16 v[44:47], v[20:23], v[52:55], v[44:47]
	v_mfma_f32_16x16x32_bf16 v[48:51], v[28:31], v[52:55], v[48:51]
	v_mfma_f32_16x16x32_bf16 v[52:55], v[16:19], v[56:59], 0
	v_mfma_f32_16x16x32_bf16 v[56:59], v[24:27], v[56:59], 0
	v_mfma_f32_16x16x32_bf16 v[52:55], v[20:23], v[60:63], v[52:55]
	v_mfma_f32_16x16x32_bf16 v[56:59], v[28:31], v[60:63], v[56:59]
	s_barrier
	v_mov_b32_e32 v113, v185
	v_lshl_add_u64 v[246:247], s[22:23], 0, v[112:113]
	s_mov_b64 s[64:65], 0x100
	s_add_i32 s59, s59, s30
	v_lshl_add_u64 v[136:137], v[246:247], 0, s[64:65]
	s_mov_b32 m0, s59
	s_mov_b64 s[66:67], 0xb0100
	s_add_i32 s60, s59, 0x2000
	ds_read_b128 v[60:63], v118 offset:16384
	ds_read_b128 v[88:91], v118 offset:17408
	ds_read_b128 v[92:95], v118 offset:18432
	ds_read_b128 v[104:107], v118 offset:19456
	ds_read_b128 v[108:111], v118 offset:20480
	ds_read_b128 v[124:127], v118 offset:21504
	ds_read_b128 v[128:131], v118 offset:22528
	ds_read_b128 v[132:135], v118 offset:23552
	global_load_lds_dwordx4 v[136:137], off
	v_lshl_add_u64 v[136:137], v[246:247], 0, s[66:67]
	s_mov_b32 m0, s60
	s_mov_b64 s[70:71], 0x160100
	s_add_i32 s61, s61, s30
	global_load_lds_dwordx4 v[136:137], off
	v_lshl_add_u64 v[136:137], v[246:247], 0, s[70:71]
	s_mov_b32 m0, s61
	s_mov_b64 s[72:73], 0x210100
	s_add_i32 s62, s61, 0x2000
	global_load_lds_dwordx4 v[136:137], off
	v_lshl_add_u64 v[136:137], v[246:247], 0, s[72:73]
	s_mov_b32 m0, s62
	s_nop 0
	global_load_lds_dwordx4 v[136:137], off
	v_lshl_add_u64 v[136:137], v[244:245], 0, s[64:65]
	s_mov_b32 m0, s31
	s_nop 0
	global_load_lds_dwordx4 v[136:137], off
	v_lshl_add_u64 v[136:137], v[244:245], 0, s[66:67]
	s_mov_b32 m0, s35
	s_nop 0
	global_load_lds_dwordx4 v[136:137], off
	s_waitcnt vmcnt(24)
	s_waitcnt lgkmcnt(0)
	s_barrier
	s_waitcnt lgkmcnt(0)
	v_mfma_f32_16x16x32_bf16 v[136:139], v[0:3], v[60:63], 0
	v_mfma_f32_16x16x32_bf16 v[144:147], v[0:3], v[92:95], 0
	v_mfma_f32_16x16x32_bf16 v[152:155], v[0:3], v[108:111], 0
	v_mfma_f32_16x16x32_bf16 v[0:3], v[0:3], v[128:131], 0
	v_mfma_f32_16x16x32_bf16 v[136:139], v[4:7], v[88:91], v[136:139]
	v_mfma_f32_16x16x32_bf16 v[144:147], v[4:7], v[104:107], v[144:147]
	v_mfma_f32_16x16x32_bf16 v[152:155], v[4:7], v[124:127], v[152:155]
	v_mfma_f32_16x16x32_bf16 v[0:3], v[4:7], v[132:135], v[0:3]
	v_mfma_f32_16x16x32_bf16 v[4:7], v[8:11], v[128:131], 0
	v_mfma_f32_16x16x32_bf16 v[140:143], v[8:11], v[60:63], 0
	v_mfma_f32_16x16x32_bf16 v[148:151], v[8:11], v[92:95], 0
	v_mfma_f32_16x16x32_bf16 v[156:159], v[8:11], v[108:111], 0
	v_mfma_f32_16x16x32_bf16 v[4:7], v[12:15], v[132:135], v[4:7]
	v_mfma_f32_16x16x32_bf16 v[140:143], v[12:15], v[88:91], v[140:143]
	v_mfma_f32_16x16x32_bf16 v[148:151], v[12:15], v[104:107], v[148:151]
	v_mfma_f32_16x16x32_bf16 v[156:159], v[12:15], v[124:127], v[156:159]
	v_mfma_f32_16x16x32_bf16 v[8:11], v[16:19], v[60:63], 0
	v_mfma_f32_16x16x32_bf16 v[160:163], v[20:23], v[88:91], v[8:11]
	v_mfma_f32_16x16x32_bf16 v[8:11], v[24:27], v[60:63], 0
	v_mfma_f32_16x16x32_bf16 v[180:183], v[28:31], v[88:91], v[8:11]
	v_mfma_f32_16x16x32_bf16 v[8:11], v[16:19], v[92:95], 0
	v_mfma_f32_16x16x32_bf16 v[188:191], v[20:23], v[104:107], v[8:11]
	v_mfma_f32_16x16x32_bf16 v[8:11], v[24:27], v[92:95], 0
	v_mfma_f32_16x16x32_bf16 v[192:195], v[28:31], v[104:107], v[8:11]
	v_mfma_f32_16x16x32_bf16 v[8:11], v[16:19], v[108:111], 0
	v_mfma_f32_16x16x32_bf16 v[196:199], v[20:23], v[124:127], v[8:11]
	v_mfma_f32_16x16x32_bf16 v[8:11], v[24:27], v[108:111], 0
	v_mfma_f32_16x16x32_bf16 v[124:127], v[28:31], v[124:127], v[8:11]
	v_mfma_f32_16x16x32_bf16 v[8:11], v[16:19], v[128:131], 0
	v_mfma_f32_16x16x32_bf16 v[200:203], v[20:23], v[132:135], v[8:11]
	v_mfma_f32_16x16x32_bf16 v[8:11], v[24:27], v[128:131], 0
	v_mfma_f32_16x16x32_bf16 v[128:131], v[28:31], v[132:135], v[8:11]
	s_barrier
	s_add_i32 s63, 0, 0x18000
	s_add_i32 s65, 0, 0x1c000
	v_add_u32_e32 v113, s63, v119
	v_add_u32_e32 v119, s65, v119
	s_nop 0
	ds_read_b128 v[8:11], v113
	ds_read_b128 v[12:15], v113 offset:1024
	ds_read_b128 v[16:19], v113 offset:2048
	ds_read_b128 v[20:23], v113 offset:3072
	ds_read_b128 v[132:135], v119
	ds_read_b128 v[212:215], v119 offset:1024
	ds_read_b128 v[216:219], v119 offset:2048
	ds_read_b128 v[220:223], v119 offset:3072
	s_mov_b32 m0, s48
	v_lshl_add_u64 v[88:89], v[244:245], 0, s[70:71]
	ds_read_b128 v[24:27], v118 offset:32768
	ds_read_b128 v[28:31], v118 offset:33792
	ds_read_b128 v[60:63], v118 offset:34816
	ds_read_b128 v[224:227], v118 offset:35840
	ds_read_b128 v[228:231], v118 offset:36864
	ds_read_b128 v[232:235], v118 offset:37888
	ds_read_b128 v[236:239], v118 offset:38912
	ds_read_b128 v[240:243], v118 offset:39936
	global_load_lds_dwordx4 v[88:89], off
	v_lshl_add_u64 v[88:89], v[244:245], 0, s[72:73]
	s_mov_b32 m0, s49
	s_nop 0
	global_load_lds_dwordx4 v[88:89], off
	s_waitcnt vmcnt(8)
	s_waitcnt lgkmcnt(0)
	s_barrier
	s_waitcnt lgkmcnt(0)
	v_mfma_f32_16x16x32_bf16 v[64:67], v[8:11], v[24:27], v[64:67]
	v_mfma_f32_16x16x32_bf16 v[172:175], v[12:15], v[28:31], v[64:67]
	v_mfma_f32_16x16x32_bf16 v[64:67], v[16:19], v[24:27], v[68:71]
	v_mfma_f32_16x16x32_bf16 v[164:167], v[20:23], v[28:31], v[64:67]
	v_mfma_f32_16x16x32_bf16 v[64:67], v[8:11], v[60:63], v[72:75]
	v_mfma_f32_16x16x32_bf16 v[108:111], v[12:15], v[224:227], v[64:67]
	v_mfma_f32_16x16x32_bf16 v[64:67], v[16:19], v[60:63], v[76:79]
	v_mfma_f32_16x16x32_bf16 v[104:107], v[20:23], v[224:227], v[64:67]
	v_mfma_f32_16x16x32_bf16 v[64:67], v[8:11], v[228:231], v[80:83]
	v_mfma_f32_16x16x32_bf16 v[92:95], v[12:15], v[232:235], v[64:67]
	v_mfma_f32_16x16x32_bf16 v[64:67], v[16:19], v[228:231], v[84:87]
	v_mfma_f32_16x16x32_bf16 v[88:91], v[20:23], v[232:235], v[64:67]
	v_mfma_f32_16x16x32_bf16 v[64:67], v[8:11], v[236:239], v[96:99]
	v_mfma_f32_16x16x32_bf16 v[76:79], v[12:15], v[240:243], v[64:67]
	v_mfma_f32_16x16x32_bf16 v[64:67], v[16:19], v[236:239], v[100:103]
	v_mfma_f32_16x16x32_bf16 v[68:71], v[20:23], v[240:243], v[64:67]
	v_mfma_f32_16x16x32_bf16 v[64:67], v[132:135], v[24:27], v[120:123]
	v_mfma_f32_16x16x32_bf16 v[24:27], v[216:219], v[24:27], v[32:35]
	v_mfma_f32_16x16x32_bf16 v[168:171], v[220:223], v[28:31], v[24:27]
	v_mfma_f32_16x16x32_bf16 v[24:27], v[132:135], v[60:63], v[36:39]
	v_mfma_f32_16x16x32_bf16 v[100:103], v[212:215], v[224:227], v[24:27]
	v_mfma_f32_16x16x32_bf16 v[24:27], v[216:219], v[60:63], v[40:43]
	v_mfma_f32_16x16x32_bf16 v[96:99], v[220:223], v[224:227], v[24:27]
	v_mfma_f32_16x16x32_bf16 v[24:27], v[132:135], v[228:231], v[44:47]
	v_mfma_f32_16x16x32_bf16 v[84:87], v[212:215], v[232:235], v[24:27]
	v_mfma_f32_16x16x32_bf16 v[24:27], v[216:219], v[228:231], v[48:51]
	v_mfma_f32_16x16x32_bf16 v[80:83], v[220:223], v[232:235], v[24:27]
	v_mfma_f32_16x16x32_bf16 v[24:27], v[132:135], v[236:239], v[52:55]
	v_mfma_f32_16x16x32_bf16 v[176:179], v[212:215], v[28:31], v[64:67]
	v_mfma_f32_16x16x32_bf16 v[64:67], v[212:215], v[240:243], v[24:27]
	v_mfma_f32_16x16x32_bf16 v[24:27], v[216:219], v[236:239], v[56:59]
	v_mfma_f32_16x16x32_bf16 v[52:55], v[220:223], v[240:243], v[24:27]
	s_barrier
; #define PG8_WAIT_V(n) asm volatile("s_waitcnt vmcnt(" #n ")" ::: "memory")
; #define PG8_WAIT_VP() asm volatile("s_waitcnt vmcnt(%0)" :: "n"(8 + Epi::NST) : "memory")
; template <class Epi, class Sched>
; __device__ __forceinline__ void gemm_phase(PG8_LAS unsigned char* lds, const Sched& S, const Epi& E, int tid_in) {
;     ...
;         { const int t = 0; PG8_KITER(PG8_WAIT_VP()); }
;         for (int t = 2; t < nt; t += 2) PG8_KITER(PG8_WAIT_V(8));
	s_mov_b64 s[70:71], 0x180
	s_add_i32 s63, s63, s30
	s_nop 2
	v_lshl_add_u64 v[24:25], v[246:247], 0, s[70:71]
	s_mov_b32 m0, s63
	s_mov_b64 s[72:73], 0xb0180
	s_add_i32 s64, s63, 0x2000
	ds_read_b128 v[32:35], v118 offset:49152
	ds_read_b128 v[36:39], v118 offset:50176
	ds_read_b128 v[120:123], v118 offset:51200
	ds_read_b128 v[224:227], v118 offset:52224
	ds_read_b128 v[228:231], v118 offset:53248
	ds_read_b128 v[232:235], v118 offset:54272
	ds_read_b128 v[236:239], v118 offset:55296
	ds_read_b128 v[240:243], v118 offset:56320
	global_load_lds_dwordx4 v[24:25], off
	v_lshl_add_u64 v[24:25], v[246:247], 0, s[72:73]
	s_mov_b32 m0, s64
	s_mov_b64 s[66:67], 0x160180
	s_add_i32 s65, s65, s30
	global_load_lds_dwordx4 v[24:25], off
	v_lshl_add_u64 v[24:25], v[246:247], 0, s[66:67]
	s_mov_b32 m0, s65
	s_mov_b64 s[66:67], 0x210180
	global_load_lds_dwordx4 v[24:25], off
	v_lshl_add_u64 v[24:25], v[246:247], 0, s[66:67]
	s_add_i32 s66, s65, 0x2000
	s_mov_b32 m0, s66
	s_nop 0
	global_load_lds_dwordx4 v[24:25], off
	v_lshl_add_u64 v[24:25], v[244:245], 0, s[70:71]
	s_mov_b32 m0, s46
	s_nop 0
	global_load_lds_dwordx4 v[24:25], off
	v_lshl_add_u64 v[24:25], v[244:245], 0, s[72:73]
	s_mov_b32 m0, s47
	s_nop 0
	global_load_lds_dwordx4 v[24:25], off
	s_waitcnt vmcnt(8)
	s_waitcnt lgkmcnt(0)
	s_barrier
	s_waitcnt lgkmcnt(0)
	v_mfma_f32_16x16x32_bf16 v[24:27], v[8:11], v[32:35], v[136:139]
	v_mfma_f32_16x16x32_bf16 v[72:75], v[12:15], v[36:39], v[24:27]
	v_mfma_f32_16x16x32_bf16 v[24:27], v[16:19], v[32:35], v[140:143]
	v_mfma_f32_16x16x32_bf16 v[60:63], v[20:23], v[36:39], v[24:27]
	v_mfma_f32_16x16x32_bf16 v[24:27], v[8:11], v[120:123], v[144:147]
	v_mfma_f32_16x16x32_bf16 v[44:47], v[12:15], v[224:227], v[24:27]
	v_mfma_f32_16x16x32_bf16 v[24:27], v[16:19], v[120:123], v[148:151]
	v_mfma_f32_16x16x32_bf16 v[40:43], v[20:23], v[224:227], v[24:27]
	v_mfma_f32_16x16x32_bf16 v[24:27], v[8:11], v[228:231], v[152:155]
	v_mfma_f32_16x16x32_bf16 v[0:3], v[8:11], v[236:239], v[0:3]
	v_mfma_f32_16x16x32_bf16 v[28:31], v[12:15], v[232:235], v[24:27]
	v_mfma_f32_16x16x32_bf16 v[24:27], v[16:19], v[228:231], v[156:159]
	v_mfma_f32_16x16x32_bf16 v[12:15], v[12:15], v[240:243], v[0:3]
	v_mfma_f32_16x16x32_bf16 v[0:3], v[16:19], v[236:239], v[4:7]
	v_mfma_f32_16x16x32_bf16 v[24:27], v[20:23], v[232:235], v[24:27]
	v_mfma_f32_16x16x32_bf16 v[8:11], v[20:23], v[240:243], v[0:3]
	v_mfma_f32_16x16x32_bf16 v[0:3], v[132:135], v[32:35], v[160:163]
	v_mfma_f32_16x16x32_bf16 v[56:59], v[212:215], v[36:39], v[0:3]
	v_mfma_f32_16x16x32_bf16 v[0:3], v[216:219], v[32:35], v[180:183]
	v_mfma_f32_16x16x32_bf16 v[48:51], v[220:223], v[36:39], v[0:3]
	v_mfma_f32_16x16x32_bf16 v[0:3], v[132:135], v[120:123], v[188:191]
	v_mfma_f32_16x16x32_bf16 v[36:39], v[212:215], v[224:227], v[0:3]
	v_mfma_f32_16x16x32_bf16 v[0:3], v[216:219], v[120:123], v[192:195]
	v_mfma_f32_16x16x32_bf16 v[32:35], v[220:223], v[224:227], v[0:3]
	v_mfma_f32_16x16x32_bf16 v[0:3], v[132:135], v[228:231], v[196:199]
	v_mfma_f32_16x16x32_bf16 v[20:23], v[212:215], v[232:235], v[0:3]
	v_mfma_f32_16x16x32_bf16 v[0:3], v[216:219], v[228:231], v[124:127]
	v_mfma_f32_16x16x32_bf16 v[16:19], v[220:223], v[232:235], v[0:3]
	v_mfma_f32_16x16x32_bf16 v[0:3], v[132:135], v[236:239], v[200:203]
	v_mfma_f32_16x16x32_bf16 v[4:7], v[212:215], v[240:243], v[0:3]
	v_mfma_f32_16x16x32_bf16 v[0:3], v[216:219], v[236:239], v[128:131]
	v_mfma_f32_16x16x32_bf16 v[0:3], v[220:223], v[240:243], v[0:3]
	s_barrier
	s_add_u32 s20, s20, 0x160180
	s_addc_u32 s21, s21, 0
	s_add_u32 s67, s22, 0x200
	s_addc_u32 s68, s23, 0
	s_mov_b32 s70, 0
.LBB0_274:
	ds_read_b128 v[120:123], v116
	ds_read_b128 v[124:127], v116 offset:1024
	ds_read_b128 v[128:131], v116 offset:2048
	ds_read_b128 v[132:135], v116 offset:3072
	ds_read_b128 v[136:139], v117
	ds_read_b128 v[140:143], v117 offset:1024
	ds_read_b128 v[144:147], v117 offset:2048
	ds_read_b128 v[148:151], v117 offset:3072
	s_add_u32 s71, s20, 0xffea0080
	s_addc_u32 s72, s21, -1
	s_cmpk_eq_i32 s70, 0x54
	s_cselect_b64 vcc, -1, 0
	s_and_b64 s[22:23], vcc, exec
	v_cndmask_b32_e32 v184, v114, v186, vcc
	s_cselect_b32 s23, s15, s72
	s_cselect_b32 s22, s14, s71
	v_cndmask_b32_e32 v212, v112, v211, vcc
	s_cselect_b32 s73, s17, s68
	s_cselect_b32 s72, s16, s67
	s_mov_b32 m0, s57
	v_lshl_add_u64 v[214:215], s[20:21], 0, v[114:115]
	ds_read_b128 v[152:155], v118
	ds_read_b128 v[156:159], v118 offset:1024
	ds_read_b128 v[160:163], v118 offset:2048
	ds_read_b128 v[180:183], v118 offset:3072
	ds_read_b128 v[188:191], v118 offset:4096
	ds_read_b128 v[192:195], v118 offset:5120
	ds_read_b128 v[196:199], v118 offset:6144
	ds_read_b128 v[200:203], v118 offset:7168
	global_load_lds_dwordx4 v[214:215], off
	v_lshl_add_u64 v[214:215], v[214:215], 0, s[0:1]
	s_mov_b32 m0, s58
	s_nop 0
	global_load_lds_dwordx4 v[214:215], off
	s_waitcnt vmcnt(8)
	s_waitcnt lgkmcnt(0)
	s_barrier
	s_waitcnt lgkmcnt(0)
	v_mfma_f32_16x16x32_bf16 v[172:175], v[120:123], v[152:155], v[172:175]
	v_mfma_f32_16x16x32_bf16 v[164:167], v[128:131], v[152:155], v[164:167]
	v_mfma_f32_16x16x32_bf16 v[108:111], v[120:123], v[160:163], v[108:111]
	v_mfma_f32_16x16x32_bf16 v[104:107], v[128:131], v[160:163], v[104:107]
	v_mfma_f32_16x16x32_bf16 v[92:95], v[120:123], v[188:191], v[92:95]
	v_mfma_f32_16x16x32_bf16 v[88:91], v[128:131], v[188:191], v[88:91]
	v_mfma_f32_16x16x32_bf16 v[76:79], v[120:123], v[196:199], v[76:79]
	v_mfma_f32_16x16x32_bf16 v[68:71], v[128:131], v[196:199], v[68:71]
	v_mfma_f32_16x16x32_bf16 v[172:175], v[124:127], v[156:159], v[172:175]
	v_mfma_f32_16x16x32_bf16 v[164:167], v[132:135], v[156:159], v[164:167]
	v_mfma_f32_16x16x32_bf16 v[108:111], v[124:127], v[180:183], v[108:111]
	v_mfma_f32_16x16x32_bf16 v[104:107], v[132:135], v[180:183], v[104:107]
	v_mfma_f32_16x16x32_bf16 v[92:95], v[124:127], v[192:195], v[92:95]
	v_mfma_f32_16x16x32_bf16 v[88:91], v[132:135], v[192:195], v[88:91]
	v_mfma_f32_16x16x32_bf16 v[76:79], v[124:127], v[200:203], v[76:79]
	v_mfma_f32_16x16x32_bf16 v[68:71], v[132:135], v[200:203], v[68:71]
	v_mfma_f32_16x16x32_bf16 v[176:179], v[136:139], v[152:155], v[176:179]
	v_mfma_f32_16x16x32_bf16 v[100:103], v[136:139], v[160:163], v[100:103]
	v_mfma_f32_16x16x32_bf16 v[96:99], v[144:147], v[160:163], v[96:99]
	v_mfma_f32_16x16x32_bf16 v[84:87], v[136:139], v[188:191], v[84:87]
	v_mfma_f32_16x16x32_bf16 v[80:83], v[144:147], v[188:191], v[80:83]
	v_mfma_f32_16x16x32_bf16 v[64:67], v[136:139], v[196:199], v[64:67]
	v_mfma_f32_16x16x32_bf16 v[52:55], v[144:147], v[196:199], v[52:55]
	v_mfma_f32_16x16x32_bf16 v[176:179], v[140:143], v[156:159], v[176:179]
	v_mfma_f32_16x16x32_bf16 v[152:155], v[144:147], v[152:155], v[168:171]
	v_mfma_f32_16x16x32_bf16 v[100:103], v[140:143], v[180:183], v[100:103]
	v_mfma_f32_16x16x32_bf16 v[96:99], v[148:151], v[180:183], v[96:99]
	v_mfma_f32_16x16x32_bf16 v[84:87], v[140:143], v[192:195], v[84:87]
	v_mfma_f32_16x16x32_bf16 v[80:83], v[148:151], v[192:195], v[80:83]
	v_mfma_f32_16x16x32_bf16 v[64:67], v[140:143], v[200:203], v[64:67]
	v_mfma_f32_16x16x32_bf16 v[52:55], v[148:151], v[200:203], v[52:55]
	v_mfma_f32_16x16x32_bf16 v[152:155], v[148:151], v[156:159], v[152:155]
	s_barrier
	v_mov_b32_e32 v213, v185
	s_mov_b32 m0, s59
	v_lshl_add_u64 v[216:217], s[72:73], 0, v[212:213]
	ds_read_b128 v[156:159], v118 offset:16384
	ds_read_b128 v[160:163], v118 offset:17408
	ds_read_b128 v[168:171], v118 offset:18432
	ds_read_b128 v[180:183], v118 offset:19456
	ds_read_b128 v[188:191], v118 offset:20480
	ds_read_b128 v[192:195], v118 offset:21504
	ds_read_b128 v[196:199], v118 offset:22528
	ds_read_b128 v[200:203], v118 offset:23552
	global_load_lds_dwordx4 v212, s[72:73]
	v_lshl_add_u64 v[212:213], v[216:217], 0, s[0:1]
	s_mov_b32 m0, s60
	v_lshl_add_u64 v[218:219], s[22:23], 0, v[184:185]
	global_load_lds_dwordx4 v[212:213], off
	v_lshl_add_u64 v[212:213], v[216:217], 0, s[2:3]
	s_mov_b32 m0, s61
	s_nop 0
	global_load_lds_dwordx4 v[212:213], off
	v_lshl_add_u64 v[212:213], v[216:217], 0, s[36:37]
	s_mov_b32 m0, s62
	s_nop 0
	global_load_lds_dwordx4 v[212:213], off
	s_mov_b32 m0, s31
	v_lshl_add_u64 v[212:213], v[218:219], 0, s[0:1]
	global_load_lds_dwordx4 v[218:219], off
	s_mov_b32 m0, s35
	s_nop 0
	global_load_lds_dwordx4 v[212:213], off
	s_waitcnt vmcnt(8)
	s_waitcnt lgkmcnt(0)
	s_barrier
	s_waitcnt lgkmcnt(0)
	v_mfma_f32_16x16x32_bf16 v[72:75], v[120:123], v[156:159], v[72:75]
	v_mfma_f32_16x16x32_bf16 v[60:63], v[128:131], v[156:159], v[60:63]
	v_mfma_f32_16x16x32_bf16 v[44:47], v[120:123], v[168:171], v[44:47]
	v_mfma_f32_16x16x32_bf16 v[40:43], v[128:131], v[168:171], v[40:43]
	v_mfma_f32_16x16x32_bf16 v[28:31], v[120:123], v[188:191], v[28:31]
	v_mfma_f32_16x16x32_bf16 v[24:27], v[128:131], v[188:191], v[24:27]
	v_mfma_f32_16x16x32_bf16 v[12:15], v[120:123], v[196:199], v[12:15]
	v_mfma_f32_16x16x32_bf16 v[8:11], v[128:131], v[196:199], v[8:11]
	v_mfma_f32_16x16x32_bf16 v[72:75], v[124:127], v[160:163], v[72:75]
	v_mfma_f32_16x16x32_bf16 v[60:63], v[132:135], v[160:163], v[60:63]
	v_mfma_f32_16x16x32_bf16 v[44:47], v[124:127], v[180:183], v[44:47]
	v_mfma_f32_16x16x32_bf16 v[40:43], v[132:135], v[180:183], v[40:43]
	v_mfma_f32_16x16x32_bf16 v[28:31], v[124:127], v[192:195], v[28:31]
	v_mfma_f32_16x16x32_bf16 v[24:27], v[132:135], v[192:195], v[24:27]
	v_mfma_f32_16x16x32_bf16 v[12:15], v[124:127], v[200:203], v[12:15]
	v_mfma_f32_16x16x32_bf16 v[8:11], v[132:135], v[200:203], v[8:11]
	v_mfma_f32_16x16x32_bf16 v[56:59], v[136:139], v[156:159], v[56:59]
	v_mfma_f32_16x16x32_bf16 v[48:51], v[144:147], v[156:159], v[48:51]
	v_mfma_f32_16x16x32_bf16 v[36:39], v[136:139], v[168:171], v[36:39]
	v_mfma_f32_16x16x32_bf16 v[32:35], v[144:147], v[168:171], v[32:35]
	v_mfma_f32_16x16x32_bf16 v[20:23], v[136:139], v[188:191], v[20:23]
	v_mfma_f32_16x16x32_bf16 v[16:19], v[144:147], v[188:191], v[16:19]
	v_mfma_f32_16x16x32_bf16 v[4:7], v[136:139], v[196:199], v[4:7]
	v_mfma_f32_16x16x32_bf16 v[0:3], v[144:147], v[196:199], v[0:3]
	v_mfma_f32_16x16x32_bf16 v[56:59], v[140:143], v[160:163], v[56:59]
	v_mfma_f32_16x16x32_bf16 v[48:51], v[148:151], v[160:163], v[48:51]
	v_mfma_f32_16x16x32_bf16 v[36:39], v[140:143], v[180:183], v[36:39]
	v_mfma_f32_16x16x32_bf16 v[32:35], v[148:151], v[180:183], v[32:35]
	v_mfma_f32_16x16x32_bf16 v[20:23], v[140:143], v[192:195], v[20:23]
	v_mfma_f32_16x16x32_bf16 v[16:19], v[148:151], v[192:195], v[16:19]
	v_mfma_f32_16x16x32_bf16 v[4:7], v[140:143], v[200:203], v[4:7]
	v_mfma_f32_16x16x32_bf16 v[0:3], v[148:151], v[200:203], v[0:3]
	s_barrier
; #define PG8_WAIT_V(n) asm volatile("s_waitcnt vmcnt(" #n ")" ::: "memory")
; #define PG8_WAIT_VP() asm volatile("s_waitcnt vmcnt(%0)" :: "n"(8 + Epi::NST) : "memory")
; #define PG8_BAR __builtin_amdgcn_s_barrier()
; template <class Epi, class Sched>
; __device__ __forceinline__ void gemm_phase(PG8_LAS unsigned char* lds, const Sched& S, const Epi& E, int tid_in) {
;     ...
;         { const int t = 0; PG8_KITER(PG8_WAIT_VP()); }
;         for (int t = 2; t < nt; t += 2) PG8_KITER(PG8_WAIT_V(8));
;     ...
;         if (wr == 0) PG8_BAR;
	ds_read_b128 v[120:123], v113
	ds_read_b128 v[124:127], v113 offset:1024
	ds_read_b128 v[128:131], v113 offset:2048
	ds_read_b128 v[132:135], v113 offset:3072
	ds_read_b128 v[136:139], v119
	ds_read_b128 v[140:143], v119 offset:1024
	ds_read_b128 v[144:147], v119 offset:2048
	ds_read_b128 v[148:151], v119 offset:3072
	s_mov_b32 m0, s48
	v_lshl_add_u64 v[168:169], v[218:219], 0, s[2:3]
	ds_read_b128 v[156:159], v118 offset:32768
	ds_read_b128 v[160:163], v118 offset:33792
	ds_read_b128 v[180:183], v118 offset:34816
	ds_read_b128 v[188:191], v118 offset:35840
	ds_read_b128 v[192:195], v118 offset:36864
	ds_read_b128 v[196:199], v118 offset:37888
	ds_read_b128 v[200:203], v118 offset:38912
	ds_read_b128 v[212:215], v118 offset:39936
	global_load_lds_dwordx4 v[168:169], off
	v_lshl_add_u64 v[168:169], v[218:219], 0, s[36:37]
	s_mov_b32 m0, s49
	s_nop 0
	global_load_lds_dwordx4 v[168:169], off
	s_waitcnt vmcnt(8)
	s_waitcnt lgkmcnt(0)
	s_barrier
	s_waitcnt lgkmcnt(0)
	v_mfma_f32_16x16x32_bf16 v[168:171], v[120:123], v[156:159], v[172:175]
	v_mfma_f32_16x16x32_bf16 v[164:167], v[128:131], v[156:159], v[164:167]
	v_mfma_f32_16x16x32_bf16 v[108:111], v[120:123], v[180:183], v[108:111]
	v_mfma_f32_16x16x32_bf16 v[104:107], v[128:131], v[180:183], v[104:107]
	v_mfma_f32_16x16x32_bf16 v[92:95], v[120:123], v[192:195], v[92:95]
	v_mfma_f32_16x16x32_bf16 v[88:91], v[128:131], v[192:195], v[88:91]
	v_mfma_f32_16x16x32_bf16 v[76:79], v[120:123], v[200:203], v[76:79]
	v_mfma_f32_16x16x32_bf16 v[68:71], v[128:131], v[200:203], v[68:71]
	v_mfma_f32_16x16x32_bf16 v[172:175], v[124:127], v[160:163], v[168:171]
	v_mfma_f32_16x16x32_bf16 v[164:167], v[132:135], v[160:163], v[164:167]
	v_mfma_f32_16x16x32_bf16 v[108:111], v[124:127], v[188:191], v[108:111]
	v_mfma_f32_16x16x32_bf16 v[104:107], v[132:135], v[188:191], v[104:107]
	v_mfma_f32_16x16x32_bf16 v[92:95], v[124:127], v[196:199], v[92:95]
	v_mfma_f32_16x16x32_bf16 v[88:91], v[132:135], v[196:199], v[88:91]
	v_mfma_f32_16x16x32_bf16 v[76:79], v[124:127], v[212:215], v[76:79]
	v_mfma_f32_16x16x32_bf16 v[68:71], v[132:135], v[212:215], v[68:71]
	v_mfma_f32_16x16x32_bf16 v[168:171], v[136:139], v[156:159], v[176:179]
	v_mfma_f32_16x16x32_bf16 v[152:155], v[144:147], v[156:159], v[152:155]
	v_mfma_f32_16x16x32_bf16 v[100:103], v[136:139], v[180:183], v[100:103]
	v_mfma_f32_16x16x32_bf16 v[96:99], v[144:147], v[180:183], v[96:99]
	v_mfma_f32_16x16x32_bf16 v[84:87], v[136:139], v[192:195], v[84:87]
	v_mfma_f32_16x16x32_bf16 v[80:83], v[144:147], v[192:195], v[80:83]
	v_mfma_f32_16x16x32_bf16 v[64:67], v[136:139], v[200:203], v[64:67]
	v_mfma_f32_16x16x32_bf16 v[52:55], v[144:147], v[200:203], v[52:55]
	v_mfma_f32_16x16x32_bf16 v[176:179], v[140:143], v[160:163], v[168:171]
	v_mfma_f32_16x16x32_bf16 v[168:171], v[148:151], v[160:163], v[152:155]
	v_mfma_f32_16x16x32_bf16 v[100:103], v[140:143], v[188:191], v[100:103]
	v_mfma_f32_16x16x32_bf16 v[96:99], v[148:151], v[188:191], v[96:99]
	v_mfma_f32_16x16x32_bf16 v[84:87], v[140:143], v[196:199], v[84:87]
	v_mfma_f32_16x16x32_bf16 v[80:83], v[148:151], v[196:199], v[80:83]
	v_mfma_f32_16x16x32_bf16 v[64:67], v[140:143], v[212:215], v[64:67]
	v_mfma_f32_16x16x32_bf16 v[52:55], v[148:151], v[212:215], v[52:55]
	s_barrier
	s_mov_b32 m0, s63
	v_lshl_add_u64 v[212:213], v[216:217], 0, s[84:85]
	ds_read_b128 v[152:155], v118 offset:49152
	ds_read_b128 v[156:159], v118 offset:50176
	ds_read_b128 v[160:163], v118 offset:51200
	ds_read_b128 v[180:183], v118 offset:52224
	ds_read_b128 v[188:191], v118 offset:53248
	ds_read_b128 v[192:195], v118 offset:54272
	ds_read_b128 v[196:199], v118 offset:55296
	ds_read_b128 v[200:203], v118 offset:56320
	global_load_lds_dwordx4 v[212:213], off
	v_lshl_add_u64 v[212:213], v[216:217], 0, s[38:39]
	s_mov_b32 m0, s64
	s_nop 0
	global_load_lds_dwordx4 v[212:213], off
	v_lshl_add_u64 v[212:213], v[216:217], 0, s[40:41]
	s_mov_b32 m0, s65
	s_nop 0
	global_load_lds_dwordx4 v[212:213], off
	v_lshl_add_u64 v[212:213], v[216:217], 0, s[42:43]
	s_mov_b32 m0, s66
	s_nop 0
	global_load_lds_dwordx4 v[212:213], off
	v_lshl_add_u64 v[212:213], v[218:219], 0, s[84:85]
	s_mov_b32 m0, s46
	s_nop 0
	global_load_lds_dwordx4 v[212:213], off
	v_lshl_add_u64 v[212:213], v[218:219], 0, s[38:39]
	s_mov_b32 m0, s47
	s_nop 0
	global_load_lds_dwordx4 v[212:213], off
	s_waitcnt vmcnt(8)
	s_waitcnt lgkmcnt(0)
	s_barrier
	s_waitcnt lgkmcnt(0)
	v_mfma_f32_16x16x32_bf16 v[72:75], v[120:123], v[152:155], v[72:75]
	v_mfma_f32_16x16x32_bf16 v[60:63], v[128:131], v[152:155], v[60:63]
	v_mfma_f32_16x16x32_bf16 v[44:47], v[120:123], v[160:163], v[44:47]
	v_mfma_f32_16x16x32_bf16 v[40:43], v[128:131], v[160:163], v[40:43]
	v_mfma_f32_16x16x32_bf16 v[28:31], v[120:123], v[188:191], v[28:31]
	v_mfma_f32_16x16x32_bf16 v[24:27], v[128:131], v[188:191], v[24:27]
	v_mfma_f32_16x16x32_bf16 v[12:15], v[120:123], v[196:199], v[12:15]
	v_mfma_f32_16x16x32_bf16 v[8:11], v[128:131], v[196:199], v[8:11]
	v_mfma_f32_16x16x32_bf16 v[72:75], v[124:127], v[156:159], v[72:75]
	v_mfma_f32_16x16x32_bf16 v[60:63], v[132:135], v[156:159], v[60:63]
	v_mfma_f32_16x16x32_bf16 v[44:47], v[124:127], v[180:183], v[44:47]
	v_mfma_f32_16x16x32_bf16 v[40:43], v[132:135], v[180:183], v[40:43]
	v_mfma_f32_16x16x32_bf16 v[28:31], v[124:127], v[192:195], v[28:31]
	v_mfma_f32_16x16x32_bf16 v[24:27], v[132:135], v[192:195], v[24:27]
	v_mfma_f32_16x16x32_bf16 v[12:15], v[124:127], v[200:203], v[12:15]
	v_mfma_f32_16x16x32_bf16 v[8:11], v[132:135], v[200:203], v[8:11]
	v_mfma_f32_16x16x32_bf16 v[56:59], v[136:139], v[152:155], v[56:59]
	v_mfma_f32_16x16x32_bf16 v[48:51], v[144:147], v[152:155], v[48:51]
	v_mfma_f32_16x16x32_bf16 v[36:39], v[136:139], v[160:163], v[36:39]
	v_mfma_f32_16x16x32_bf16 v[32:35], v[144:147], v[160:163], v[32:35]
	v_mfma_f32_16x16x32_bf16 v[20:23], v[136:139], v[188:191], v[20:23]
	v_mfma_f32_16x16x32_bf16 v[16:19], v[144:147], v[188:191], v[16:19]
	v_mfma_f32_16x16x32_bf16 v[4:7], v[136:139], v[196:199], v[4:7]
	v_mfma_f32_16x16x32_bf16 v[0:3], v[144:147], v[196:199], v[0:3]
	v_mfma_f32_16x16x32_bf16 v[56:59], v[140:143], v[156:159], v[56:59]
	v_mfma_f32_16x16x32_bf16 v[48:51], v[148:151], v[156:159], v[48:51]
	v_mfma_f32_16x16x32_bf16 v[36:39], v[140:143], v[180:183], v[36:39]
	v_mfma_f32_16x16x32_bf16 v[32:35], v[148:151], v[180:183], v[32:35]
	v_mfma_f32_16x16x32_bf16 v[20:23], v[140:143], v[192:195], v[20:23]
	v_mfma_f32_16x16x32_bf16 v[16:19], v[148:151], v[192:195], v[16:19]
	v_mfma_f32_16x16x32_bf16 v[4:7], v[140:143], v[200:203], v[4:7]
	v_mfma_f32_16x16x32_bf16 v[0:3], v[148:151], v[200:203], v[0:3]
	s_barrier
	s_add_i32 s70, s70, 2
	s_add_u32 s20, s20, 0x100
	s_addc_u32 s21, s21, 0
	s_add_u32 s67, s67, 0x100
	s_addc_u32 s68, s68, 0
	s_cmpk_gt_u32 s70, 0x55
	s_cbranch_scc0 .LBB0_274
	s_and_b64 vcc, exec, s[12:13]
	s_cbranch_vccz .LBB0_277
	s_barrier

; __device__ __forceinline__ int lane_id() { int l; asm volatile("v_mbcnt_lo_u32_b32 %0, -1, 0\n\tv_mbcnt_hi_u32_b32 %0, -1, %0" : "=v"(l)); return l; }
;     __device__ __forceinline__ bool next(int i, UnitG& u) const { if (!P.next(i, u)) return false; u.O = O + ((size_t)u.x0 * 256 * 2048 + (size_t)u.x1 * 256) * 2; u.ldo = 2048; u.kind = 0; return true; }
; template <class Epi, class Sched>
; __device__ __forceinline__ void gemm_phase(PG8_LAS unsigned char* lds, const Sched& S, const Epi& E, int tid_in) {
;     ...
;         int aoff, boff; { const int l3 = lane_id(), fr3 = l3 & 15, fq3 = l3 >> 4; aoff = lds_byte(wr * 64 + fr3, fq3 * 8); boff = lds_byte(wc * 32 + fr3, fq3 * 8); }
;         const bool has_next = S.next(ui + 1, nxt);
;         const char* nA = has_next ? nxt.A : cA; const char* nB = has_next ? nxt.B : cB;
;         const int nlda = has_next ? nxt.lda : cur.lda, nldb = has_next ? nxt.ldb : cur.ldb;
;         unsigned nvA, nvB; { int r2, c2; stage_rc((wid * 64 + lane_id()) * 16, r2, c2); const int rb2 = Epi::PERM ? ((r2 & ~31) + perm32(r2 & 31)) : r2;
;             nvA = (unsigned)(r2 * nlda + c2) * 2u; nvB = (unsigned)(rb2 * nldb + c2) * 2u; }
;         const unsigned nqA = (unsigned)nlda * 128u, nqB = (unsigned)nldb * 128u;
;         const int nt = cur.K / BK;
.LBB0_393:
	v_and_b32_e32 v1, 15, v0
	v_or_b32_e32 v2, s47, v1
	v_ashrrev_i32_e32 v3, 6, v0
	v_lshlrev_b32_e32 v4, 6, v2
	v_and_b32_e32 v5, 48, v0
	s_movk_i32 s53, 0x3c0
	v_lshlrev_b32_e32 v2, 2, v2
	v_and_or_b32 v4, v4, s53, v5
	v_lshl_add_u32 v6, v3, 10, s48
	v_and_b32_e32 v2, 32, v2
	v_lshlrev_b32_e32 v0, 2, v0
	s_waitcnt vmcnt(0)
	v_bitop3_b32 v32, v4, v6, v2 bitop3:0xde
	v_lshl_or_b32 v1, v1, 6, v5
	v_add_lshl_u32 v2, v3, s50, 10
	v_and_b32_e32 v0, 32, v0
	v_bitop3_b32 v137, v1, v2, v0 bitop3:0xde
	v_mbcnt_lo_u32_b32 v0, -1, 0
	v_mbcnt_hi_u32_b32 v0, -1, v0
	s_mov_b32 s53, 0xfffe0
	v_add_u32_e32 v0, s51, v0
	v_ashrrev_i32_e32 v2, 31, v0
	v_lshrrev_b32_e32 v2, 26, v2
	v_lshlrev_b32_e32 v1, 4, v0
	v_add_u32_e32 v2, v0, v2
	v_bfe_i32 v0, v0, 27, 1
	v_lshrrev_b32_e32 v0, 22, v0
	v_add_u32_e32 v0, v1, v0
	v_and_b32_e32 v0, 0xfffffc00, v0
	v_sub_u32_e32 v0, v1, v0
	v_lshrrev_b32_e32 v1, 4, v0
	v_bitop3_b32 v0, v1, v0, 32 bitop3:0x6c
	v_ashrrev_i32_e32 v3, 31, v0
	v_lshrrev_b32_e32 v3, 26, v3
	v_ashrrev_i32_e32 v2, 6, v2
	v_add_u32_e32 v3, v0, v3
	v_lshlrev_b32_e32 v1, 3, v2
	v_ashrrev_i32_e32 v4, 6, v3
	v_and_b32_e32 v3, 0xc0, v3
	v_and_b32_e32 v1, -16, v1
	v_sub_u32_e32 v0, v0, v3
	v_add_u32_e32 v1, v4, v1
	v_lshlrev_b32_e32 v2, 5, v2
	v_ashrrev_i16_sdwa v0, v205, sext(v0) dst_sel:DWORD dst_unused:UNUSED_PAD src0_sel:DWORD src1_sel:BYTE_0
	v_and_b32_e32 v2, 32, v2
	v_bfe_i32 v0, v0, 0, 16
	v_lshlrev_b32_e32 v3, 1, v1
	v_lshrrev_b32_e32 v5, 2, v1
	v_and_b32_e32 v4, 3, v4
	s_add_i32 s55, 0, 0x10000
	s_add_i32 s57, 0, 0x14000
	v_and_b32_e32 v3, 24, v3
	v_and_b32_e32 v5, 4, v5
	v_and_or_b32 v4, v1, s53, v4
	v_add_lshl_u32 v34, v2, v0, 1
	v_add_u32_e32 v134, s55, v137
	v_add_u32_e32 v135, s57, v137
	v_or3_b32 v33, v4, v5, v3
	v_lshl_add_u32 v128, v1, 12, v34
	ds_read_b128 v[0:3], v134
	ds_read_b128 v[4:7], v134 offset:1024
	ds_read_b128 v[8:11], v134 offset:2048
	ds_read_b128 v[12:15], v134 offset:3072
	ds_read_b128 v[16:19], v135
	ds_read_b128 v[20:23], v135 offset:1024
	ds_read_b128 v[24:27], v135 offset:2048
	ds_read_b128 v[28:31], v135 offset:3072
	v_lshl_add_u32 v129, v33, 12, v34
	v_mov_b32_e32 v133, v185
	v_lshl_add_u64 v[182:183], s[18:19], 0, v[132:133]
	s_add_i32 s53, s29, 0xc000
	v_add_u32_e32 v136, 0, v32
	v_lshl_add_u64 v[64:65], v[182:183], 0, s[80:81]
	s_mov_b32 m0, s53
	s_add_i32 s54, s29, 0xe000
	ds_read_b128 v[32:35], v136
	ds_read_b128 v[36:39], v136 offset:1024
	ds_read_b128 v[40:43], v136 offset:2048
	ds_read_b128 v[44:47], v136 offset:3072
	ds_read_b128 v[48:51], v136 offset:4096
	ds_read_b128 v[52:55], v136 offset:5120
	ds_read_b128 v[56:59], v136 offset:6144
	ds_read_b128 v[60:63], v136 offset:7168
	global_load_lds_dwordx4 v[64:65], off
	v_lshl_add_u64 v[64:65], v[182:183], 0, s[78:79]
	s_mov_b32 m0, s54
	s_nop 0
	global_load_lds_dwordx4 v[64:65], off
	s_waitcnt vmcnt(24)
	s_waitcnt lgkmcnt(0)
	s_barrier
	s_waitcnt lgkmcnt(0)
	v_mfma_f32_16x16x32_bf16 v[64:67], v[0:3], v[32:35], 0
	v_mfma_f32_16x16x32_bf16 v[68:71], v[8:11], v[32:35], 0
	v_mfma_f32_16x16x32_bf16 v[72:75], v[0:3], v[40:43], 0
	v_mfma_f32_16x16x32_bf16 v[76:79], v[8:11], v[40:43], 0
	v_mfma_f32_16x16x32_bf16 v[80:83], v[0:3], v[48:51], 0
	v_mfma_f32_16x16x32_bf16 v[84:87], v[8:11], v[48:51], 0
	v_mfma_f32_16x16x32_bf16 v[88:91], v[0:3], v[56:59], 0
	v_mfma_f32_16x16x32_bf16 v[92:95], v[8:11], v[56:59], 0
	v_mfma_f32_16x16x32_bf16 v[64:67], v[4:7], v[36:39], v[64:67]
	v_mfma_f32_16x16x32_bf16 v[68:71], v[12:15], v[36:39], v[68:71]
	v_mfma_f32_16x16x32_bf16 v[72:75], v[4:7], v[44:47], v[72:75]
	v_mfma_f32_16x16x32_bf16 v[76:79], v[12:15], v[44:47], v[76:79]
	v_mfma_f32_16x16x32_bf16 v[80:83], v[4:7], v[52:55], v[80:83]
	v_mfma_f32_16x16x32_bf16 v[84:87], v[12:15], v[52:55], v[84:87]
	v_mfma_f32_16x16x32_bf16 v[88:91], v[4:7], v[60:63], v[88:91]
	v_mfma_f32_16x16x32_bf16 v[92:95], v[12:15], v[60:63], v[92:95]
	v_mfma_f32_16x16x32_bf16 v[96:99], v[16:19], v[32:35], 0
	v_mfma_f32_16x16x32_bf16 v[32:35], v[24:27], v[32:35], 0
	v_mfma_f32_16x16x32_bf16 v[108:111], v[28:31], v[36:39], v[32:35]
	v_mfma_f32_16x16x32_bf16 v[32:35], v[16:19], v[40:43], 0
	v_mfma_f32_16x16x32_bf16 v[138:141], v[20:23], v[44:47], v[32:35]
	v_mfma_f32_16x16x32_bf16 v[32:35], v[24:27], v[40:43], 0
	v_mfma_f32_16x16x32_bf16 v[40:43], v[28:31], v[44:47], v[32:35]
	v_mfma_f32_16x16x32_bf16 v[32:35], v[16:19], v[48:51], 0
	v_mfma_f32_16x16x32_bf16 v[44:47], v[20:23], v[52:55], v[32:35]
	v_mfma_f32_16x16x32_bf16 v[32:35], v[24:27], v[48:51], 0
	v_mfma_f32_16x16x32_bf16 v[48:51], v[28:31], v[52:55], v[32:35]
	v_mfma_f32_16x16x32_bf16 v[32:35], v[16:19], v[56:59], 0
	v_mfma_f32_16x16x32_bf16 v[52:55], v[20:23], v[60:63], v[32:35]
	v_mfma_f32_16x16x32_bf16 v[32:35], v[24:27], v[56:59], 0
	v_mfma_f32_16x16x32_bf16 v[104:107], v[20:23], v[36:39], v[96:99]
	v_mfma_f32_16x16x32_bf16 v[56:59], v[28:31], v[60:63], v[32:35]
	s_barrier
	v_mov_b32_e32 v131, v185
	v_lshl_add_u64 v[248:249], s[20:21], 0, v[130:131]
	s_mov_b64 s[60:61], 0x100
	s_add_i32 s55, s55, s28
	v_lshl_add_u64 v[124:125], v[248:249], 0, s[60:61]
	s_mov_b32 m0, s55
	s_mov_b64 s[62:63], 0x40100
	s_add_i32 s56, s55, 0x2000
	ds_read_b128 v[32:35], v136 offset:16384
	ds_read_b128 v[36:39], v136 offset:17408
	ds_read_b128 v[60:63], v136 offset:18432
	ds_read_b128 v[96:99], v136 offset:19456
	ds_read_b128 v[100:103], v136 offset:20480
	ds_read_b128 v[112:115], v136 offset:21504
	ds_read_b128 v[116:119], v136 offset:22528
	ds_read_b128 v[120:123], v136 offset:23552
	global_load_lds_dwordx4 v[124:125], off
	v_lshl_add_u64 v[124:125], v[248:249], 0, s[62:63]
	s_mov_b32 m0, s56
	s_mov_b64 s[64:65], 0x80100
	s_add_i32 s57, s57, s28
	global_load_lds_dwordx4 v[124:125], off
	v_lshl_add_u64 v[124:125], v[248:249], 0, s[64:65]
	s_mov_b32 m0, s57
	s_mov_b64 s[66:67], 0xc0100
	s_add_i32 s58, s57, 0x2000
	global_load_lds_dwordx4 v[124:125], off
	v_lshl_add_u64 v[124:125], v[248:249], 0, s[66:67]
	s_mov_b32 m0, s58
	s_nop 0
	global_load_lds_dwordx4 v[124:125], off
	v_lshl_add_u64 v[124:125], v[182:183], 0, s[60:61]
	s_mov_b32 m0, s29
	s_nop 0
	global_load_lds_dwordx4 v[124:125], off
	v_lshl_add_u64 v[124:125], v[182:183], 0, s[62:63]
	s_mov_b32 m0, s30
	s_nop 0
	global_load_lds_dwordx4 v[124:125], off
	s_waitcnt vmcnt(24)
	s_waitcnt lgkmcnt(0)
	s_barrier
	s_waitcnt lgkmcnt(0)
	v_mfma_f32_16x16x32_bf16 v[124:127], v[0:3], v[32:35], 0
	v_mfma_f32_16x16x32_bf16 v[142:145], v[4:7], v[36:39], v[124:127]
	v_mfma_f32_16x16x32_bf16 v[124:127], v[8:11], v[32:35], 0
	v_mfma_f32_16x16x32_bf16 v[146:149], v[12:15], v[36:39], v[124:127]
	v_mfma_f32_16x16x32_bf16 v[124:127], v[0:3], v[60:63], 0
	v_mfma_f32_16x16x32_bf16 v[150:153], v[4:7], v[96:99], v[124:127]
	v_mfma_f32_16x16x32_bf16 v[124:127], v[8:11], v[60:63], 0
	v_mfma_f32_16x16x32_bf16 v[154:157], v[12:15], v[96:99], v[124:127]
	v_mfma_f32_16x16x32_bf16 v[124:127], v[0:3], v[100:103], 0
	v_mfma_f32_16x16x32_bf16 v[0:3], v[0:3], v[116:119], 0
	v_mfma_f32_16x16x32_bf16 v[158:161], v[4:7], v[112:115], v[124:127]
	v_mfma_f32_16x16x32_bf16 v[0:3], v[4:7], v[120:123], v[0:3]
	v_mfma_f32_16x16x32_bf16 v[4:7], v[8:11], v[116:119], 0
	v_mfma_f32_16x16x32_bf16 v[124:127], v[8:11], v[100:103], 0
	v_mfma_f32_16x16x32_bf16 v[8:11], v[12:15], v[120:123], v[4:7]
	v_mfma_f32_16x16x32_bf16 v[162:165], v[12:15], v[112:115], v[124:127]
	v_mfma_f32_16x16x32_bf16 v[4:7], v[16:19], v[32:35], 0
	v_mfma_f32_16x16x32_bf16 v[12:15], v[20:23], v[36:39], v[4:7]
	v_mfma_f32_16x16x32_bf16 v[4:7], v[24:27], v[32:35], 0
	v_mfma_f32_16x16x32_bf16 v[166:169], v[28:31], v[36:39], v[4:7]
	v_mfma_f32_16x16x32_bf16 v[4:7], v[16:19], v[60:63], 0
	v_mfma_f32_16x16x32_bf16 v[170:173], v[20:23], v[96:99], v[4:7]
	v_mfma_f32_16x16x32_bf16 v[4:7], v[24:27], v[60:63], 0
	v_mfma_f32_16x16x32_bf16 v[174:177], v[28:31], v[96:99], v[4:7]
	v_mfma_f32_16x16x32_bf16 v[4:7], v[16:19], v[100:103], 0
	v_mfma_f32_16x16x32_bf16 v[178:181], v[20:23], v[112:115], v[4:7]
	v_mfma_f32_16x16x32_bf16 v[4:7], v[24:27], v[100:103], 0
	v_mfma_f32_16x16x32_bf16 v[188:191], v[28:31], v[112:115], v[4:7]
	v_mfma_f32_16x16x32_bf16 v[4:7], v[16:19], v[116:119], 0
	v_mfma_f32_16x16x32_bf16 v[192:195], v[20:23], v[120:123], v[4:7]
	v_mfma_f32_16x16x32_bf16 v[4:7], v[24:27], v[116:119], 0
	v_mfma_f32_16x16x32_bf16 v[196:199], v[28:31], v[120:123], v[4:7]
	s_barrier
	s_add_i32 s59, 0, 0x18000
	s_add_i32 s61, 0, 0x1c000
	v_add_u32_e32 v131, s59, v137
	v_add_u32_e32 v137, s61, v137
	s_nop 0
	ds_read_b128 v[4:7], v131
	ds_read_b128 v[24:27], v131 offset:1024
	ds_read_b128 v[28:31], v131 offset:2048
	ds_read_b128 v[60:63], v131 offset:3072
	ds_read_b128 v[200:203], v137
	ds_read_b128 v[212:215], v137 offset:1024
	ds_read_b128 v[216:219], v137 offset:2048
	ds_read_b128 v[220:223], v137 offset:3072
	s_mov_b32 m0, s31
	v_lshl_add_u64 v[32:33], v[182:183], 0, s[64:65]
	ds_read_b128 v[16:19], v136 offset:32768
	ds_read_b128 v[20:23], v136 offset:33792
	ds_read_b128 v[224:227], v136 offset:34816
	ds_read_b128 v[228:231], v136 offset:35840
	ds_read_b128 v[232:235], v136 offset:36864
	ds_read_b128 v[236:239], v136 offset:37888
	ds_read_b128 v[240:243], v136 offset:38912
	ds_read_b128 v[244:247], v136 offset:39936
	global_load_lds_dwordx4 v[32:33], off
	v_lshl_add_u64 v[32:33], v[182:183], 0, s[66:67]
	s_mov_b32 m0, s34
	s_nop 0
	global_load_lds_dwordx4 v[32:33], off
	s_waitcnt vmcnt(8)
	s_waitcnt lgkmcnt(0)
	s_barrier
	s_waitcnt lgkmcnt(0)
	v_mfma_f32_16x16x32_bf16 v[32:35], v[4:7], v[16:19], v[64:67]
	v_mfma_f32_16x16x32_bf16 v[116:119], v[24:27], v[20:23], v[32:35]
	v_mfma_f32_16x16x32_bf16 v[32:35], v[28:31], v[16:19], v[68:71]
	v_mfma_f32_16x16x32_bf16 v[112:115], v[60:63], v[20:23], v[32:35]
	v_mfma_f32_16x16x32_bf16 v[32:35], v[4:7], v[224:227], v[72:75]
	v_mfma_f32_16x16x32_bf16 v[100:103], v[24:27], v[228:231], v[32:35]
	v_mfma_f32_16x16x32_bf16 v[32:35], v[28:31], v[224:227], v[76:79]
	v_mfma_f32_16x16x32_bf16 v[96:99], v[60:63], v[228:231], v[32:35]
	v_mfma_f32_16x16x32_bf16 v[32:35], v[4:7], v[232:235], v[80:83]
	v_mfma_f32_16x16x32_bf16 v[68:71], v[24:27], v[236:239], v[32:35]
	v_mfma_f32_16x16x32_bf16 v[32:35], v[28:31], v[232:235], v[84:87]
	v_mfma_f32_16x16x32_bf16 v[64:67], v[60:63], v[236:239], v[32:35]
	v_mfma_f32_16x16x32_bf16 v[32:35], v[4:7], v[240:243], v[88:91]
	v_mfma_f32_16x16x32_bf16 v[36:39], v[24:27], v[244:247], v[32:35]
	v_mfma_f32_16x16x32_bf16 v[32:35], v[28:31], v[240:243], v[92:95]
	v_mfma_f32_16x16x32_bf16 v[32:35], v[60:63], v[244:247], v[32:35]
	v_mfma_f32_16x16x32_bf16 v[72:75], v[200:203], v[16:19], v[104:107]
	v_mfma_f32_16x16x32_bf16 v[16:19], v[216:219], v[16:19], v[108:111]
	v_mfma_f32_16x16x32_bf16 v[120:123], v[220:223], v[20:23], v[16:19]
	v_mfma_f32_16x16x32_bf16 v[16:19], v[200:203], v[224:227], v[138:141]
	v_mfma_f32_16x16x32_bf16 v[108:111], v[212:215], v[228:231], v[16:19]
	v_mfma_f32_16x16x32_bf16 v[16:19], v[216:219], v[224:227], v[40:43]
	v_mfma_f32_16x16x32_bf16 v[104:107], v[220:223], v[228:231], v[16:19]
	v_mfma_f32_16x16x32_bf16 v[16:19], v[200:203], v[232:235], v[44:47]
	v_mfma_f32_16x16x32_bf16 v[76:79], v[212:215], v[236:239], v[16:19]
	v_mfma_f32_16x16x32_bf16 v[16:19], v[216:219], v[232:235], v[48:51]
	v_mfma_f32_16x16x32_bf16 v[124:127], v[212:215], v[20:23], v[72:75]
	v_mfma_f32_16x16x32_bf16 v[72:75], v[220:223], v[236:239], v[16:19]
	v_mfma_f32_16x16x32_bf16 v[16:19], v[200:203], v[240:243], v[52:55]
	v_mfma_f32_16x16x32_bf16 v[44:47], v[212:215], v[244:247], v[16:19]
	v_mfma_f32_16x16x32_bf16 v[16:19], v[216:219], v[240:243], v[56:59]
	v_mfma_f32_16x16x32_bf16 v[40:43], v[220:223], v[244:247], v[16:19]
	s_barrier
; #define PG8_WAIT_V(n) asm volatile("s_waitcnt vmcnt(" #n ")" ::: "memory")
; #define PG8_WAIT_VP() asm volatile("s_waitcnt vmcnt(%0)" :: "n"(8 + Epi::NST) : "memory")
; template <class Epi, class Sched>
; __device__ __forceinline__ void gemm_phase(PG8_LAS unsigned char* lds, const Sched& S, const Epi& E, int tid_in) {
;     ...
;         { const int t = 0; PG8_KITER(PG8_WAIT_VP()); }
;         for (int t = 2; t < nt; t += 2) PG8_KITER(PG8_WAIT_V(8));
	s_mov_b64 s[64:65], 0x180
	s_add_i32 s59, s59, s28
	s_nop 2
	v_lshl_add_u64 v[16:17], v[248:249], 0, s[64:65]
	s_mov_b32 m0, s59
	s_mov_b64 s[66:67], 0x40180
	s_add_i32 s60, s59, 0x2000
	ds_read_b128 v[56:59], v136 offset:49152
	ds_read_b128 v[88:91], v136 offset:50176
	ds_read_b128 v[138:141], v136 offset:51200
	ds_read_b128 v[224:227], v136 offset:52224
	ds_read_b128 v[228:231], v136 offset:53248
	ds_read_b128 v[232:235], v136 offset:54272
	ds_read_b128 v[236:239], v136 offset:55296
	ds_read_b128 v[240:243], v136 offset:56320
	global_load_lds_dwordx4 v[16:17], off
	v_lshl_add_u64 v[16:17], v[248:249], 0, s[66:67]
	s_mov_b32 m0, s60
	s_add_i32 s61, s61, s28
	global_load_lds_dwordx4 v[16:17], off
	v_lshl_add_u64 v[16:17], v[248:249], 0, s[70:71]
	s_mov_b32 m0, s61
	s_add_i32 s62, s61, 0x2000
	global_load_lds_dwordx4 v[16:17], off
	v_lshl_add_u64 v[16:17], v[248:249], 0, s[72:73]
	s_mov_b32 m0, s62
	s_nop 0
	global_load_lds_dwordx4 v[16:17], off
	v_lshl_add_u64 v[16:17], v[182:183], 0, s[64:65]
	s_mov_b32 m0, s45
	s_nop 0
	global_load_lds_dwordx4 v[16:17], off
	v_lshl_add_u64 v[16:17], v[182:183], 0, s[66:67]
	s_mov_b32 m0, s46
	s_nop 0
	global_load_lds_dwordx4 v[16:17], off
	s_waitcnt vmcnt(8)
	s_waitcnt lgkmcnt(0)
	s_barrier
	s_waitcnt lgkmcnt(0)
	v_mfma_f32_16x16x32_bf16 v[16:19], v[4:7], v[56:59], v[142:145]
	v_mfma_f32_16x16x32_bf16 v[84:87], v[24:27], v[88:91], v[16:19]
	v_mfma_f32_16x16x32_bf16 v[16:19], v[28:31], v[56:59], v[146:149]
	v_mfma_f32_16x16x32_bf16 v[80:83], v[60:63], v[88:91], v[16:19]
	v_mfma_f32_16x16x32_bf16 v[16:19], v[4:7], v[138:141], v[150:153]
	v_mfma_f32_16x16x32_bf16 v[52:55], v[24:27], v[224:227], v[16:19]
	v_mfma_f32_16x16x32_bf16 v[16:19], v[28:31], v[138:141], v[154:157]
	v_mfma_f32_16x16x32_bf16 v[48:51], v[60:63], v[224:227], v[16:19]
	v_mfma_f32_16x16x32_bf16 v[16:19], v[4:7], v[228:231], v[158:161]
	v_mfma_f32_16x16x32_bf16 v[0:3], v[4:7], v[236:239], v[0:3]
	v_mfma_f32_16x16x32_bf16 v[20:23], v[24:27], v[232:235], v[16:19]
	v_mfma_f32_16x16x32_bf16 v[16:19], v[28:31], v[228:231], v[162:165]
	v_mfma_f32_16x16x32_bf16 v[4:7], v[24:27], v[240:243], v[0:3]
	v_mfma_f32_16x16x32_bf16 v[0:3], v[28:31], v[236:239], v[8:11]
	v_mfma_f32_16x16x32_bf16 v[16:19], v[60:63], v[232:235], v[16:19]
	v_mfma_f32_16x16x32_bf16 v[0:3], v[60:63], v[240:243], v[0:3]
	v_mfma_f32_16x16x32_bf16 v[8:11], v[200:203], v[56:59], v[12:15]
	v_mfma_f32_16x16x32_bf16 v[92:95], v[212:215], v[88:91], v[8:11]
	v_mfma_f32_16x16x32_bf16 v[8:11], v[216:219], v[56:59], v[166:169]
	v_mfma_f32_16x16x32_bf16 v[88:91], v[220:223], v[88:91], v[8:11]
	v_mfma_f32_16x16x32_bf16 v[8:11], v[200:203], v[138:141], v[170:173]
	v_mfma_f32_16x16x32_bf16 v[60:63], v[212:215], v[224:227], v[8:11]
	v_mfma_f32_16x16x32_bf16 v[8:11], v[216:219], v[138:141], v[174:177]
	v_mfma_f32_16x16x32_bf16 v[56:59], v[220:223], v[224:227], v[8:11]
	v_mfma_f32_16x16x32_bf16 v[8:11], v[200:203], v[228:231], v[178:181]
	v_mfma_f32_16x16x32_bf16 v[28:31], v[212:215], v[232:235], v[8:11]
	v_mfma_f32_16x16x32_bf16 v[8:11], v[216:219], v[228:231], v[188:191]
	v_mfma_f32_16x16x32_bf16 v[24:27], v[220:223], v[232:235], v[8:11]
	v_mfma_f32_16x16x32_bf16 v[8:11], v[200:203], v[236:239], v[192:195]
	v_mfma_f32_16x16x32_bf16 v[12:15], v[212:215], v[240:243], v[8:11]
	v_mfma_f32_16x16x32_bf16 v[8:11], v[216:219], v[236:239], v[196:199]
	v_mfma_f32_16x16x32_bf16 v[8:11], v[220:223], v[240:243], v[8:11]
	s_barrier
	s_add_u32 s18, s18, 0x80180
	s_addc_u32 s19, s19, 0
	s_add_u32 s63, s20, 0x200
	s_addc_u32 s64, s21, 0
	s_mov_b32 s65, 0
.LBB0_394:
	ds_read_b128 v[138:141], v134
	ds_read_b128 v[142:145], v134 offset:1024
	ds_read_b128 v[146:149], v134 offset:2048
	ds_read_b128 v[150:153], v134 offset:3072
	ds_read_b128 v[154:157], v135
	ds_read_b128 v[158:161], v135 offset:1024
	ds_read_b128 v[162:165], v135 offset:2048
	ds_read_b128 v[166:169], v135 offset:3072
	s_add_u32 s66, s18, 0xfff80080
	s_addc_u32 s67, s19, -1
	s_cmp_eq_u32 s65, 28
	s_cselect_b64 vcc, -1, 0
	s_and_b64 s[20:21], vcc, exec
	v_cndmask_b32_e32 v184, v132, v128, vcc
	s_cselect_b32 s21, s13, s67
	s_cselect_b32 s20, s12, s66
	v_cndmask_b32_e32 v182, v130, v129, vcc
	s_cselect_b32 s67, s15, s64
	s_cselect_b32 s66, s14, s63
	s_mov_b32 m0, s53
	v_lshl_add_u64 v[216:217], s[18:19], 0, v[132:133]
	ds_read_b128 v[170:173], v136
	ds_read_b128 v[174:177], v136 offset:1024
	ds_read_b128 v[178:181], v136 offset:2048
	ds_read_b128 v[188:191], v136 offset:3072
	ds_read_b128 v[192:195], v136 offset:4096
	ds_read_b128 v[196:199], v136 offset:5120
	ds_read_b128 v[200:203], v136 offset:6144
	ds_read_b128 v[212:215], v136 offset:7168
	global_load_lds_dwordx4 v[216:217], off
	v_lshl_add_u64 v[216:217], v[216:217], 0, s[88:89]
	s_mov_b32 m0, s54
	s_nop 0
	global_load_lds_dwordx4 v[216:217], off
	s_waitcnt vmcnt(8)
	s_waitcnt lgkmcnt(0)
	s_barrier
	s_waitcnt lgkmcnt(0)
	v_mfma_f32_16x16x32_bf16 v[116:119], v[138:141], v[170:173], v[116:119]
	v_mfma_f32_16x16x32_bf16 v[112:115], v[146:149], v[170:173], v[112:115]
	v_mfma_f32_16x16x32_bf16 v[100:103], v[138:141], v[178:181], v[100:103]
	v_mfma_f32_16x16x32_bf16 v[96:99], v[146:149], v[178:181], v[96:99]
	v_mfma_f32_16x16x32_bf16 v[68:71], v[138:141], v[192:195], v[68:71]
	v_mfma_f32_16x16x32_bf16 v[64:67], v[146:149], v[192:195], v[64:67]
	v_mfma_f32_16x16x32_bf16 v[36:39], v[138:141], v[200:203], v[36:39]
	v_mfma_f32_16x16x32_bf16 v[32:35], v[146:149], v[200:203], v[32:35]
	v_mfma_f32_16x16x32_bf16 v[116:119], v[142:145], v[174:177], v[116:119]
	v_mfma_f32_16x16x32_bf16 v[112:115], v[150:153], v[174:177], v[112:115]
	v_mfma_f32_16x16x32_bf16 v[100:103], v[142:145], v[188:191], v[100:103]
	v_mfma_f32_16x16x32_bf16 v[96:99], v[150:153], v[188:191], v[96:99]
	v_mfma_f32_16x16x32_bf16 v[68:71], v[142:145], v[196:199], v[68:71]
	v_mfma_f32_16x16x32_bf16 v[64:67], v[150:153], v[196:199], v[64:67]
	v_mfma_f32_16x16x32_bf16 v[36:39], v[142:145], v[212:215], v[36:39]
	v_mfma_f32_16x16x32_bf16 v[32:35], v[150:153], v[212:215], v[32:35]
	v_mfma_f32_16x16x32_bf16 v[124:127], v[154:157], v[170:173], v[124:127]
	v_mfma_f32_16x16x32_bf16 v[120:123], v[162:165], v[170:173], v[120:123]
	v_mfma_f32_16x16x32_bf16 v[108:111], v[154:157], v[178:181], v[108:111]
	v_mfma_f32_16x16x32_bf16 v[104:107], v[162:165], v[178:181], v[104:107]
	v_mfma_f32_16x16x32_bf16 v[76:79], v[154:157], v[192:195], v[76:79]
	v_mfma_f32_16x16x32_bf16 v[72:75], v[162:165], v[192:195], v[72:75]
	v_mfma_f32_16x16x32_bf16 v[44:47], v[154:157], v[200:203], v[44:47]
	v_mfma_f32_16x16x32_bf16 v[40:43], v[162:165], v[200:203], v[40:43]
	v_mfma_f32_16x16x32_bf16 v[124:127], v[158:161], v[174:177], v[124:127]
	v_mfma_f32_16x16x32_bf16 v[120:123], v[166:169], v[174:177], v[120:123]
	v_mfma_f32_16x16x32_bf16 v[108:111], v[158:161], v[188:191], v[108:111]
	v_mfma_f32_16x16x32_bf16 v[104:107], v[166:169], v[188:191], v[104:107]
	v_mfma_f32_16x16x32_bf16 v[76:79], v[158:161], v[196:199], v[76:79]
	v_mfma_f32_16x16x32_bf16 v[72:75], v[166:169], v[196:199], v[72:75]
	v_mfma_f32_16x16x32_bf16 v[44:47], v[158:161], v[212:215], v[44:47]
	v_mfma_f32_16x16x32_bf16 v[40:43], v[166:169], v[212:215], v[40:43]
	s_barrier
	v_mov_b32_e32 v183, v185
	s_mov_b32 m0, s55
	v_lshl_add_u64 v[216:217], s[66:67], 0, v[182:183]
	ds_read_b128 v[170:173], v136 offset:16384
	ds_read_b128 v[174:177], v136 offset:17408
	ds_read_b128 v[178:181], v136 offset:18432
	ds_read_b128 v[188:191], v136 offset:19456
	ds_read_b128 v[192:195], v136 offset:20480
	ds_read_b128 v[196:199], v136 offset:21504
	ds_read_b128 v[200:203], v136 offset:22528
	ds_read_b128 v[212:215], v136 offset:23552
	global_load_lds_dwordx4 v182, s[66:67]
	v_lshl_add_u64 v[182:183], v[216:217], 0, s[88:89]
	s_mov_b32 m0, s56
	s_nop 0
	global_load_lds_dwordx4 v[182:183], off
	v_lshl_add_u64 v[182:183], v[216:217], 0, s[90:91]
	s_mov_b32 m0, s57
	s_nop 0
	global_load_lds_dwordx4 v[182:183], off
	v_lshl_add_u64 v[182:183], v[216:217], 0, s[96:97]
	s_mov_b32 m0, s58
	s_nop 0
	global_load_lds_dwordx4 v[182:183], off
	v_lshl_add_u64 v[182:183], s[20:21], 0, v[184:185]
	s_mov_b32 m0, s29
	v_lshl_add_u64 v[218:219], v[182:183], 0, s[88:89]
	global_load_lds_dwordx4 v[182:183], off
	s_mov_b32 m0, s30
	s_nop 0
	global_load_lds_dwordx4 v[218:219], off
	s_waitcnt vmcnt(8)
	s_waitcnt lgkmcnt(0)
	s_barrier
	s_waitcnt lgkmcnt(0)
	v_mfma_f32_16x16x32_bf16 v[84:87], v[138:141], v[170:173], v[84:87]
	v_mfma_f32_16x16x32_bf16 v[80:83], v[146:149], v[170:173], v[80:83]
	v_mfma_f32_16x16x32_bf16 v[52:55], v[138:141], v[178:181], v[52:55]
	v_mfma_f32_16x16x32_bf16 v[48:51], v[146:149], v[178:181], v[48:51]
	v_mfma_f32_16x16x32_bf16 v[20:23], v[138:141], v[192:195], v[20:23]
	v_mfma_f32_16x16x32_bf16 v[16:19], v[146:149], v[192:195], v[16:19]
	v_mfma_f32_16x16x32_bf16 v[4:7], v[138:141], v[200:203], v[4:7]
	v_mfma_f32_16x16x32_bf16 v[0:3], v[146:149], v[200:203], v[0:3]
	v_mfma_f32_16x16x32_bf16 v[84:87], v[142:145], v[174:177], v[84:87]
	v_mfma_f32_16x16x32_bf16 v[80:83], v[150:153], v[174:177], v[80:83]
	v_mfma_f32_16x16x32_bf16 v[52:55], v[142:145], v[188:191], v[52:55]
	v_mfma_f32_16x16x32_bf16 v[48:51], v[150:153], v[188:191], v[48:51]
	v_mfma_f32_16x16x32_bf16 v[20:23], v[142:145], v[196:199], v[20:23]
	v_mfma_f32_16x16x32_bf16 v[16:19], v[150:153], v[196:199], v[16:19]
	v_mfma_f32_16x16x32_bf16 v[4:7], v[142:145], v[212:215], v[4:7]
	v_mfma_f32_16x16x32_bf16 v[0:3], v[150:153], v[212:215], v[0:3]
	v_mfma_f32_16x16x32_bf16 v[92:95], v[154:157], v[170:173], v[92:95]
	v_mfma_f32_16x16x32_bf16 v[88:91], v[162:165], v[170:173], v[88:91]
	v_mfma_f32_16x16x32_bf16 v[60:63], v[154:157], v[178:181], v[60:63]
	v_mfma_f32_16x16x32_bf16 v[56:59], v[162:165], v[178:181], v[56:59]
	v_mfma_f32_16x16x32_bf16 v[28:31], v[154:157], v[192:195], v[28:31]
	v_mfma_f32_16x16x32_bf16 v[24:27], v[162:165], v[192:195], v[24:27]
	v_mfma_f32_16x16x32_bf16 v[12:15], v[154:157], v[200:203], v[12:15]
	v_mfma_f32_16x16x32_bf16 v[8:11], v[162:165], v[200:203], v[8:11]
	v_mfma_f32_16x16x32_bf16 v[92:95], v[158:161], v[174:177], v[92:95]
	v_mfma_f32_16x16x32_bf16 v[88:91], v[166:169], v[174:177], v[88:91]
	v_mfma_f32_16x16x32_bf16 v[60:63], v[158:161], v[188:191], v[60:63]
	v_mfma_f32_16x16x32_bf16 v[56:59], v[166:169], v[188:191], v[56:59]
	v_mfma_f32_16x16x32_bf16 v[28:31], v[158:161], v[196:199], v[28:31]
	v_mfma_f32_16x16x32_bf16 v[24:27], v[166:169], v[196:199], v[24:27]
	v_mfma_f32_16x16x32_bf16 v[12:15], v[158:161], v[212:215], v[12:15]
	v_mfma_f32_16x16x32_bf16 v[8:11], v[166:169], v[212:215], v[8:11]
	s_barrier
; #define PG8_WAIT_V(n) asm volatile("s_waitcnt vmcnt(" #n ")" ::: "memory")
; #define PG8_WAIT_VP() asm volatile("s_waitcnt vmcnt(%0)" :: "n"(8 + Epi::NST) : "memory")
; #define PG8_BAR __builtin_amdgcn_s_barrier()
; template <class Epi, class Sched>
; __device__ __forceinline__ void gemm_phase(PG8_LAS unsigned char* lds, const Sched& S, const Epi& E, int tid_in) {
;     ...
;         { const int t = 0; PG8_KITER(PG8_WAIT_VP()); }
;         for (int t = 2; t < nt; t += 2) PG8_KITER(PG8_WAIT_V(8));
;     ...
;         if (wr == 0) PG8_BAR;
	ds_read_b128 v[138:141], v131
	ds_read_b128 v[142:145], v131 offset:1024
	ds_read_b128 v[146:149], v131 offset:2048
	ds_read_b128 v[150:153], v131 offset:3072
	ds_read_b128 v[154:157], v137
	ds_read_b128 v[158:161], v137 offset:1024
	ds_read_b128 v[162:165], v137 offset:2048
	ds_read_b128 v[166:169], v137 offset:3072
	s_mov_b32 m0, s31
	v_lshl_add_u64 v[218:219], v[182:183], 0, s[90:91]
	ds_read_b128 v[170:173], v136 offset:32768
	ds_read_b128 v[174:177], v136 offset:33792
	ds_read_b128 v[178:181], v136 offset:34816
	ds_read_b128 v[188:191], v136 offset:35840
	ds_read_b128 v[192:195], v136 offset:36864
	ds_read_b128 v[196:199], v136 offset:37888
	ds_read_b128 v[200:203], v136 offset:38912
	ds_read_b128 v[212:215], v136 offset:39936
	global_load_lds_dwordx4 v[218:219], off
	v_lshl_add_u64 v[218:219], v[182:183], 0, s[96:97]
	s_mov_b32 m0, s34
	s_nop 0
	global_load_lds_dwordx4 v[218:219], off
	s_waitcnt vmcnt(8)
	s_waitcnt lgkmcnt(0)
	s_barrier
	s_waitcnt lgkmcnt(0)
	v_mfma_f32_16x16x32_bf16 v[116:119], v[138:141], v[170:173], v[116:119]
	v_mfma_f32_16x16x32_bf16 v[112:115], v[146:149], v[170:173], v[112:115]
	v_mfma_f32_16x16x32_bf16 v[100:103], v[138:141], v[178:181], v[100:103]
	v_mfma_f32_16x16x32_bf16 v[96:99], v[146:149], v[178:181], v[96:99]
	v_mfma_f32_16x16x32_bf16 v[68:71], v[138:141], v[192:195], v[68:71]
	v_mfma_f32_16x16x32_bf16 v[64:67], v[146:149], v[192:195], v[64:67]
	v_mfma_f32_16x16x32_bf16 v[36:39], v[138:141], v[200:203], v[36:39]
	v_mfma_f32_16x16x32_bf16 v[32:35], v[146:149], v[200:203], v[32:35]
	v_mfma_f32_16x16x32_bf16 v[116:119], v[142:145], v[174:177], v[116:119]
	v_mfma_f32_16x16x32_bf16 v[112:115], v[150:153], v[174:177], v[112:115]
	v_mfma_f32_16x16x32_bf16 v[100:103], v[142:145], v[188:191], v[100:103]
	v_mfma_f32_16x16x32_bf16 v[96:99], v[150:153], v[188:191], v[96:99]
	v_mfma_f32_16x16x32_bf16 v[68:71], v[142:145], v[196:199], v[68:71]
	v_mfma_f32_16x16x32_bf16 v[64:67], v[150:153], v[196:199], v[64:67]
	v_mfma_f32_16x16x32_bf16 v[36:39], v[142:145], v[212:215], v[36:39]
	v_mfma_f32_16x16x32_bf16 v[32:35], v[150:153], v[212:215], v[32:35]
	v_mfma_f32_16x16x32_bf16 v[124:127], v[154:157], v[170:173], v[124:127]
	v_mfma_f32_16x16x32_bf16 v[120:123], v[162:165], v[170:173], v[120:123]
	v_mfma_f32_16x16x32_bf16 v[108:111], v[154:157], v[178:181], v[108:111]
	v_mfma_f32_16x16x32_bf16 v[104:107], v[162:165], v[178:181], v[104:107]
	v_mfma_f32_16x16x32_bf16 v[76:79], v[154:157], v[192:195], v[76:79]
	v_mfma_f32_16x16x32_bf16 v[72:75], v[162:165], v[192:195], v[72:75]
	v_mfma_f32_16x16x32_bf16 v[44:47], v[154:157], v[200:203], v[44:47]
	v_mfma_f32_16x16x32_bf16 v[40:43], v[162:165], v[200:203], v[40:43]
	v_mfma_f32_16x16x32_bf16 v[124:127], v[158:161], v[174:177], v[124:127]
	v_mfma_f32_16x16x32_bf16 v[120:123], v[166:169], v[174:177], v[120:123]
	v_mfma_f32_16x16x32_bf16 v[108:111], v[158:161], v[188:191], v[108:111]
	v_mfma_f32_16x16x32_bf16 v[104:107], v[166:169], v[188:191], v[104:107]
	v_mfma_f32_16x16x32_bf16 v[76:79], v[158:161], v[196:199], v[76:79]
	v_mfma_f32_16x16x32_bf16 v[72:75], v[166:169], v[196:199], v[72:75]
	v_mfma_f32_16x16x32_bf16 v[44:47], v[158:161], v[212:215], v[44:47]
	v_mfma_f32_16x16x32_bf16 v[40:43], v[166:169], v[212:215], v[40:43]
	s_barrier
	s_mov_b32 m0, s59
	v_lshl_add_u64 v[218:219], v[216:217], 0, s[84:85]
	ds_read_b128 v[170:173], v136 offset:49152
	ds_read_b128 v[174:177], v136 offset:50176
	ds_read_b128 v[178:181], v136 offset:51200
	ds_read_b128 v[188:191], v136 offset:52224
	ds_read_b128 v[192:195], v136 offset:53248
	ds_read_b128 v[196:199], v136 offset:54272
	ds_read_b128 v[200:203], v136 offset:55296
	ds_read_b128 v[212:215], v136 offset:56320
	global_load_lds_dwordx4 v[218:219], off
	v_lshl_add_u64 v[218:219], v[216:217], 0, s[94:95]
	s_mov_b32 m0, s60
	s_nop 0
	global_load_lds_dwordx4 v[218:219], off
	v_lshl_add_u64 v[218:219], v[216:217], 0, s[80:81]
	s_mov_b32 m0, s61
	v_lshl_add_u64 v[216:217], v[216:217], 0, s[78:79]
	global_load_lds_dwordx4 v[218:219], off
	s_mov_b32 m0, s62
	s_nop 0
	global_load_lds_dwordx4 v[216:217], off
	v_lshl_add_u64 v[216:217], v[182:183], 0, s[84:85]
	s_mov_b32 m0, s45
	v_lshl_add_u64 v[182:183], v[182:183], 0, s[94:95]
	global_load_lds_dwordx4 v[216:217], off
	s_mov_b32 m0, s46
	s_nop 0
	global_load_lds_dwordx4 v[182:183], off
	s_waitcnt vmcnt(8)
	s_waitcnt lgkmcnt(0)
	s_barrier
	s_waitcnt lgkmcnt(0)
	v_mfma_f32_16x16x32_bf16 v[84:87], v[138:141], v[170:173], v[84:87]
	v_mfma_f32_16x16x32_bf16 v[80:83], v[146:149], v[170:173], v[80:83]
	v_mfma_f32_16x16x32_bf16 v[52:55], v[138:141], v[178:181], v[52:55]
	v_mfma_f32_16x16x32_bf16 v[48:51], v[146:149], v[178:181], v[48:51]
	v_mfma_f32_16x16x32_bf16 v[20:23], v[138:141], v[192:195], v[20:23]
	v_mfma_f32_16x16x32_bf16 v[16:19], v[146:149], v[192:195], v[16:19]
	v_mfma_f32_16x16x32_bf16 v[4:7], v[138:141], v[200:203], v[4:7]
	v_mfma_f32_16x16x32_bf16 v[0:3], v[146:149], v[200:203], v[0:3]
	v_mfma_f32_16x16x32_bf16 v[84:87], v[142:145], v[174:177], v[84:87]
	v_mfma_f32_16x16x32_bf16 v[80:83], v[150:153], v[174:177], v[80:83]
	v_mfma_f32_16x16x32_bf16 v[52:55], v[142:145], v[188:191], v[52:55]
	v_mfma_f32_16x16x32_bf16 v[48:51], v[150:153], v[188:191], v[48:51]
	v_mfma_f32_16x16x32_bf16 v[20:23], v[142:145], v[196:199], v[20:23]
	v_mfma_f32_16x16x32_bf16 v[16:19], v[150:153], v[196:199], v[16:19]
	v_mfma_f32_16x16x32_bf16 v[4:7], v[142:145], v[212:215], v[4:7]
	v_mfma_f32_16x16x32_bf16 v[0:3], v[150:153], v[212:215], v[0:3]
	v_mfma_f32_16x16x32_bf16 v[92:95], v[154:157], v[170:173], v[92:95]
	v_mfma_f32_16x16x32_bf16 v[88:91], v[162:165], v[170:173], v[88:91]
	v_mfma_f32_16x16x32_bf16 v[60:63], v[154:157], v[178:181], v[60:63]
	v_mfma_f32_16x16x32_bf16 v[56:59], v[162:165], v[178:181], v[56:59]
	v_mfma_f32_16x16x32_bf16 v[28:31], v[154:157], v[192:195], v[28:31]
	v_mfma_f32_16x16x32_bf16 v[24:27], v[162:165], v[192:195], v[24:27]
	v_mfma_f32_16x16x32_bf16 v[12:15], v[154:157], v[200:203], v[12:15]
	v_mfma_f32_16x16x32_bf16 v[8:11], v[162:165], v[200:203], v[8:11]
	v_mfma_f32_16x16x32_bf16 v[92:95], v[158:161], v[174:177], v[92:95]
	v_mfma_f32_16x16x32_bf16 v[88:91], v[166:169], v[174:177], v[88:91]
	v_mfma_f32_16x16x32_bf16 v[60:63], v[158:161], v[188:191], v[60:63]
	v_mfma_f32_16x16x32_bf16 v[56:59], v[166:169], v[188:191], v[56:59]
	v_mfma_f32_16x16x32_bf16 v[28:31], v[158:161], v[196:199], v[28:31]
	v_mfma_f32_16x16x32_bf16 v[24:27], v[166:169], v[196:199], v[24:27]
	v_mfma_f32_16x16x32_bf16 v[12:15], v[158:161], v[212:215], v[12:15]
	v_mfma_f32_16x16x32_bf16 v[8:11], v[166:169], v[212:215], v[8:11]
	s_barrier
	s_add_i32 s65, s65, 2
	s_add_u32 s18, s18, 0x100
	s_addc_u32 s19, s19, 0
	s_add_u32 s63, s63, 0x100
	s_addc_u32 s64, s64, 0
	s_cmp_gt_u32 s65, 29
	s_cbranch_scc0 .LBB0_394
	s_and_b64 vcc, exec, s[10:11]
	s_cbranch_vccz .LBB0_397
	s_barrier

; __device__ __forceinline__ int lane_id() { int l; asm volatile("v_mbcnt_lo_u32_b32 %0, -1, 0\n\tv_mbcnt_hi_u32_b32 %0, -1, %0" : "=v"(l)); return l; }
;     __device__ __forceinline__ bool next(int i, UnitG& u) const { if (!P.next(i, u)) return false; u.O = O + ((size_t)u.x0 * 256 * 2048 + (size_t)u.x1 * 256) * 2; u.ldo = 2048; u.kind = 0; return true; }
; template <class Epi, class Sched>
; __device__ __forceinline__ void gemm_phase(PG8_LAS unsigned char* lds, const Sched& S, const Epi& E, int tid_in) {
;     ...
;         int aoff, boff; { const int l3 = lane_id(), fr3 = l3 & 15, fq3 = l3 >> 4; aoff = lds_byte(wr * 64 + fr3, fq3 * 8); boff = lds_byte(wc * 32 + fr3, fq3 * 8); }
;         const bool has_next = S.next(ui + 1, nxt);
;         const char* nA = has_next ? nxt.A : cA; const char* nB = has_next ? nxt.B : cB;
;         const int nlda = has_next ? nxt.lda : cur.lda, nldb = has_next ? nxt.ldb : cur.ldb;
;         unsigned nvA, nvB; { int r2, c2; stage_rc((wid * 64 + lane_id()) * 16, r2, c2); const int rb2 = Epi::PERM ? ((r2 & ~31) + perm32(r2 & 31)) : r2;
;             nvA = (unsigned)(r2 * nlda + c2) * 2u; nvB = (unsigned)(rb2 * nldb + c2) * 2u; }
;         const unsigned nqA = (unsigned)nlda * 128u, nqB = (unsigned)nldb * 128u;
;         const int nt = cur.K / BK;
.LBB0_541:
	v_and_b32_e32 v1, 15, v0
	v_or_b32_e32 v2, s56, v1
	v_ashrrev_i32_e32 v3, 6, v0
	v_lshlrev_b32_e32 v4, 6, v2
	v_and_b32_e32 v5, 48, v0
	s_movk_i32 s22, 0x3c0
	v_lshlrev_b32_e32 v2, 2, v2
	v_and_or_b32 v4, v4, s22, v5
	v_lshl_add_u32 v6, v3, 10, s57
	v_and_b32_e32 v2, 32, v2
	v_lshlrev_b32_e32 v0, 2, v0
	s_waitcnt vmcnt(0)
	v_bitop3_b32 v32, v4, v6, v2 bitop3:0xde
	v_lshl_or_b32 v1, v1, 6, v5
	v_add_lshl_u32 v2, v3, s59, 10
	v_and_b32_e32 v0, 32, v0
	v_bitop3_b32 v186, v1, v2, v0 bitop3:0xde
	v_mbcnt_lo_u32_b32 v0, -1, 0
	v_mbcnt_hi_u32_b32 v0, -1, v0
	s_mov_b32 s22, 0x1ffffe0
	v_add_u32_e32 v0, s60, v0
	v_ashrrev_i32_e32 v2, 31, v0
	v_lshrrev_b32_e32 v2, 26, v2
	v_lshlrev_b32_e32 v1, 4, v0
	v_add_u32_e32 v2, v0, v2
	v_bfe_i32 v0, v0, 27, 1
	v_lshrrev_b32_e32 v0, 22, v0
	v_add_u32_e32 v0, v1, v0
	v_and_b32_e32 v0, 0xfffffc00, v0
	v_sub_u32_e32 v0, v1, v0
	v_lshrrev_b32_e32 v1, 4, v0
	v_bitop3_b32 v0, v1, v0, 32 bitop3:0x6c
	v_ashrrev_i32_e32 v3, 31, v0
	v_lshrrev_b32_e32 v3, 26, v3
	v_ashrrev_i32_e32 v2, 6, v2
	v_add_u32_e32 v3, v0, v3
	v_lshlrev_b32_e32 v1, 3, v2
	v_ashrrev_i32_e32 v4, 6, v3
	v_and_b32_e32 v3, 0xc0, v3
	v_and_b32_e32 v1, -16, v1
	v_lshlrev_b32_e32 v2, 5, v2
	v_sub_u32_e32 v0, v0, v3
	v_add_u32_e32 v1, v4, v1
	v_and_b32_e32 v2, 32, v2
	v_ashrrev_i16_sdwa v0, v205, sext(v0) dst_sel:DWORD dst_unused:UNUSED_PAD src0_sel:DWORD src1_sel:BYTE_0
	v_add_u32_sdwa v68, v2, sext(v0) dst_sel:DWORD dst_unused:UNUSED_PAD src0_sel:DWORD src1_sel:WORD_0
	v_lshlrev_b32_e32 v0, 1, v1
	v_lshrrev_b32_e32 v2, 2, v1
	v_and_b32_e32 v3, 3, v4
	v_and_b32_e32 v0, 24, v0
	v_and_b32_e32 v2, 4, v2
	v_and_or_b32 v3, v1, s22, v3
	v_or3_b32 v0, v3, v2, v0
	s_movk_i32 s22, 0x180
	v_mul_lo_u32 v69, v1, s22
	v_mul_lo_u32 v0, v0, s22
	s_add_i32 s22, 0, 0x10000
	s_add_i32 s23, 0, 0x14000
	v_add_u32_e32 v12, s22, v186
	v_add_u32_e32 v28, s23, v186
	v_add_lshl_u32 v128, v0, v68, 1
	ds_read_b128 v[0:3], v12
	ds_read_b128 v[4:7], v12 offset:1024
	ds_read_b128 v[8:11], v12 offset:2048
	ds_read_b128 v[12:15], v12 offset:3072
	ds_read_b128 v[16:19], v28
	ds_read_b128 v[20:23], v28 offset:1024
	ds_read_b128 v[24:27], v28 offset:2048
	ds_read_b128 v[28:31], v28 offset:3072
	v_lshl_add_u64 v[64:65], s[20:21], 0, v[184:185]
	s_mov_b64 s[66:67], 0x18080
	v_add_u32_e32 v187, 0, v32
	v_lshl_add_u64 v[66:67], v[64:65], 0, s[66:67]
	s_add_i32 m0, s49, 0xc000
	s_mov_b64 s[70:71], 0x24080
	ds_read_b128 v[32:35], v187
	ds_read_b128 v[36:39], v187 offset:1024
	ds_read_b128 v[40:43], v187 offset:2048
	ds_read_b128 v[44:47], v187 offset:3072
	ds_read_b128 v[48:51], v187 offset:4096
	ds_read_b128 v[52:55], v187 offset:5120
	ds_read_b128 v[56:59], v187 offset:6144
	ds_read_b128 v[60:63], v187 offset:7168
	global_load_lds_dwordx4 v[66:67], off
	v_lshl_add_u64 v[64:65], v[64:65], 0, s[70:71]
	s_add_i32 m0, s49, 0xe000
	v_add_lshl_u32 v134, v68, v69, 1
	global_load_lds_dwordx4 v[64:65], off
	s_waitcnt vmcnt(24)
	s_waitcnt lgkmcnt(0)
	s_barrier
	s_waitcnt lgkmcnt(0)
	v_mfma_f32_16x16x32_bf16 v[88:91], v[0:3], v[56:59], 0
	v_mfma_f32_16x16x32_bf16 v[64:67], v[0:3], v[32:35], 0
	v_mfma_f32_16x16x32_bf16 v[68:71], v[8:11], v[32:35], 0
	v_mfma_f32_16x16x32_bf16 v[72:75], v[0:3], v[40:43], 0
	v_mfma_f32_16x16x32_bf16 v[76:79], v[8:11], v[40:43], 0
	v_mfma_f32_16x16x32_bf16 v[80:83], v[0:3], v[48:51], 0
	v_mfma_f32_16x16x32_bf16 v[84:87], v[8:11], v[48:51], 0
	v_mfma_f32_16x16x32_bf16 v[96:99], v[4:7], v[60:63], v[88:91]
	v_mfma_f32_16x16x32_bf16 v[88:91], v[8:11], v[56:59], 0
	v_mfma_f32_16x16x32_bf16 v[64:67], v[4:7], v[36:39], v[64:67]
	v_mfma_f32_16x16x32_bf16 v[68:71], v[12:15], v[36:39], v[68:71]
	v_mfma_f32_16x16x32_bf16 v[72:75], v[4:7], v[44:47], v[72:75]
	v_mfma_f32_16x16x32_bf16 v[76:79], v[12:15], v[44:47], v[76:79]
	v_mfma_f32_16x16x32_bf16 v[80:83], v[4:7], v[52:55], v[80:83]
	v_mfma_f32_16x16x32_bf16 v[84:87], v[12:15], v[52:55], v[84:87]
	v_mfma_f32_16x16x32_bf16 v[100:103], v[12:15], v[60:63], v[88:91]
	v_mfma_f32_16x16x32_bf16 v[88:91], v[16:19], v[32:35], 0
	v_mfma_f32_16x16x32_bf16 v[32:35], v[24:27], v[32:35], 0
	v_mfma_f32_16x16x32_bf16 v[112:115], v[20:23], v[36:39], v[88:91]
	v_mfma_f32_16x16x32_bf16 v[32:35], v[28:31], v[36:39], v[32:35]
	v_mfma_f32_16x16x32_bf16 v[36:39], v[16:19], v[40:43], 0
	v_mfma_f32_16x16x32_bf16 v[40:43], v[24:27], v[40:43], 0
	v_mfma_f32_16x16x32_bf16 v[36:39], v[20:23], v[44:47], v[36:39]
	v_mfma_f32_16x16x32_bf16 v[40:43], v[28:31], v[44:47], v[40:43]
	v_mfma_f32_16x16x32_bf16 v[44:47], v[16:19], v[48:51], 0
	v_mfma_f32_16x16x32_bf16 v[48:51], v[24:27], v[48:51], 0
	v_mfma_f32_16x16x32_bf16 v[44:47], v[20:23], v[52:55], v[44:47]
	v_mfma_f32_16x16x32_bf16 v[48:51], v[28:31], v[52:55], v[48:51]
	v_mfma_f32_16x16x32_bf16 v[52:55], v[16:19], v[56:59], 0
	v_mfma_f32_16x16x32_bf16 v[56:59], v[24:27], v[56:59], 0
	v_mfma_f32_16x16x32_bf16 v[52:55], v[20:23], v[60:63], v[52:55]
	v_mfma_f32_16x16x32_bf16 v[56:59], v[28:31], v[60:63], v[56:59]
	s_barrier
	v_mov_b32_e32 v129, v185
	s_add_i32 s20, s22, s47
	v_lshl_add_u64 v[240:241], s[8:9], 0, v[128:129]
	s_mov_b32 m0, s20
	s_mov_b64 s[24:25], 0xc000
	ds_read_b128 v[60:63], v187 offset:16384
	ds_read_b128 v[88:91], v187 offset:17408
	ds_read_b128 v[92:95], v187 offset:18432
	ds_read_b128 v[104:107], v187 offset:19456
	ds_read_b128 v[108:111], v187 offset:20480
	ds_read_b128 v[116:119], v187 offset:21504
	ds_read_b128 v[120:123], v187 offset:22528
	ds_read_b128 v[124:127], v187 offset:23552
	global_load_lds_dwordx4 v128, s[8:9]
	v_lshl_add_u64 v[128:129], v[240:241], 0, s[24:25]
	s_add_i32 m0, s20, 0x2000
	s_mov_b64 s[64:65], 0x18000
	s_add_i32 s20, s23, s47
	global_load_lds_dwordx4 v[128:129], off
	v_lshl_add_u64 v[128:129], v[240:241], 0, s[64:65]
	s_mov_b32 m0, s20
	s_mov_b64 s[22:23], 0x24000
	global_load_lds_dwordx4 v[128:129], off
	v_lshl_add_u64 v[128:129], v[240:241], 0, s[22:23]
	s_add_i32 m0, s20, 0x2000
	v_mov_b32_e32 v135, v185
	global_load_lds_dwordx4 v[128:129], off
	v_lshl_add_u64 v[242:243], s[16:17], 0, v[134:135]
	s_mov_b32 m0, s49
	v_lshl_add_u64 v[128:129], v[242:243], 0, s[24:25]
	global_load_lds_dwordx4 v134, s[16:17]
	s_mov_b32 m0, s51
	s_nop 0
	global_load_lds_dwordx4 v[128:129], off
	s_waitcnt vmcnt(24)
	s_waitcnt lgkmcnt(0)
	s_barrier
	s_waitcnt lgkmcnt(0)
	v_mfma_f32_16x16x32_bf16 v[128:131], v[0:3], v[60:63], 0
	v_mfma_f32_16x16x32_bf16 v[140:143], v[0:3], v[92:95], 0
	v_mfma_f32_16x16x32_bf16 v[148:151], v[0:3], v[108:111], 0
	v_mfma_f32_16x16x32_bf16 v[0:3], v[0:3], v[120:123], 0
	v_mfma_f32_16x16x32_bf16 v[128:131], v[4:7], v[88:91], v[128:131]
	v_mfma_f32_16x16x32_bf16 v[140:143], v[4:7], v[104:107], v[140:143]
	v_mfma_f32_16x16x32_bf16 v[148:151], v[4:7], v[116:119], v[148:151]
	v_mfma_f32_16x16x32_bf16 v[0:3], v[4:7], v[124:127], v[0:3]
	v_mfma_f32_16x16x32_bf16 v[4:7], v[8:11], v[120:123], 0
	v_mfma_f32_16x16x32_bf16 v[136:139], v[8:11], v[60:63], 0
	v_mfma_f32_16x16x32_bf16 v[144:147], v[8:11], v[92:95], 0
	v_mfma_f32_16x16x32_bf16 v[152:155], v[8:11], v[108:111], 0
	v_mfma_f32_16x16x32_bf16 v[4:7], v[12:15], v[124:127], v[4:7]
	v_mfma_f32_16x16x32_bf16 v[136:139], v[12:15], v[88:91], v[136:139]
	v_mfma_f32_16x16x32_bf16 v[144:147], v[12:15], v[104:107], v[144:147]
	v_mfma_f32_16x16x32_bf16 v[152:155], v[12:15], v[116:119], v[152:155]
	v_mfma_f32_16x16x32_bf16 v[8:11], v[16:19], v[60:63], 0
	v_mfma_f32_16x16x32_bf16 v[156:159], v[20:23], v[88:91], v[8:11]
	v_mfma_f32_16x16x32_bf16 v[8:11], v[24:27], v[60:63], 0
	v_mfma_f32_16x16x32_bf16 v[160:163], v[28:31], v[88:91], v[8:11]
	v_mfma_f32_16x16x32_bf16 v[8:11], v[16:19], v[92:95], 0
	v_mfma_f32_16x16x32_bf16 v[164:167], v[20:23], v[104:107], v[8:11]
	v_mfma_f32_16x16x32_bf16 v[8:11], v[24:27], v[92:95], 0
	v_mfma_f32_16x16x32_bf16 v[168:171], v[28:31], v[104:107], v[8:11]
	v_mfma_f32_16x16x32_bf16 v[8:11], v[16:19], v[108:111], 0
	v_mfma_f32_16x16x32_bf16 v[172:175], v[20:23], v[116:119], v[8:11]
	v_mfma_f32_16x16x32_bf16 v[8:11], v[24:27], v[108:111], 0
	v_mfma_f32_16x16x32_bf16 v[176:179], v[28:31], v[116:119], v[8:11]
	v_mfma_f32_16x16x32_bf16 v[8:11], v[16:19], v[120:123], 0
	v_mfma_f32_16x16x32_bf16 v[180:183], v[20:23], v[124:127], v[8:11]
	v_mfma_f32_16x16x32_bf16 v[8:11], v[24:27], v[120:123], 0
	v_mfma_f32_16x16x32_bf16 v[188:191], v[28:31], v[124:127], v[8:11]
	s_barrier
	s_add_i32 s20, 0, 0x18000
	s_add_i32 s21, 0, 0x1c000
	v_add_u32_e32 v20, s20, v186
	v_add_u32_e32 v24, s21, v186
	s_nop 0
	ds_read_b128 v[8:11], v20
	ds_read_b128 v[12:15], v20 offset:1024
	ds_read_b128 v[16:19], v20 offset:2048
	ds_read_b128 v[20:23], v20 offset:3072
	ds_read_b128 v[192:195], v24
	ds_read_b128 v[196:199], v24 offset:1024
	ds_read_b128 v[200:203], v24 offset:2048
	ds_read_b128 v[212:215], v24 offset:3072
	s_mov_b32 m0, s52
	v_lshl_add_u64 v[88:89], v[242:243], 0, s[64:65]
	ds_read_b128 v[24:27], v187 offset:32768
	ds_read_b128 v[28:31], v187 offset:33792
	ds_read_b128 v[60:63], v187 offset:34816
	ds_read_b128 v[216:219], v187 offset:35840
	ds_read_b128 v[220:223], v187 offset:36864
	ds_read_b128 v[224:227], v187 offset:37888
	ds_read_b128 v[228:231], v187 offset:38912
	ds_read_b128 v[232:235], v187 offset:39936
	global_load_lds_dwordx4 v[88:89], off
	v_lshl_add_u64 v[88:89], v[242:243], 0, s[22:23]
	s_mov_b32 m0, s53
	s_nop 0
	global_load_lds_dwordx4 v[88:89], off
	s_waitcnt vmcnt(8)
	s_waitcnt lgkmcnt(0)
	s_barrier
	s_waitcnt lgkmcnt(0)
	v_mfma_f32_16x16x32_bf16 v[64:67], v[8:11], v[24:27], v[64:67]
	v_mfma_f32_16x16x32_bf16 v[124:127], v[12:15], v[28:31], v[64:67]
	v_mfma_f32_16x16x32_bf16 v[64:67], v[16:19], v[24:27], v[68:71]
	v_mfma_f32_16x16x32_bf16 v[120:123], v[20:23], v[28:31], v[64:67]
	v_mfma_f32_16x16x32_bf16 v[64:67], v[8:11], v[60:63], v[72:75]
	v_mfma_f32_16x16x32_bf16 v[108:111], v[12:15], v[216:219], v[64:67]
	v_mfma_f32_16x16x32_bf16 v[64:67], v[16:19], v[60:63], v[76:79]
	v_mfma_f32_16x16x32_bf16 v[104:107], v[20:23], v[216:219], v[64:67]
	v_mfma_f32_16x16x32_bf16 v[64:67], v[8:11], v[220:223], v[80:83]
	v_mfma_f32_16x16x32_bf16 v[92:95], v[12:15], v[224:227], v[64:67]
	v_mfma_f32_16x16x32_bf16 v[64:67], v[16:19], v[220:223], v[84:87]
	v_mfma_f32_16x16x32_bf16 v[88:91], v[20:23], v[224:227], v[64:67]
	v_mfma_f32_16x16x32_bf16 v[64:67], v[8:11], v[228:231], v[96:99]
	v_mfma_f32_16x16x32_bf16 v[76:79], v[12:15], v[232:235], v[64:67]
	v_mfma_f32_16x16x32_bf16 v[64:67], v[16:19], v[228:231], v[100:103]
	v_mfma_f32_16x16x32_bf16 v[72:75], v[20:23], v[232:235], v[64:67]
	v_mfma_f32_16x16x32_bf16 v[64:67], v[192:195], v[24:27], v[112:115]
	v_mfma_f32_16x16x32_bf16 v[24:27], v[200:203], v[24:27], v[32:35]
	v_mfma_f32_16x16x32_bf16 v[112:115], v[212:215], v[28:31], v[24:27]
	v_mfma_f32_16x16x32_bf16 v[24:27], v[192:195], v[60:63], v[36:39]
	v_mfma_f32_16x16x32_bf16 v[100:103], v[196:199], v[216:219], v[24:27]
	v_mfma_f32_16x16x32_bf16 v[24:27], v[200:203], v[60:63], v[40:43]
	v_mfma_f32_16x16x32_bf16 v[96:99], v[212:215], v[216:219], v[24:27]
	v_mfma_f32_16x16x32_bf16 v[24:27], v[192:195], v[220:223], v[44:47]
	v_mfma_f32_16x16x32_bf16 v[84:87], v[196:199], v[224:227], v[24:27]
	v_mfma_f32_16x16x32_bf16 v[24:27], v[200:203], v[220:223], v[48:51]
	v_mfma_f32_16x16x32_bf16 v[80:83], v[212:215], v[224:227], v[24:27]
	v_mfma_f32_16x16x32_bf16 v[24:27], v[192:195], v[228:231], v[52:55]
	v_mfma_f32_16x16x32_bf16 v[68:71], v[196:199], v[232:235], v[24:27]
	v_mfma_f32_16x16x32_bf16 v[24:27], v[200:203], v[228:231], v[56:59]
	v_mfma_f32_16x16x32_bf16 v[116:119], v[196:199], v[28:31], v[64:67]
	v_mfma_f32_16x16x32_bf16 v[64:67], v[212:215], v[232:235], v[24:27]
	s_barrier
; #define PG8_WAIT_V(n) asm volatile("s_waitcnt vmcnt(" #n ")" ::: "memory")
; #define PG8_WAIT_VP() asm volatile("s_waitcnt vmcnt(%0)" :: "n"(8 + Epi::NST) : "memory")
; #define PG8_BAR __builtin_amdgcn_s_barrier()
; template <class Epi, class Sched>
; __device__ __forceinline__ void gemm_phase(PG8_LAS unsigned char* lds, const Sched& S, const Epi& E, int tid_in) {
;     ...
;         { const int t = 0; PG8_KITER(PG8_WAIT_VP()); }
;         for (int t = 2; t < nt; t += 2) PG8_KITER(PG8_WAIT_V(8));
;     ...
;         if (wr == 0) PG8_BAR;
	s_add_i32 s20, s20, s47
	s_nop 2
	v_lshl_add_u64 v[24:25], v[240:241], 0, s[84:85]
	s_mov_b32 m0, s20
	s_mov_b64 s[22:23], 0xc080
	ds_read_b128 v[32:35], v187 offset:49152
	ds_read_b128 v[36:39], v187 offset:50176
	ds_read_b128 v[216:219], v187 offset:51200
	ds_read_b128 v[220:223], v187 offset:52224
	ds_read_b128 v[224:227], v187 offset:53248
	ds_read_b128 v[228:231], v187 offset:54272
	ds_read_b128 v[232:235], v187 offset:55296
	ds_read_b128 v[236:239], v187 offset:56320
	global_load_lds_dwordx4 v[24:25], off
	v_lshl_add_u64 v[24:25], v[240:241], 0, s[22:23]
	s_add_i32 m0, s20, 0x2000
	s_add_i32 s20, s21, s47
	global_load_lds_dwordx4 v[24:25], off
	v_lshl_add_u64 v[24:25], v[240:241], 0, s[66:67]
	s_mov_b32 m0, s20
	s_nop 0
	global_load_lds_dwordx4 v[24:25], off
	v_lshl_add_u64 v[24:25], v[240:241], 0, s[70:71]
	s_add_i32 m0, s20, 0x2000
	s_nop 0
	global_load_lds_dwordx4 v[24:25], off
	v_lshl_add_u64 v[24:25], v[242:243], 0, s[84:85]
	s_mov_b32 m0, s54
	s_nop 0
	global_load_lds_dwordx4 v[24:25], off
	v_lshl_add_u64 v[24:25], v[242:243], 0, s[22:23]
	s_mov_b32 m0, s55
	s_nop 0
	global_load_lds_dwordx4 v[24:25], off
	s_waitcnt vmcnt(8)
	s_waitcnt lgkmcnt(0)
	s_barrier
	s_waitcnt lgkmcnt(0)
	v_mfma_f32_16x16x32_bf16 v[24:27], v[8:11], v[32:35], v[128:131]
	v_mfma_f32_16x16x32_bf16 v[60:63], v[12:15], v[36:39], v[24:27]
	v_mfma_f32_16x16x32_bf16 v[24:27], v[16:19], v[32:35], v[136:139]
	v_mfma_f32_16x16x32_bf16 v[56:59], v[20:23], v[36:39], v[24:27]
	v_mfma_f32_16x16x32_bf16 v[24:27], v[8:11], v[216:219], v[140:143]
	v_mfma_f32_16x16x32_bf16 v[44:47], v[12:15], v[220:223], v[24:27]
	v_mfma_f32_16x16x32_bf16 v[24:27], v[16:19], v[216:219], v[144:147]
	v_mfma_f32_16x16x32_bf16 v[40:43], v[20:23], v[220:223], v[24:27]
	v_mfma_f32_16x16x32_bf16 v[24:27], v[8:11], v[224:227], v[148:151]
	v_mfma_f32_16x16x32_bf16 v[0:3], v[8:11], v[232:235], v[0:3]
	v_mfma_f32_16x16x32_bf16 v[28:31], v[12:15], v[228:231], v[24:27]
	v_mfma_f32_16x16x32_bf16 v[24:27], v[16:19], v[224:227], v[152:155]
	v_mfma_f32_16x16x32_bf16 v[12:15], v[12:15], v[236:239], v[0:3]
	v_mfma_f32_16x16x32_bf16 v[0:3], v[16:19], v[232:235], v[4:7]
	v_mfma_f32_16x16x32_bf16 v[24:27], v[20:23], v[228:231], v[24:27]
	v_mfma_f32_16x16x32_bf16 v[8:11], v[20:23], v[236:239], v[0:3]
	v_mfma_f32_16x16x32_bf16 v[0:3], v[192:195], v[32:35], v[156:159]
	v_mfma_f32_16x16x32_bf16 v[52:55], v[196:199], v[36:39], v[0:3]
	v_mfma_f32_16x16x32_bf16 v[0:3], v[200:203], v[32:35], v[160:163]
	v_mfma_f32_16x16x32_bf16 v[48:51], v[212:215], v[36:39], v[0:3]
	v_mfma_f32_16x16x32_bf16 v[0:3], v[192:195], v[216:219], v[164:167]
	v_mfma_f32_16x16x32_bf16 v[36:39], v[196:199], v[220:223], v[0:3]
	v_mfma_f32_16x16x32_bf16 v[0:3], v[200:203], v[216:219], v[168:171]
	v_mfma_f32_16x16x32_bf16 v[32:35], v[212:215], v[220:223], v[0:3]
	v_mfma_f32_16x16x32_bf16 v[0:3], v[192:195], v[224:227], v[172:175]
	v_mfma_f32_16x16x32_bf16 v[20:23], v[196:199], v[228:231], v[0:3]
	v_mfma_f32_16x16x32_bf16 v[0:3], v[200:203], v[224:227], v[176:179]
	v_mfma_f32_16x16x32_bf16 v[16:19], v[212:215], v[228:231], v[0:3]
	v_mfma_f32_16x16x32_bf16 v[0:3], v[192:195], v[232:235], v[180:183]
	v_mfma_f32_16x16x32_bf16 v[4:7], v[196:199], v[236:239], v[0:3]
	v_mfma_f32_16x16x32_bf16 v[0:3], v[200:203], v[232:235], v[188:191]
	v_mfma_f32_16x16x32_bf16 v[0:3], v[212:215], v[236:239], v[0:3]
	s_barrier
	s_andn2_b64 vcc, exec, s[14:15]
	s_cbranch_vccnz .LBB0_543
	s_barrier

; __device__ __forceinline__ int lane_id() { int l; asm volatile("v_mbcnt_lo_u32_b32 %0, -1, 0\n\tv_mbcnt_hi_u32_b32 %0, -1, %0" : "=v"(l)); return l; }
;     __device__ __forceinline__ bool next(int i, UnitG& u) const { if (!P.next(i, u)) return false; u.O = O + ((size_t)u.x0 * 256 * 2048 + (size_t)u.x1 * 256) * 2; u.ldo = 2048; u.kind = 0; return true; }
; template <class Epi, class Sched>
; __device__ __forceinline__ void gemm_phase(PG8_LAS unsigned char* lds, const Sched& S, const Epi& E, int tid_in) {
;     ...
;         int aoff, boff; { const int l3 = lane_id(), fr3 = l3 & 15, fq3 = l3 >> 4; aoff = lds_byte(wr * 64 + fr3, fq3 * 8); boff = lds_byte(wc * 32 + fr3, fq3 * 8); }
;         const bool has_next = S.next(ui + 1, nxt);
;         const char* nA = has_next ? nxt.A : cA; const char* nB = has_next ? nxt.B : cB;
;         const int nlda = has_next ? nxt.lda : cur.lda, nldb = has_next ? nxt.ldb : cur.ldb;
;         unsigned nvA, nvB; { int r2, c2; stage_rc((wid * 64 + lane_id()) * 16, r2, c2); const int rb2 = Epi::PERM ? ((r2 & ~31) + perm32(r2 & 31)) : r2;
;             nvA = (unsigned)(r2 * nlda + c2) * 2u; nvB = (unsigned)(rb2 * nldb + c2) * 2u; }
;         const unsigned nqA = (unsigned)nlda * 128u, nqB = (unsigned)nldb * 128u;
;         const int nt = cur.K / BK;
.LBB0_914:
	v_and_b32_e32 v1, 15, v0
	v_and_b32_e32 v2, 48, v0
	v_lshl_or_b32 v1, v1, 6, v2
	v_lshlrev_b32_e32 v2, 4, v0
	v_and_b32_e32 v2, 0xfffffc00, v2
	v_readlane_b32 s4, v255, 5
	v_lshlrev_b32_e32 v0, 2, v0
	v_and_b32_e32 v0, 32, v0
	v_add_u32_e32 v3, s4, v2
	v_readlane_b32 s4, v255, 7
	v_bitop3_b32 v32, v1, v3, v0 bitop3:0xde
	s_add_i32 s93, 0, 0x10000
	v_add_u32_e32 v2, s4, v2
	v_bitop3_b32 v129, v1, v2, v0 bitop3:0xde
	v_mbcnt_lo_u32_b32 v0, -1, 0
	v_mbcnt_hi_u32_b32 v0, -1, v0
	v_readlane_b32 s4, v255, 9
	s_add_i32 s10, 0, 0x14000
	v_add_u32_e32 v142, s93, v129
	v_add_u32_e32 v0, s4, v0
	v_ashrrev_i32_e32 v2, 31, v0
	v_lshrrev_b32_e32 v2, 26, v2
	v_lshlrev_b32_e32 v1, 4, v0
	v_add_u32_e32 v2, v0, v2
	v_bfe_i32 v0, v0, 27, 1
	v_lshrrev_b32_e32 v0, 22, v0
	v_add_u32_e32 v0, v1, v0
	v_and_b32_e32 v0, 0xfffffc00, v0
	v_sub_u32_e32 v0, v1, v0
	v_lshrrev_b32_e32 v1, 4, v0
	v_bitop3_b32 v0, v1, v0, 32 bitop3:0x6c
	v_ashrrev_i32_e32 v3, 31, v0
	v_lshrrev_b32_e32 v3, 26, v3
	v_ashrrev_i32_e32 v2, 6, v2
	v_add_u32_e32 v3, v0, v3
	v_lshlrev_b32_e32 v1, 3, v2
	v_ashrrev_i32_e32 v4, 6, v3
	v_and_b32_e32 v3, 0xc0, v3
	v_and_b32_e32 v1, -16, v1
	v_lshlrev_b32_e32 v2, 5, v2
	v_sub_u32_e32 v0, v0, v3
	v_add_u32_e32 v1, v4, v1
	v_and_b32_e32 v2, 32, v2
	v_ashrrev_i16_sdwa v0, v205, sext(v0) dst_sel:DWORD dst_unused:UNUSED_PAD src0_sel:DWORD src1_sel:BYTE_0
	v_add_u32_sdwa v16, v2, sext(v0) dst_sel:DWORD dst_unused:UNUSED_PAD src0_sel:DWORD src1_sel:WORD_0
	v_lshlrev_b32_e32 v0, 1, v1
	v_lshrrev_b32_e32 v2, 2, v1
	v_and_b32_e32 v3, 3, v4
	s_mov_b32 s4, 0x7fffffe0
	v_and_b32_e32 v0, 24, v0
	v_and_b32_e32 v2, 4, v2
	v_and_or_b32 v3, v1, s4, v3
	v_or3_b32 v0, v3, v2, v0
	v_mul_lo_u32 v17, v1, s46
	v_mul_lo_u32 v0, v0, s47
	v_add_u32_e32 v143, s10, v129
	v_add_lshl_u32 v128, v0, v16, 1
	ds_read_b128 v[0:3], v142
	ds_read_b128 v[4:7], v142 offset:1024
	ds_read_b128 v[8:11], v142 offset:2048
	ds_read_b128 v[12:15], v142 offset:3072
	v_add_lshl_u32 v130, v16, v17, 1
	ds_read_b128 v[16:19], v143
	ds_read_b128 v[20:23], v143 offset:1024
	ds_read_b128 v[24:27], v143 offset:2048
	ds_read_b128 v[28:31], v143 offset:3072
	s_lshl_b32 s22, s47, 7
	s_lshl_b32 s82, s30, 1
	s_lshl_b32 s24, s46, 7
	s_add_u32 s50, s26, s82
	s_addc_u32 s51, s27, 0
	v_lshl_add_u64 v[244:245], s[50:51], 0, v[184:185]
	s_add_i32 s7, s92, 0xc000
	s_mov_b32 s31, s83
	v_add_u32_e32 v144, 0, v32
	v_lshl_add_u64 v[64:65], v[244:245], 0, s[84:85]
	s_mov_b32 m0, s7
	v_lshl_add_u64 v[246:247], v[244:245], 0, s[30:31]
	s_add_i32 s75, s92, 0xe000
	ds_read_b128 v[32:35], v144
	ds_read_b128 v[36:39], v144 offset:1024
	ds_read_b128 v[40:43], v144 offset:2048
	ds_read_b128 v[44:47], v144 offset:3072
	ds_read_b128 v[48:51], v144 offset:4096
	ds_read_b128 v[52:55], v144 offset:5120
	ds_read_b128 v[56:59], v144 offset:6144
	ds_read_b128 v[60:63], v144 offset:7168
	global_load_lds_dwordx4 v[64:65], off
	v_lshl_add_u64 v[64:65], v[246:247], 0, s[84:85]
	s_mov_b32 m0, s75
	s_nop 0
	global_load_lds_dwordx4 v[64:65], off
	s_waitcnt vmcnt(24)
	s_waitcnt lgkmcnt(0)
	s_barrier
	s_waitcnt lgkmcnt(0)
	v_mfma_f32_16x16x32_bf16 v[88:91], v[0:3], v[56:59], 0
	v_mfma_f32_16x16x32_bf16 v[64:67], v[0:3], v[32:35], 0
	v_mfma_f32_16x16x32_bf16 v[68:71], v[8:11], v[32:35], 0
	v_mfma_f32_16x16x32_bf16 v[72:75], v[0:3], v[40:43], 0
	v_mfma_f32_16x16x32_bf16 v[76:79], v[8:11], v[40:43], 0
	v_mfma_f32_16x16x32_bf16 v[80:83], v[0:3], v[48:51], 0
	v_mfma_f32_16x16x32_bf16 v[84:87], v[8:11], v[48:51], 0
	v_mfma_f32_16x16x32_bf16 v[96:99], v[4:7], v[60:63], v[88:91]
	v_mfma_f32_16x16x32_bf16 v[88:91], v[8:11], v[56:59], 0
	v_mfma_f32_16x16x32_bf16 v[64:67], v[4:7], v[36:39], v[64:67]
	v_mfma_f32_16x16x32_bf16 v[68:71], v[12:15], v[36:39], v[68:71]
	v_mfma_f32_16x16x32_bf16 v[72:75], v[4:7], v[44:47], v[72:75]
	v_mfma_f32_16x16x32_bf16 v[76:79], v[12:15], v[44:47], v[76:79]
	v_mfma_f32_16x16x32_bf16 v[80:83], v[4:7], v[52:55], v[80:83]
	v_mfma_f32_16x16x32_bf16 v[84:87], v[12:15], v[52:55], v[84:87]
	v_mfma_f32_16x16x32_bf16 v[100:103], v[12:15], v[60:63], v[88:91]
	v_mfma_f32_16x16x32_bf16 v[88:91], v[16:19], v[32:35], 0
	v_mfma_f32_16x16x32_bf16 v[32:35], v[24:27], v[32:35], 0
	v_mfma_f32_16x16x32_bf16 v[112:115], v[20:23], v[36:39], v[88:91]
	v_mfma_f32_16x16x32_bf16 v[32:35], v[28:31], v[36:39], v[32:35]
	v_mfma_f32_16x16x32_bf16 v[36:39], v[16:19], v[40:43], 0
	v_mfma_f32_16x16x32_bf16 v[40:43], v[24:27], v[40:43], 0
	v_mfma_f32_16x16x32_bf16 v[36:39], v[20:23], v[44:47], v[36:39]
	v_mfma_f32_16x16x32_bf16 v[40:43], v[28:31], v[44:47], v[40:43]
	v_mfma_f32_16x16x32_bf16 v[44:47], v[16:19], v[48:51], 0
	v_mfma_f32_16x16x32_bf16 v[48:51], v[24:27], v[48:51], 0
	v_mfma_f32_16x16x32_bf16 v[44:47], v[20:23], v[52:55], v[44:47]
	v_mfma_f32_16x16x32_bf16 v[48:51], v[28:31], v[52:55], v[48:51]
	v_mfma_f32_16x16x32_bf16 v[52:55], v[16:19], v[56:59], 0
	v_mfma_f32_16x16x32_bf16 v[56:59], v[24:27], v[56:59], 0
	v_mfma_f32_16x16x32_bf16 v[52:55], v[20:23], v[60:63], v[52:55]
	v_mfma_f32_16x16x32_bf16 v[56:59], v[28:31], v[60:63], v[56:59]
	s_barrier
	s_add_i32 s93, s93, s74
	v_mov_b32_e32 v133, v185
	s_add_i32 s71, s93, 0x2000
	s_lshl_b32 s44, s28, 1
	v_lshl_add_u64 v[248:249], s[34:35], 0, v[132:133]
	s_mov_b64 s[12:13], 0x100
	s_mov_b32 s29, s83
	s_add_u32 s4, s34, s44
	v_lshl_add_u64 v[134:135], v[248:249], 0, s[12:13]
	s_mov_b32 m0, s93
	v_lshl_add_u64 v[250:251], v[248:249], 0, s[28:29]
	s_addc_u32 s5, s35, 0
	ds_read_b128 v[60:63], v144 offset:16384
	ds_read_b128 v[88:91], v144 offset:17408
	ds_read_b128 v[92:95], v144 offset:18432
	ds_read_b128 v[104:107], v144 offset:19456
	ds_read_b128 v[108:111], v144 offset:20480
	ds_read_b128 v[116:119], v144 offset:21504
	ds_read_b128 v[120:123], v144 offset:22528
	ds_read_b128 v[124:127], v144 offset:23552
	global_load_lds_dwordx4 v[134:135], off
	v_lshl_add_u64 v[134:135], v[250:251], 0, s[12:13]
	s_mov_b32 m0, s71
	v_lshl_add_u64 v[252:253], s[4:5], 0, v[132:133]
	s_add_i32 s10, s10, s74
	global_load_lds_dwordx4 v[134:135], off
	v_lshl_add_u64 v[134:135], v[252:253], 0, s[12:13]
	s_mov_b32 m0, s10
	v_lshl_add_u64 v[210:211], v[252:253], 0, s[28:29]
	s_add_i32 s11, s10, 0x2000
	global_load_lds_dwordx4 v[134:135], off
	v_lshl_add_u64 v[134:135], v[210:211], 0, s[12:13]
	s_mov_b32 m0, s11
	v_lshl_add_u64 v[206:207], s[26:27], 0, v[184:185]
	global_load_lds_dwordx4 v[134:135], off
	v_lshl_add_u64 v[134:135], v[206:207], 0, s[12:13]
	s_mov_b32 m0, s92
	v_lshl_add_u64 v[186:187], v[206:207], 0, s[30:31]
	global_load_lds_dwordx4 v[134:135], off
	v_lshl_add_u64 v[134:135], v[186:187], 0, s[12:13]
	s_mov_b32 m0, s76
	s_mov_b32 s45, s83
	global_load_lds_dwordx4 v[134:135], off
	s_waitcnt vmcnt(24)
	s_waitcnt lgkmcnt(0)
	s_barrier
	s_waitcnt lgkmcnt(0)
	v_mfma_f32_16x16x32_bf16 v[134:137], v[0:3], v[60:63], 0
	v_mfma_f32_16x16x32_bf16 v[146:149], v[0:3], v[92:95], 0
	v_mfma_f32_16x16x32_bf16 v[156:159], v[0:3], v[108:111], 0
	v_mfma_f32_16x16x32_bf16 v[0:3], v[0:3], v[120:123], 0
	v_mfma_f32_16x16x32_bf16 v[134:137], v[4:7], v[88:91], v[134:137]
	v_mfma_f32_16x16x32_bf16 v[148:151], v[4:7], v[104:107], v[146:149]
	v_mfma_f32_16x16x32_bf16 v[156:159], v[4:7], v[116:119], v[156:159]
	v_mfma_f32_16x16x32_bf16 v[0:3], v[4:7], v[124:127], v[0:3]
	v_mfma_f32_16x16x32_bf16 v[4:7], v[8:11], v[120:123], 0
	v_mfma_f32_16x16x32_bf16 v[138:141], v[8:11], v[60:63], 0
	v_mfma_f32_16x16x32_bf16 v[152:155], v[8:11], v[92:95], 0
	v_mfma_f32_16x16x32_bf16 v[160:163], v[8:11], v[108:111], 0
	v_mfma_f32_16x16x32_bf16 v[4:7], v[12:15], v[124:127], v[4:7]
	v_mfma_f32_16x16x32_bf16 v[138:141], v[12:15], v[88:91], v[138:141]
	v_mfma_f32_16x16x32_bf16 v[152:155], v[12:15], v[104:107], v[152:155]
	v_mfma_f32_16x16x32_bf16 v[160:163], v[12:15], v[116:119], v[160:163]
	v_mfma_f32_16x16x32_bf16 v[8:11], v[16:19], v[60:63], 0
	v_mfma_f32_16x16x32_bf16 v[164:167], v[20:23], v[88:91], v[8:11]
	v_mfma_f32_16x16x32_bf16 v[8:11], v[24:27], v[60:63], 0
	v_mfma_f32_16x16x32_bf16 v[168:171], v[28:31], v[88:91], v[8:11]
	v_mfma_f32_16x16x32_bf16 v[8:11], v[16:19], v[92:95], 0
	v_mfma_f32_16x16x32_bf16 v[172:175], v[20:23], v[104:107], v[8:11]
	v_mfma_f32_16x16x32_bf16 v[8:11], v[24:27], v[92:95], 0
	v_mfma_f32_16x16x32_bf16 v[176:179], v[28:31], v[104:107], v[8:11]
	v_mfma_f32_16x16x32_bf16 v[8:11], v[16:19], v[108:111], 0
	v_mfma_f32_16x16x32_bf16 v[180:183], v[20:23], v[116:119], v[8:11]
	v_mfma_f32_16x16x32_bf16 v[8:11], v[24:27], v[108:111], 0
	v_mfma_f32_16x16x32_bf16 v[188:191], v[28:31], v[116:119], v[8:11]
	v_mfma_f32_16x16x32_bf16 v[8:11], v[16:19], v[120:123], 0
	v_mfma_f32_16x16x32_bf16 v[192:195], v[20:23], v[124:127], v[8:11]
	v_mfma_f32_16x16x32_bf16 v[8:11], v[24:27], v[120:123], 0
	v_mfma_f32_16x16x32_bf16 v[196:199], v[28:31], v[124:127], v[8:11]
	s_barrier
	s_add_i32 s70, 0, 0x18000
	s_add_i32 s4, 0, 0x1c000
	v_add_u32_e32 v145, s70, v129
	v_add_u32_e32 v146, s4, v129
	s_nop 0
	ds_read_b128 v[8:11], v145
	ds_read_b128 v[12:15], v145 offset:1024
	ds_read_b128 v[16:19], v145 offset:2048
	ds_read_b128 v[20:23], v145 offset:3072
	ds_read_b128 v[200:203], v146
	ds_read_b128 v[212:215], v146 offset:1024
	ds_read_b128 v[216:219], v146 offset:2048
	ds_read_b128 v[220:223], v146 offset:3072
	s_mov_b32 m0, s77
	v_lshl_add_u64 v[88:89], v[244:245], 0, s[12:13]
	ds_read_b128 v[24:27], v144 offset:32768
	ds_read_b128 v[28:31], v144 offset:33792
	ds_read_b128 v[60:63], v144 offset:34816
	ds_read_b128 v[224:227], v144 offset:35840
	ds_read_b128 v[228:231], v144 offset:36864
	ds_read_b128 v[232:235], v144 offset:37888
	ds_read_b128 v[236:239], v144 offset:38912
	ds_read_b128 v[240:243], v144 offset:39936
	global_load_lds_dwordx4 v[88:89], off
	v_lshl_add_u64 v[88:89], v[246:247], 0, s[12:13]
	s_mov_b32 m0, s64
	s_nop 0
	global_load_lds_dwordx4 v[88:89], off
	s_waitcnt vmcnt(8)
	s_waitcnt lgkmcnt(0)
	s_barrier
; #define PG8_WAIT_V(n) asm volatile("s_waitcnt vmcnt(" #n ")" ::: "memory")
; #define PG8_WAIT_VP() asm volatile("s_waitcnt vmcnt(%0)" :: "n"(8 + Epi::NST) : "memory")
; template <class Epi, class Sched>
; __device__ __forceinline__ void gemm_phase(PG8_LAS unsigned char* lds, const Sched& S, const Epi& E, int tid_in) {
;     ...
;         { const int t = 0; PG8_KITER(PG8_WAIT_VP()); }
;         for (int t = 2; t < nt; t += 2) PG8_KITER(PG8_WAIT_V(8));
	s_waitcnt lgkmcnt(0)
	v_mfma_f32_16x16x32_bf16 v[64:67], v[8:11], v[24:27], v[64:67]
	v_mfma_f32_16x16x32_bf16 v[124:127], v[12:15], v[28:31], v[64:67]
	v_mfma_f32_16x16x32_bf16 v[64:67], v[16:19], v[24:27], v[68:71]
	v_mfma_f32_16x16x32_bf16 v[120:123], v[20:23], v[28:31], v[64:67]
	v_mfma_f32_16x16x32_bf16 v[64:67], v[8:11], v[60:63], v[72:75]
	v_mfma_f32_16x16x32_bf16 v[108:111], v[12:15], v[224:227], v[64:67]
	v_mfma_f32_16x16x32_bf16 v[64:67], v[16:19], v[60:63], v[76:79]
	v_mfma_f32_16x16x32_bf16 v[104:107], v[20:23], v[224:227], v[64:67]
	v_mfma_f32_16x16x32_bf16 v[64:67], v[8:11], v[228:231], v[80:83]
	v_mfma_f32_16x16x32_bf16 v[92:95], v[12:15], v[232:235], v[64:67]
	v_mfma_f32_16x16x32_bf16 v[64:67], v[16:19], v[228:231], v[84:87]
	v_mfma_f32_16x16x32_bf16 v[88:91], v[20:23], v[232:235], v[64:67]
	v_mfma_f32_16x16x32_bf16 v[64:67], v[8:11], v[236:239], v[96:99]
	v_mfma_f32_16x16x32_bf16 v[76:79], v[12:15], v[240:243], v[64:67]
	v_mfma_f32_16x16x32_bf16 v[64:67], v[16:19], v[236:239], v[100:103]
	v_mfma_f32_16x16x32_bf16 v[72:75], v[20:23], v[240:243], v[64:67]
	v_mfma_f32_16x16x32_bf16 v[64:67], v[200:203], v[24:27], v[112:115]
	v_mfma_f32_16x16x32_bf16 v[24:27], v[216:219], v[24:27], v[32:35]
	v_mfma_f32_16x16x32_bf16 v[112:115], v[220:223], v[28:31], v[24:27]
	v_mfma_f32_16x16x32_bf16 v[24:27], v[200:203], v[60:63], v[36:39]
	v_mfma_f32_16x16x32_bf16 v[100:103], v[212:215], v[224:227], v[24:27]
	v_mfma_f32_16x16x32_bf16 v[24:27], v[216:219], v[60:63], v[40:43]
	v_mfma_f32_16x16x32_bf16 v[96:99], v[220:223], v[224:227], v[24:27]
	v_mfma_f32_16x16x32_bf16 v[24:27], v[200:203], v[228:231], v[44:47]
	v_mfma_f32_16x16x32_bf16 v[84:87], v[212:215], v[232:235], v[24:27]
	v_mfma_f32_16x16x32_bf16 v[24:27], v[216:219], v[228:231], v[48:51]
	v_mfma_f32_16x16x32_bf16 v[80:83], v[220:223], v[232:235], v[24:27]
	v_mfma_f32_16x16x32_bf16 v[24:27], v[200:203], v[236:239], v[52:55]
	v_mfma_f32_16x16x32_bf16 v[68:71], v[212:215], v[240:243], v[24:27]
	v_mfma_f32_16x16x32_bf16 v[24:27], v[216:219], v[236:239], v[56:59]
	v_mfma_f32_16x16x32_bf16 v[116:119], v[212:215], v[28:31], v[64:67]
	v_mfma_f32_16x16x32_bf16 v[64:67], v[220:223], v[240:243], v[24:27]
	s_barrier
	s_mov_b64 s[12:13], 0x180
	s_add_i32 s70, s70, s74
	s_nop 1
	v_lshl_add_u64 v[24:25], v[248:249], 0, s[12:13]
	s_mov_b32 m0, s70
	s_add_i32 s15, s70, 0x2000
	ds_read_b128 v[32:35], v144 offset:49152
	ds_read_b128 v[36:39], v144 offset:50176
	ds_read_b128 v[224:227], v144 offset:51200
	ds_read_b128 v[228:231], v144 offset:52224
	ds_read_b128 v[232:235], v144 offset:53248
	ds_read_b128 v[236:239], v144 offset:54272
	ds_read_b128 v[240:243], v144 offset:55296
	ds_read_b128 v[244:247], v144 offset:56320
	global_load_lds_dwordx4 v[24:25], off
	v_lshl_add_u64 v[24:25], v[250:251], 0, s[12:13]
	s_mov_b32 m0, s15
	s_add_i32 s4, s4, s74
	global_load_lds_dwordx4 v[24:25], off
	v_lshl_add_u64 v[24:25], v[252:253], 0, s[12:13]
	s_mov_b32 m0, s4
	s_add_i32 s5, s4, 0x2000
	global_load_lds_dwordx4 v[24:25], off
	v_lshl_add_u64 v[24:25], v[210:211], 0, s[12:13]
	s_mov_b32 m0, s5
	v_mov_b32_e32 v252, 0x3a27c5ac
	global_load_lds_dwordx4 v[24:25], off
	v_lshl_add_u64 v[24:25], v[206:207], 0, s[12:13]
	s_mov_b32 m0, s67
	s_nop 0
	global_load_lds_dwordx4 v[24:25], off
	v_lshl_add_u64 v[24:25], v[186:187], 0, s[12:13]
	s_mov_b32 m0, s14
	s_nop 0
	global_load_lds_dwordx4 v[24:25], off
	s_waitcnt vmcnt(8)
	s_waitcnt lgkmcnt(0)
	s_barrier
	s_waitcnt lgkmcnt(0)
	v_mfma_f32_16x16x32_bf16 v[24:27], v[8:11], v[32:35], v[134:137]
	v_mfma_f32_16x16x32_bf16 v[60:63], v[12:15], v[36:39], v[24:27]
	v_mfma_f32_16x16x32_bf16 v[24:27], v[16:19], v[32:35], v[138:141]
	v_mfma_f32_16x16x32_bf16 v[56:59], v[20:23], v[36:39], v[24:27]
	v_mfma_f32_16x16x32_bf16 v[24:27], v[8:11], v[224:227], v[148:151]
	v_mfma_f32_16x16x32_bf16 v[44:47], v[12:15], v[228:231], v[24:27]
	v_mfma_f32_16x16x32_bf16 v[24:27], v[16:19], v[224:227], v[152:155]
	v_mfma_f32_16x16x32_bf16 v[40:43], v[20:23], v[228:231], v[24:27]
	v_mfma_f32_16x16x32_bf16 v[24:27], v[8:11], v[232:235], v[156:159]
	v_mfma_f32_16x16x32_bf16 v[0:3], v[8:11], v[240:243], v[0:3]
	v_mfma_f32_16x16x32_bf16 v[28:31], v[12:15], v[236:239], v[24:27]
	v_mfma_f32_16x16x32_bf16 v[24:27], v[16:19], v[232:235], v[160:163]
	v_mfma_f32_16x16x32_bf16 v[12:15], v[12:15], v[244:247], v[0:3]
	v_mfma_f32_16x16x32_bf16 v[0:3], v[16:19], v[240:243], v[4:7]
	v_mfma_f32_16x16x32_bf16 v[24:27], v[20:23], v[236:239], v[24:27]
	v_mfma_f32_16x16x32_bf16 v[8:11], v[20:23], v[244:247], v[0:3]
	v_mfma_f32_16x16x32_bf16 v[0:3], v[200:203], v[32:35], v[164:167]
	v_mfma_f32_16x16x32_bf16 v[52:55], v[212:215], v[36:39], v[0:3]
	v_mfma_f32_16x16x32_bf16 v[0:3], v[216:219], v[32:35], v[168:171]
	v_mfma_f32_16x16x32_bf16 v[48:51], v[220:223], v[36:39], v[0:3]
	v_mfma_f32_16x16x32_bf16 v[0:3], v[200:203], v[224:227], v[172:175]
	v_mfma_f32_16x16x32_bf16 v[36:39], v[212:215], v[228:231], v[0:3]
	v_mfma_f32_16x16x32_bf16 v[0:3], v[216:219], v[224:227], v[176:179]
	v_mfma_f32_16x16x32_bf16 v[32:35], v[220:223], v[228:231], v[0:3]
	v_mfma_f32_16x16x32_bf16 v[0:3], v[200:203], v[232:235], v[180:183]
	v_mfma_f32_16x16x32_bf16 v[20:23], v[212:215], v[236:239], v[0:3]
	v_mfma_f32_16x16x32_bf16 v[0:3], v[216:219], v[232:235], v[188:191]
	v_mfma_f32_16x16x32_bf16 v[16:19], v[220:223], v[236:239], v[0:3]
	v_mfma_f32_16x16x32_bf16 v[0:3], v[200:203], v[240:243], v[192:195]
	v_mfma_f32_16x16x32_bf16 v[4:7], v[212:215], v[244:247], v[0:3]
	v_mfma_f32_16x16x32_bf16 v[0:3], v[216:219], v[240:243], v[196:199]
	v_mfma_f32_16x16x32_bf16 v[0:3], v[220:223], v[244:247], v[0:3]
	s_barrier
	s_lshl_b32 s46, s46, 8
	s_lshl_b32 s48, s47, 8
	s_add_u32 s12, s34, 0x200
	s_addc_u32 s13, s35, 0
	s_add_u32 s34, s50, 0x180
	s_addc_u32 s35, s51, 0
	v_lshl_add_u64 v[134:135], s[34:35], 0, v[184:185]
	s_add_u32 s34, s34, s30
	s_addc_u32 s35, s35, 0
	v_mov_b32_e32 v129, v185
	s_mov_b32 s23, s83
	s_mov_b32 s49, s83
	v_mov_b32_e32 v131, v185
	s_mov_b32 s25, s83
	s_mov_b32 s47, s83
	v_lshl_add_u64 v[136:137], s[34:35], 0, v[184:185]
	s_mov_b32 s68, 0
	s_mov_b64 s[34:35], 0
	s_branch .LBB0_916
.LBB0_915:
	ds_read_b128 v[148:151], v142
	ds_read_b128 v[152:155], v142 offset:1024
	ds_read_b128 v[156:159], v142 offset:2048
	ds_read_b128 v[160:163], v142 offset:3072
	ds_read_b128 v[164:167], v143
	ds_read_b128 v[168:171], v143 offset:1024
	ds_read_b128 v[172:175], v143 offset:2048
	ds_read_b128 v[176:179], v143 offset:3072
	s_add_u32 vcc_lo, s26, s34
	s_addc_u32 vcc_hi, s27, s35
	s_add_u32 vcc_lo, vcc_lo, 0x200
	s_addc_u32 vcc_hi, vcc_hi, 0
	s_and_b64 s[54:55], exec, s[54:55]
	s_cselect_b32 s55, s17, vcc_hi
	s_cselect_b32 s54, s16, vcc_lo
	s_mov_b32 m0, s7
	v_lshl_add_u64 v[186:187], v[134:135], 0, s[34:35]
	ds_read_b128 v[180:183], v144
	ds_read_b128 v[188:191], v144 offset:1024
	ds_read_b128 v[192:195], v144 offset:2048
	ds_read_b128 v[196:199], v144 offset:3072
	ds_read_b128 v[200:203], v144 offset:4096
	ds_read_b128 v[212:215], v144 offset:5120
	ds_read_b128 v[216:219], v144 offset:6144
	ds_read_b128 v[220:223], v144 offset:7168
	global_load_lds_dwordx4 v[186:187], off
	v_lshl_add_u64 v[186:187], v[136:137], 0, s[34:35]
	s_mov_b32 m0, s75
	s_nop 0
	global_load_lds_dwordx4 v[186:187], off
	s_waitcnt vmcnt(8)
	s_waitcnt lgkmcnt(0)
	s_barrier
	s_waitcnt lgkmcnt(0)
	v_mfma_f32_16x16x32_bf16 v[124:127], v[148:151], v[180:183], v[124:127]
	v_mfma_f32_16x16x32_bf16 v[120:123], v[156:159], v[180:183], v[120:123]
	v_mfma_f32_16x16x32_bf16 v[108:111], v[148:151], v[192:195], v[108:111]
	v_mfma_f32_16x16x32_bf16 v[104:107], v[156:159], v[192:195], v[104:107]
	v_mfma_f32_16x16x32_bf16 v[92:95], v[148:151], v[200:203], v[92:95]
	v_mfma_f32_16x16x32_bf16 v[88:91], v[156:159], v[200:203], v[88:91]
	v_mfma_f32_16x16x32_bf16 v[76:79], v[148:151], v[216:219], v[76:79]
	v_mfma_f32_16x16x32_bf16 v[72:75], v[156:159], v[216:219], v[72:75]
	v_mfma_f32_16x16x32_bf16 v[124:127], v[152:155], v[188:191], v[124:127]
	v_mfma_f32_16x16x32_bf16 v[120:123], v[160:163], v[188:191], v[120:123]
	v_mfma_f32_16x16x32_bf16 v[108:111], v[152:155], v[196:199], v[108:111]
	v_mfma_f32_16x16x32_bf16 v[104:107], v[160:163], v[196:199], v[104:107]
	v_mfma_f32_16x16x32_bf16 v[92:95], v[152:155], v[212:215], v[92:95]
	v_mfma_f32_16x16x32_bf16 v[88:91], v[160:163], v[212:215], v[88:91]
	v_mfma_f32_16x16x32_bf16 v[76:79], v[152:155], v[220:223], v[76:79]
	v_mfma_f32_16x16x32_bf16 v[72:75], v[160:163], v[220:223], v[72:75]
	v_mfma_f32_16x16x32_bf16 v[116:119], v[164:167], v[180:183], v[116:119]
	v_mfma_f32_16x16x32_bf16 v[112:115], v[172:175], v[180:183], v[112:115]
	v_mfma_f32_16x16x32_bf16 v[100:103], v[164:167], v[192:195], v[100:103]
	v_mfma_f32_16x16x32_bf16 v[96:99], v[172:175], v[192:195], v[96:99]
	v_mfma_f32_16x16x32_bf16 v[84:87], v[164:167], v[200:203], v[84:87]
	v_mfma_f32_16x16x32_bf16 v[80:83], v[172:175], v[200:203], v[80:83]
	v_mfma_f32_16x16x32_bf16 v[68:71], v[164:167], v[216:219], v[68:71]
	v_mfma_f32_16x16x32_bf16 v[64:67], v[172:175], v[216:219], v[64:67]
	v_mfma_f32_16x16x32_bf16 v[116:119], v[168:171], v[188:191], v[116:119]
	v_mfma_f32_16x16x32_bf16 v[112:115], v[176:179], v[188:191], v[112:115]
	v_mfma_f32_16x16x32_bf16 v[100:103], v[168:171], v[196:199], v[100:103]
	v_mfma_f32_16x16x32_bf16 v[96:99], v[176:179], v[196:199], v[96:99]
	v_mfma_f32_16x16x32_bf16 v[84:87], v[168:171], v[212:215], v[84:87]
	v_mfma_f32_16x16x32_bf16 v[80:83], v[176:179], v[212:215], v[80:83]
	v_mfma_f32_16x16x32_bf16 v[68:71], v[168:171], v[220:223], v[68:71]
	v_mfma_f32_16x16x32_bf16 v[64:67], v[176:179], v[220:223], v[64:67]
	s_barrier
	s_mov_b32 m0, s93
	v_lshl_add_u64 v[186:187], s[58:59], 0, v[140:141]
	s_add_u32 s58, s58, s60
	ds_read_b128 v[180:183], v144 offset:16384
	ds_read_b128 v[188:191], v144 offset:17408
	ds_read_b128 v[192:195], v144 offset:18432
	ds_read_b128 v[196:199], v144 offset:19456
	ds_read_b128 v[200:203], v144 offset:20480
	ds_read_b128 v[212:215], v144 offset:21504
	ds_read_b128 v[216:219], v144 offset:22528
	ds_read_b128 v[220:223], v144 offset:23552
	global_load_lds_dwordx4 v[186:187], off
	v_lshl_add_u64 v[206:207], v[186:187], 0, s[56:57]
	s_mov_b32 m0, s71
	s_addc_u32 s59, s59, s61
	global_load_lds_dwordx4 v[206:207], off
	v_lshl_add_u64 v[210:211], s[58:59], 0, v[140:141]
	s_mov_b32 m0, s10
	v_lshl_add_u64 v[224:225], v[210:211], 0, s[56:57]
	global_load_lds_dwordx4 v[210:211], off
	s_mov_b32 m0, s11
	v_lshl_add_u64 v[226:227], s[54:55], 0, v[138:139]
	global_load_lds_dwordx4 v[224:225], off
	s_mov_b32 m0, s92
	v_lshl_add_u64 v[228:229], v[226:227], 0, s[50:51]
	global_load_lds_dwordx4 v[226:227], off
	s_mov_b32 m0, s76
	s_nop 0
	global_load_lds_dwordx4 v[228:229], off
	s_waitcnt vmcnt(8)
	s_waitcnt lgkmcnt(0)
	s_barrier
	s_waitcnt lgkmcnt(0)
	v_mfma_f32_16x16x32_bf16 v[60:63], v[148:151], v[180:183], v[60:63]
	v_mfma_f32_16x16x32_bf16 v[56:59], v[156:159], v[180:183], v[56:59]
	v_mfma_f32_16x16x32_bf16 v[44:47], v[148:151], v[192:195], v[44:47]
	v_mfma_f32_16x16x32_bf16 v[40:43], v[156:159], v[192:195], v[40:43]
	v_mfma_f32_16x16x32_bf16 v[28:31], v[148:151], v[200:203], v[28:31]
	v_mfma_f32_16x16x32_bf16 v[24:27], v[156:159], v[200:203], v[24:27]
	v_mfma_f32_16x16x32_bf16 v[12:15], v[148:151], v[216:219], v[12:15]
	v_mfma_f32_16x16x32_bf16 v[8:11], v[156:159], v[216:219], v[8:11]
	v_mfma_f32_16x16x32_bf16 v[60:63], v[152:155], v[188:191], v[60:63]
	v_mfma_f32_16x16x32_bf16 v[56:59], v[160:163], v[188:191], v[56:59]
	v_mfma_f32_16x16x32_bf16 v[44:47], v[152:155], v[196:199], v[44:47]
	v_mfma_f32_16x16x32_bf16 v[40:43], v[160:163], v[196:199], v[40:43]
	v_mfma_f32_16x16x32_bf16 v[28:31], v[152:155], v[212:215], v[28:31]
	v_mfma_f32_16x16x32_bf16 v[24:27], v[160:163], v[212:215], v[24:27]
	v_mfma_f32_16x16x32_bf16 v[12:15], v[152:155], v[220:223], v[12:15]
	v_mfma_f32_16x16x32_bf16 v[8:11], v[160:163], v[220:223], v[8:11]
	v_mfma_f32_16x16x32_bf16 v[52:55], v[164:167], v[180:183], v[52:55]
	v_mfma_f32_16x16x32_bf16 v[48:51], v[172:175], v[180:183], v[48:51]
	v_mfma_f32_16x16x32_bf16 v[36:39], v[164:167], v[192:195], v[36:39]
	v_mfma_f32_16x16x32_bf16 v[32:35], v[172:175], v[192:195], v[32:35]
	v_mfma_f32_16x16x32_bf16 v[20:23], v[164:167], v[200:203], v[20:23]
	v_mfma_f32_16x16x32_bf16 v[16:19], v[172:175], v[200:203], v[16:19]
	v_mfma_f32_16x16x32_bf16 v[4:7], v[164:167], v[216:219], v[4:7]
	v_mfma_f32_16x16x32_bf16 v[0:3], v[172:175], v[216:219], v[0:3]
	v_mfma_f32_16x16x32_bf16 v[52:55], v[168:171], v[188:191], v[52:55]
	v_mfma_f32_16x16x32_bf16 v[48:51], v[176:179], v[188:191], v[48:51]
	v_mfma_f32_16x16x32_bf16 v[36:39], v[168:171], v[196:199], v[36:39]
	v_mfma_f32_16x16x32_bf16 v[32:35], v[176:179], v[196:199], v[32:35]
	v_mfma_f32_16x16x32_bf16 v[20:23], v[168:171], v[212:215], v[20:23]
	v_mfma_f32_16x16x32_bf16 v[16:19], v[176:179], v[212:215], v[16:19]
	v_mfma_f32_16x16x32_bf16 v[4:7], v[168:171], v[220:223], v[4:7]
	v_mfma_f32_16x16x32_bf16 v[0:3], v[176:179], v[220:223], v[0:3]
	s_barrier
	ds_read_b128 v[148:151], v145
	ds_read_b128 v[152:155], v145 offset:1024
	ds_read_b128 v[156:159], v145 offset:2048
	ds_read_b128 v[160:163], v145 offset:3072
	ds_read_b128 v[164:167], v146
	ds_read_b128 v[168:171], v146 offset:1024
	ds_read_b128 v[172:175], v146 offset:2048
	ds_read_b128 v[176:179], v146 offset:3072
	s_add_u32 s52, s54, s52
	s_addc_u32 s53, s55, s53
	s_mov_b32 m0, s77
	v_lshl_add_u64 v[138:139], s[52:53], 0, v[138:139]
	ds_read_b128 v[180:183], v144 offset:32768
	ds_read_b128 v[188:191], v144 offset:33792
	ds_read_b128 v[192:195], v144 offset:34816
	ds_read_b128 v[196:199], v144 offset:35840
	ds_read_b128 v[200:203], v144 offset:36864
	ds_read_b128 v[212:215], v144 offset:37888
	ds_read_b128 v[216:219], v144 offset:38912
	ds_read_b128 v[220:223], v144 offset:39936
	global_load_lds_dwordx4 v[138:139], off
	v_lshl_add_u64 v[138:139], v[138:139], 0, s[50:51]
	s_mov_b32 m0, s64
	s_nop 0
	global_load_lds_dwordx4 v[138:139], off
	s_waitcnt vmcnt(8)
	s_waitcnt lgkmcnt(0)
	s_barrier
	s_waitcnt lgkmcnt(0)
	v_mfma_f32_16x16x32_bf16 v[124:127], v[148:151], v[180:183], v[124:127]
	v_mfma_f32_16x16x32_bf16 v[120:123], v[156:159], v[180:183], v[120:123]
	v_mfma_f32_16x16x32_bf16 v[108:111], v[148:151], v[192:195], v[108:111]
	v_mfma_f32_16x16x32_bf16 v[104:107], v[156:159], v[192:195], v[104:107]
	v_mfma_f32_16x16x32_bf16 v[92:95], v[148:151], v[200:203], v[92:95]
	v_mfma_f32_16x16x32_bf16 v[88:91], v[156:159], v[200:203], v[88:91]
	v_mfma_f32_16x16x32_bf16 v[76:79], v[148:151], v[216:219], v[76:79]
	v_mfma_f32_16x16x32_bf16 v[72:75], v[156:159], v[216:219], v[72:75]
	v_mfma_f32_16x16x32_bf16 v[124:127], v[152:155], v[188:191], v[124:127]
	v_mfma_f32_16x16x32_bf16 v[120:123], v[160:163], v[188:191], v[120:123]
	v_mfma_f32_16x16x32_bf16 v[108:111], v[152:155], v[196:199], v[108:111]
	v_mfma_f32_16x16x32_bf16 v[104:107], v[160:163], v[196:199], v[104:107]
	v_mfma_f32_16x16x32_bf16 v[92:95], v[152:155], v[212:215], v[92:95]
	v_mfma_f32_16x16x32_bf16 v[88:91], v[160:163], v[212:215], v[88:91]
	v_mfma_f32_16x16x32_bf16 v[76:79], v[152:155], v[220:223], v[76:79]
	v_mfma_f32_16x16x32_bf16 v[72:75], v[160:163], v[220:223], v[72:75]
	v_mfma_f32_16x16x32_bf16 v[116:119], v[164:167], v[180:183], v[116:119]
	v_mfma_f32_16x16x32_bf16 v[112:115], v[172:175], v[180:183], v[112:115]
	v_mfma_f32_16x16x32_bf16 v[100:103], v[164:167], v[192:195], v[100:103]
	v_mfma_f32_16x16x32_bf16 v[96:99], v[172:175], v[192:195], v[96:99]
	v_mfma_f32_16x16x32_bf16 v[84:87], v[164:167], v[200:203], v[84:87]
	v_mfma_f32_16x16x32_bf16 v[80:83], v[172:175], v[200:203], v[80:83]
	v_mfma_f32_16x16x32_bf16 v[68:71], v[164:167], v[216:219], v[68:71]
	v_mfma_f32_16x16x32_bf16 v[64:67], v[172:175], v[216:219], v[64:67]
	v_mfma_f32_16x16x32_bf16 v[116:119], v[168:171], v[188:191], v[116:119]
	v_mfma_f32_16x16x32_bf16 v[112:115], v[176:179], v[188:191], v[112:115]
	v_mfma_f32_16x16x32_bf16 v[100:103], v[168:171], v[196:199], v[100:103]
	v_mfma_f32_16x16x32_bf16 v[96:99], v[176:179], v[196:199], v[96:99]
	v_mfma_f32_16x16x32_bf16 v[84:87], v[168:171], v[212:215], v[84:87]
	v_mfma_f32_16x16x32_bf16 v[80:83], v[176:179], v[212:215], v[80:83]
	v_mfma_f32_16x16x32_bf16 v[68:71], v[168:171], v[220:223], v[68:71]
	v_mfma_f32_16x16x32_bf16 v[64:67], v[176:179], v[220:223], v[64:67]
	s_barrier
; #define PG8_WAIT_V(n) asm volatile("s_waitcnt vmcnt(" #n ")" ::: "memory")
; #define PG8_WAIT_VP() asm volatile("s_waitcnt vmcnt(%0)" :: "n"(8 + Epi::NST) : "memory")
; template <class Epi, class Sched>
; __device__ __forceinline__ void gemm_phase(PG8_LAS unsigned char* lds, const Sched& S, const Epi& E, int tid_in) {
;     ...
;         { const int t = 0; PG8_KITER(PG8_WAIT_VP()); }
;         for (int t = 2; t < nt; t += 2) PG8_KITER(PG8_WAIT_V(8));
	s_mov_b32 m0, s70
	v_lshl_add_u64 v[186:187], v[186:187], 0, s[84:85]
	ds_read_b128 v[138:141], v144 offset:49152
	ds_read_b128 v[180:183], v144 offset:50176
	ds_read_b128 v[188:191], v144 offset:51200
	ds_read_b128 v[192:195], v144 offset:52224
	ds_read_b128 v[196:199], v144 offset:53248
	ds_read_b128 v[200:203], v144 offset:54272
	ds_read_b128 v[212:215], v144 offset:55296
	ds_read_b128 v[216:219], v144 offset:56320
	global_load_lds_dwordx4 v[186:187], off
	v_lshl_add_u64 v[186:187], v[206:207], 0, s[84:85]
	s_mov_b32 m0, s15
	s_nop 0
	global_load_lds_dwordx4 v[186:187], off
	v_lshl_add_u64 v[186:187], v[210:211], 0, s[84:85]
	s_mov_b32 m0, s4
	s_nop 0
	global_load_lds_dwordx4 v[186:187], off
	v_lshl_add_u64 v[186:187], v[224:225], 0, s[84:85]
	s_mov_b32 m0, s5
	s_nop 0
	global_load_lds_dwordx4 v[186:187], off
	v_lshl_add_u64 v[186:187], v[226:227], 0, s[84:85]
	s_mov_b32 m0, s67
	s_nop 0
	global_load_lds_dwordx4 v[186:187], off
	v_lshl_add_u64 v[186:187], v[228:229], 0, s[84:85]
	s_mov_b32 m0, s14
	s_nop 0
	global_load_lds_dwordx4 v[186:187], off
	s_waitcnt vmcnt(8)
	s_waitcnt lgkmcnt(0)
	s_barrier
	s_waitcnt lgkmcnt(0)
	v_mfma_f32_16x16x32_bf16 v[60:63], v[148:151], v[138:141], v[60:63]
	v_mfma_f32_16x16x32_bf16 v[56:59], v[156:159], v[138:141], v[56:59]
	v_mfma_f32_16x16x32_bf16 v[44:47], v[148:151], v[188:191], v[44:47]
	v_mfma_f32_16x16x32_bf16 v[40:43], v[156:159], v[188:191], v[40:43]
	v_mfma_f32_16x16x32_bf16 v[28:31], v[148:151], v[196:199], v[28:31]
	v_mfma_f32_16x16x32_bf16 v[24:27], v[156:159], v[196:199], v[24:27]
	v_mfma_f32_16x16x32_bf16 v[12:15], v[148:151], v[212:215], v[12:15]
	v_mfma_f32_16x16x32_bf16 v[8:11], v[156:159], v[212:215], v[8:11]
	v_mfma_f32_16x16x32_bf16 v[60:63], v[152:155], v[180:183], v[60:63]
	v_mfma_f32_16x16x32_bf16 v[56:59], v[160:163], v[180:183], v[56:59]
	v_mfma_f32_16x16x32_bf16 v[44:47], v[152:155], v[192:195], v[44:47]
	v_mfma_f32_16x16x32_bf16 v[40:43], v[160:163], v[192:195], v[40:43]
	v_mfma_f32_16x16x32_bf16 v[28:31], v[152:155], v[200:203], v[28:31]
	v_mfma_f32_16x16x32_bf16 v[24:27], v[160:163], v[200:203], v[24:27]
	v_mfma_f32_16x16x32_bf16 v[12:15], v[152:155], v[216:219], v[12:15]
	v_mfma_f32_16x16x32_bf16 v[8:11], v[160:163], v[216:219], v[8:11]
	v_mfma_f32_16x16x32_bf16 v[52:55], v[164:167], v[138:141], v[52:55]
	v_mfma_f32_16x16x32_bf16 v[48:51], v[172:175], v[138:141], v[48:51]
	v_mfma_f32_16x16x32_bf16 v[36:39], v[164:167], v[188:191], v[36:39]
	v_mfma_f32_16x16x32_bf16 v[32:35], v[172:175], v[188:191], v[32:35]
	v_mfma_f32_16x16x32_bf16 v[20:23], v[164:167], v[196:199], v[20:23]
	v_mfma_f32_16x16x32_bf16 v[16:19], v[172:175], v[196:199], v[16:19]
	v_mfma_f32_16x16x32_bf16 v[4:7], v[164:167], v[212:215], v[4:7]
	v_mfma_f32_16x16x32_bf16 v[0:3], v[172:175], v[212:215], v[0:3]
	v_mfma_f32_16x16x32_bf16 v[52:55], v[168:171], v[180:183], v[52:55]
	v_mfma_f32_16x16x32_bf16 v[48:51], v[176:179], v[180:183], v[48:51]
	v_mfma_f32_16x16x32_bf16 v[36:39], v[168:171], v[192:195], v[36:39]
	v_mfma_f32_16x16x32_bf16 v[32:35], v[176:179], v[192:195], v[32:35]
	v_mfma_f32_16x16x32_bf16 v[20:23], v[168:171], v[200:203], v[20:23]
	v_mfma_f32_16x16x32_bf16 v[16:19], v[176:179], v[200:203], v[16:19]
	v_mfma_f32_16x16x32_bf16 v[4:7], v[168:171], v[216:219], v[4:7]
	v_mfma_f32_16x16x32_bf16 v[0:3], v[176:179], v[216:219], v[0:3]
	s_barrier
	s_add_i32 s68, s68, 2
	s_add_u32 s34, s34, 0x100
	s_addc_u32 s35, s35, 0
	s_cmp_gt_u32 s68, 29
	s_cbranch_scc1 .LBB0_918

; __device__ __forceinline__ int lane_id() { int l; asm volatile("v_mbcnt_lo_u32_b32 %0, -1, 0\n\tv_mbcnt_hi_u32_b32 %0, -1, %0" : "=v"(l)); return l; }
;     __device__ __forceinline__ bool next(int i, UnitG& u) const { if (!P.next(i, u)) return false; u.O = O + ((size_t)u.x0 * 256 * 2048 + (size_t)u.x1 * 256) * 2; u.ldo = 2048; u.kind = 0; return true; }
; template <class Epi, class Sched>
; __device__ __forceinline__ void gemm_phase(PG8_LAS unsigned char* lds, const Sched& S, const Epi& E, int tid_in) {
;     ...
;         int aoff, boff; { const int l3 = lane_id(), fr3 = l3 & 15, fq3 = l3 >> 4; aoff = lds_byte(wr * 64 + fr3, fq3 * 8); boff = lds_byte(wc * 32 + fr3, fq3 * 8); }
;         const bool has_next = S.next(ui + 1, nxt);
;         const char* nA = has_next ? nxt.A : cA; const char* nB = has_next ? nxt.B : cB;
;         const int nlda = has_next ? nxt.lda : cur.lda, nldb = has_next ? nxt.ldb : cur.ldb;
;         unsigned nvA, nvB; { int r2, c2; stage_rc((wid * 64 + lane_id()) * 16, r2, c2); const int rb2 = Epi::PERM ? ((r2 & ~31) + perm32(r2 & 31)) : r2;
;             nvA = (unsigned)(r2 * nlda + c2) * 2u; nvB = (unsigned)(rb2 * nldb + c2) * 2u; }
;         const unsigned nqA = (unsigned)nlda * 128u, nqB = (unsigned)nldb * 128u;
;         const int nt = cur.K / BK;
.LBB0_1078:
	v_and_b32_e32 v1, 15, v0
	v_or_b32_e32 v2, s53, v1
	v_lshlrev_b32_e32 v5, 4, v0
	v_lshlrev_b32_e32 v3, 6, v2
	v_and_b32_e32 v4, 48, v0
	s_movk_i32 s24, 0x3c0
	v_and_b32_e32 v5, 0xfffffc00, v5
	v_lshlrev_b32_e32 v2, 2, v2
	v_and_or_b32 v3, v3, s24, v4
	v_add_u32_e32 v6, s54, v5
	v_and_b32_e32 v2, 32, v2
	v_lshlrev_b32_e32 v0, 2, v0
	v_bitop3_b32 v32, v3, v6, v2 bitop3:0xde
	v_lshl_or_b32 v1, v1, 6, v4
	v_add_u32_e32 v2, s56, v5
	v_and_b32_e32 v0, 32, v0
	v_bitop3_b32 v139, v1, v2, v0 bitop3:0xde
	v_mbcnt_lo_u32_b32 v0, -1, 0
	v_mbcnt_hi_u32_b32 v0, -1, v0
	s_mov_b32 s24, 0xfffe0
	v_add_u32_e32 v0, s57, v0
	v_ashrrev_i32_e32 v2, 31, v0
	v_lshrrev_b32_e32 v2, 26, v2
	v_lshlrev_b32_e32 v1, 4, v0
	v_add_u32_e32 v2, v0, v2
	v_bfe_i32 v0, v0, 27, 1
	v_lshrrev_b32_e32 v0, 22, v0
	v_add_u32_e32 v0, v1, v0
	v_and_b32_e32 v0, 0xfffffc00, v0
	v_sub_u32_e32 v0, v1, v0
	v_lshrrev_b32_e32 v1, 4, v0
	v_bitop3_b32 v0, v1, v0, 32 bitop3:0x6c
	v_ashrrev_i32_e32 v3, 31, v0
	v_ashrrev_i32_e32 v2, 6, v2
	v_lshrrev_b32_e32 v3, 26, v3
	v_lshlrev_b32_e32 v1, 3, v2
	v_add_u32_e32 v3, v0, v3
	v_and_b32_e32 v1, -16, v1
	v_ashrrev_i32_e32 v4, 6, v3
	v_and_b32_e32 v3, 0xc0, v3
	v_add_u32_e32 v1, v4, v1
	v_sub_u32_e32 v0, v0, v3
	v_lshlrev_b32_e32 v2, 5, v2
	v_ashrrev_i16_sdwa v0, v205, sext(v0) dst_sel:DWORD dst_unused:UNUSED_PAD src0_sel:DWORD src1_sel:BYTE_0
	v_lshrrev_b32_e32 v3, 2, v1
	v_and_b32_e32 v2, 32, v2
	v_bfe_i32 v0, v0, 0, 16
	v_lshlrev_b32_e32 v16, 1, v1
	v_and_b32_e32 v17, 4, v3
	v_and_b32_e32 v3, 3, v4
	s_add_i32 s67, 0, 0x10000
	s_add_i32 s71, 0, 0x14000
	v_and_or_b32 v18, v1, s24, v3
	v_add_lshl_u32 v33, v2, v0, 1
	v_add_u32_e32 v136, s67, v139
	v_and_b32_e32 v16, 24, v16
	v_add_u32_e32 v137, s71, v139
	v_lshl_add_u32 v134, v1, 12, v33
	ds_read_b128 v[0:3], v136
	ds_read_b128 v[4:7], v136 offset:1024
	ds_read_b128 v[8:11], v136 offset:2048
	ds_read_b128 v[12:15], v136 offset:3072
	v_or3_b32 v34, v18, v17, v16
	ds_read_b128 v[16:19], v137
	ds_read_b128 v[20:23], v137 offset:1024
	ds_read_b128 v[24:27], v137 offset:2048
	ds_read_b128 v[28:31], v137 offset:3072
	v_lshl_add_u32 v135, v34, 12, v33
	v_mov_b32_e32 v131, v185
	v_lshl_add_u64 v[132:133], s[20:21], 0, v[130:131]
	s_add_i32 s65, s35, 0xc000
	v_add_u32_e32 v138, 0, v32
	v_lshl_add_u64 v[64:65], v[132:133], 0, s[80:81]
	s_mov_b32 m0, s65
	s_add_i32 s66, s35, 0xe000
	ds_read_b128 v[32:35], v138
	ds_read_b128 v[36:39], v138 offset:1024
	ds_read_b128 v[40:43], v138 offset:2048
	ds_read_b128 v[44:47], v138 offset:3072
	ds_read_b128 v[48:51], v138 offset:4096
	ds_read_b128 v[52:55], v138 offset:5120
	ds_read_b128 v[56:59], v138 offset:6144
	ds_read_b128 v[60:63], v138 offset:7168
	global_load_lds_dwordx4 v[64:65], off
	v_lshl_add_u64 v[64:65], v[132:133], 0, s[78:79]
	s_mov_b32 m0, s66
	s_nop 0
	global_load_lds_dwordx4 v[64:65], off
	s_waitcnt vmcnt(24)
	s_waitcnt lgkmcnt(0)
	s_barrier
	s_waitcnt lgkmcnt(0)
	v_mfma_f32_16x16x32_bf16 v[64:67], v[0:3], v[32:35], 0
	v_mfma_f32_16x16x32_bf16 v[68:71], v[8:11], v[32:35], 0
	v_mfma_f32_16x16x32_bf16 v[72:75], v[0:3], v[40:43], 0
	v_mfma_f32_16x16x32_bf16 v[76:79], v[8:11], v[40:43], 0
	v_mfma_f32_16x16x32_bf16 v[80:83], v[0:3], v[48:51], 0
	v_mfma_f32_16x16x32_bf16 v[84:87], v[8:11], v[48:51], 0
	v_mfma_f32_16x16x32_bf16 v[88:91], v[0:3], v[56:59], 0
	v_mfma_f32_16x16x32_bf16 v[92:95], v[8:11], v[56:59], 0
	v_mfma_f32_16x16x32_bf16 v[64:67], v[4:7], v[36:39], v[64:67]
	v_mfma_f32_16x16x32_bf16 v[68:71], v[12:15], v[36:39], v[68:71]
	v_mfma_f32_16x16x32_bf16 v[72:75], v[4:7], v[44:47], v[72:75]
	v_mfma_f32_16x16x32_bf16 v[76:79], v[12:15], v[44:47], v[76:79]
	v_mfma_f32_16x16x32_bf16 v[80:83], v[4:7], v[52:55], v[80:83]
	v_mfma_f32_16x16x32_bf16 v[84:87], v[12:15], v[52:55], v[84:87]
	v_mfma_f32_16x16x32_bf16 v[88:91], v[4:7], v[60:63], v[88:91]
	v_mfma_f32_16x16x32_bf16 v[92:95], v[12:15], v[60:63], v[92:95]
	v_mfma_f32_16x16x32_bf16 v[96:99], v[16:19], v[32:35], 0
	v_mfma_f32_16x16x32_bf16 v[32:35], v[24:27], v[32:35], 0
	v_mfma_f32_16x16x32_bf16 v[108:111], v[28:31], v[36:39], v[32:35]
	v_mfma_f32_16x16x32_bf16 v[32:35], v[16:19], v[40:43], 0
	v_mfma_f32_16x16x32_bf16 v[140:143], v[20:23], v[44:47], v[32:35]
	v_mfma_f32_16x16x32_bf16 v[32:35], v[24:27], v[40:43], 0
	v_mfma_f32_16x16x32_bf16 v[40:43], v[28:31], v[44:47], v[32:35]
	v_mfma_f32_16x16x32_bf16 v[32:35], v[16:19], v[48:51], 0
	v_mfma_f32_16x16x32_bf16 v[44:47], v[20:23], v[52:55], v[32:35]
	v_mfma_f32_16x16x32_bf16 v[32:35], v[24:27], v[48:51], 0
	v_mfma_f32_16x16x32_bf16 v[48:51], v[28:31], v[52:55], v[32:35]
	v_mfma_f32_16x16x32_bf16 v[32:35], v[16:19], v[56:59], 0
	v_mfma_f32_16x16x32_bf16 v[52:55], v[20:23], v[60:63], v[32:35]
	v_mfma_f32_16x16x32_bf16 v[32:35], v[24:27], v[56:59], 0
	v_mfma_f32_16x16x32_bf16 v[104:107], v[20:23], v[36:39], v[96:99]
	v_mfma_f32_16x16x32_bf16 v[56:59], v[28:31], v[60:63], v[32:35]
	s_barrier
	v_mov_b32_e32 v129, v185
	v_lshl_add_u64 v[186:187], s[22:23], 0, v[128:129]
	s_mov_b64 s[24:25], 0x100
	s_add_i32 s67, s67, s34
	v_lshl_add_u64 v[124:125], v[186:187], 0, s[24:25]
	s_mov_b32 m0, s67
	s_mov_b64 s[74:75], 0x40100
	s_add_i32 s70, s67, 0x2000
	ds_read_b128 v[32:35], v138 offset:16384
	ds_read_b128 v[36:39], v138 offset:17408
	ds_read_b128 v[60:63], v138 offset:18432
	ds_read_b128 v[96:99], v138 offset:19456
	ds_read_b128 v[100:103], v138 offset:20480
	ds_read_b128 v[112:115], v138 offset:21504
	ds_read_b128 v[116:119], v138 offset:22528
	ds_read_b128 v[120:123], v138 offset:23552
	global_load_lds_dwordx4 v[124:125], off
	v_lshl_add_u64 v[124:125], v[186:187], 0, s[74:75]
	s_mov_b32 m0, s70
	s_mov_b64 s[76:77], 0x80100
	s_add_i32 s71, s71, s34
	global_load_lds_dwordx4 v[124:125], off
	v_lshl_add_u64 v[124:125], v[186:187], 0, s[76:77]
	s_mov_b32 m0, s71
	s_mov_b64 s[86:87], 0xc0100
	s_add_i32 s72, s71, 0x2000
	global_load_lds_dwordx4 v[124:125], off
	v_lshl_add_u64 v[124:125], v[186:187], 0, s[86:87]
	s_mov_b32 m0, s72
	s_nop 0
	global_load_lds_dwordx4 v[124:125], off
	v_lshl_add_u64 v[124:125], v[132:133], 0, s[24:25]
	s_mov_b32 m0, s35
	s_nop 0
	global_load_lds_dwordx4 v[124:125], off
	v_lshl_add_u64 v[124:125], v[132:133], 0, s[74:75]
	s_mov_b32 m0, s44
	s_nop 0
	global_load_lds_dwordx4 v[124:125], off
	s_waitcnt vmcnt(24)
	s_waitcnt lgkmcnt(0)
	s_barrier
	s_waitcnt lgkmcnt(0)
	v_mfma_f32_16x16x32_bf16 v[124:127], v[0:3], v[32:35], 0
	v_mfma_f32_16x16x32_bf16 v[144:147], v[4:7], v[36:39], v[124:127]
	v_mfma_f32_16x16x32_bf16 v[124:127], v[8:11], v[32:35], 0
	v_mfma_f32_16x16x32_bf16 v[148:151], v[12:15], v[36:39], v[124:127]
	v_mfma_f32_16x16x32_bf16 v[124:127], v[0:3], v[60:63], 0
	v_mfma_f32_16x16x32_bf16 v[152:155], v[4:7], v[96:99], v[124:127]
	v_mfma_f32_16x16x32_bf16 v[124:127], v[8:11], v[60:63], 0
	v_mfma_f32_16x16x32_bf16 v[156:159], v[12:15], v[96:99], v[124:127]
	v_mfma_f32_16x16x32_bf16 v[124:127], v[0:3], v[100:103], 0
	v_mfma_f32_16x16x32_bf16 v[0:3], v[0:3], v[116:119], 0
	v_mfma_f32_16x16x32_bf16 v[160:163], v[4:7], v[112:115], v[124:127]
	v_mfma_f32_16x16x32_bf16 v[0:3], v[4:7], v[120:123], v[0:3]
	v_mfma_f32_16x16x32_bf16 v[4:7], v[8:11], v[116:119], 0
	v_mfma_f32_16x16x32_bf16 v[124:127], v[8:11], v[100:103], 0
	v_mfma_f32_16x16x32_bf16 v[8:11], v[12:15], v[120:123], v[4:7]
	v_mfma_f32_16x16x32_bf16 v[164:167], v[12:15], v[112:115], v[124:127]
	v_mfma_f32_16x16x32_bf16 v[4:7], v[16:19], v[32:35], 0
	v_mfma_f32_16x16x32_bf16 v[12:15], v[20:23], v[36:39], v[4:7]
	v_mfma_f32_16x16x32_bf16 v[4:7], v[24:27], v[32:35], 0
	v_mfma_f32_16x16x32_bf16 v[168:171], v[28:31], v[36:39], v[4:7]
	v_mfma_f32_16x16x32_bf16 v[4:7], v[16:19], v[60:63], 0
	v_mfma_f32_16x16x32_bf16 v[172:175], v[20:23], v[96:99], v[4:7]
	v_mfma_f32_16x16x32_bf16 v[4:7], v[24:27], v[60:63], 0
	v_mfma_f32_16x16x32_bf16 v[176:179], v[28:31], v[96:99], v[4:7]
	v_mfma_f32_16x16x32_bf16 v[4:7], v[16:19], v[100:103], 0
	v_mfma_f32_16x16x32_bf16 v[180:183], v[20:23], v[112:115], v[4:7]
	v_mfma_f32_16x16x32_bf16 v[4:7], v[24:27], v[100:103], 0
	v_mfma_f32_16x16x32_bf16 v[188:191], v[28:31], v[112:115], v[4:7]
	v_mfma_f32_16x16x32_bf16 v[4:7], v[16:19], v[116:119], 0
	v_mfma_f32_16x16x32_bf16 v[192:195], v[20:23], v[120:123], v[4:7]
	v_mfma_f32_16x16x32_bf16 v[4:7], v[24:27], v[116:119], 0
	v_mfma_f32_16x16x32_bf16 v[196:199], v[28:31], v[120:123], v[4:7]
	s_barrier
	s_add_i32 s73, 0, 0x18000
	s_add_i32 s75, 0, 0x1c000
	v_add_u32_e32 v129, s73, v139
	v_add_u32_e32 v131, s75, v139
	s_nop 0
	ds_read_b128 v[4:7], v129
	ds_read_b128 v[24:27], v129 offset:1024
	ds_read_b128 v[28:31], v129 offset:2048
	ds_read_b128 v[60:63], v129 offset:3072
	ds_read_b128 v[200:203], v131
	ds_read_b128 v[212:215], v131 offset:1024
	ds_read_b128 v[216:219], v131 offset:2048
	ds_read_b128 v[220:223], v131 offset:3072
	s_mov_b32 m0, s45
	v_lshl_add_u64 v[32:33], v[132:133], 0, s[76:77]
	ds_read_b128 v[16:19], v138 offset:32768
	ds_read_b128 v[20:23], v138 offset:33792
	ds_read_b128 v[224:227], v138 offset:34816
	ds_read_b128 v[228:231], v138 offset:35840
	ds_read_b128 v[232:235], v138 offset:36864
	ds_read_b128 v[236:239], v138 offset:37888
	ds_read_b128 v[240:243], v138 offset:38912
	ds_read_b128 v[244:247], v138 offset:39936
	global_load_lds_dwordx4 v[32:33], off
	v_lshl_add_u64 v[32:33], v[132:133], 0, s[86:87]
	s_mov_b32 m0, s46
	s_nop 0
	global_load_lds_dwordx4 v[32:33], off
	s_waitcnt vmcnt(8)
	s_waitcnt lgkmcnt(0)
	s_barrier
	s_waitcnt lgkmcnt(0)
	v_mfma_f32_16x16x32_bf16 v[32:35], v[4:7], v[16:19], v[64:67]
	v_mfma_f32_16x16x32_bf16 v[116:119], v[24:27], v[20:23], v[32:35]
	v_mfma_f32_16x16x32_bf16 v[32:35], v[28:31], v[16:19], v[68:71]
	v_mfma_f32_16x16x32_bf16 v[112:115], v[60:63], v[20:23], v[32:35]
	v_mfma_f32_16x16x32_bf16 v[32:35], v[4:7], v[224:227], v[72:75]
	v_mfma_f32_16x16x32_bf16 v[100:103], v[24:27], v[228:231], v[32:35]
	v_mfma_f32_16x16x32_bf16 v[32:35], v[28:31], v[224:227], v[76:79]
	v_mfma_f32_16x16x32_bf16 v[96:99], v[60:63], v[228:231], v[32:35]
	v_mfma_f32_16x16x32_bf16 v[32:35], v[4:7], v[232:235], v[80:83]
	v_mfma_f32_16x16x32_bf16 v[68:71], v[24:27], v[236:239], v[32:35]
	v_mfma_f32_16x16x32_bf16 v[32:35], v[28:31], v[232:235], v[84:87]
	v_mfma_f32_16x16x32_bf16 v[64:67], v[60:63], v[236:239], v[32:35]
	v_mfma_f32_16x16x32_bf16 v[32:35], v[4:7], v[240:243], v[88:91]
	v_mfma_f32_16x16x32_bf16 v[36:39], v[24:27], v[244:247], v[32:35]
	v_mfma_f32_16x16x32_bf16 v[32:35], v[28:31], v[240:243], v[92:95]
	v_mfma_f32_16x16x32_bf16 v[32:35], v[60:63], v[244:247], v[32:35]
	v_mfma_f32_16x16x32_bf16 v[72:75], v[200:203], v[16:19], v[104:107]
	v_mfma_f32_16x16x32_bf16 v[16:19], v[216:219], v[16:19], v[108:111]
	v_mfma_f32_16x16x32_bf16 v[120:123], v[220:223], v[20:23], v[16:19]
	v_mfma_f32_16x16x32_bf16 v[16:19], v[200:203], v[224:227], v[140:143]
	v_mfma_f32_16x16x32_bf16 v[108:111], v[212:215], v[228:231], v[16:19]
	v_mfma_f32_16x16x32_bf16 v[16:19], v[216:219], v[224:227], v[40:43]
	v_mfma_f32_16x16x32_bf16 v[104:107], v[220:223], v[228:231], v[16:19]
	v_mfma_f32_16x16x32_bf16 v[16:19], v[200:203], v[232:235], v[44:47]
	v_mfma_f32_16x16x32_bf16 v[84:87], v[212:215], v[236:239], v[16:19]
	v_mfma_f32_16x16x32_bf16 v[16:19], v[216:219], v[232:235], v[48:51]
	v_mfma_f32_16x16x32_bf16 v[80:83], v[220:223], v[236:239], v[16:19]
	v_mfma_f32_16x16x32_bf16 v[16:19], v[200:203], v[240:243], v[52:55]
	v_mfma_f32_16x16x32_bf16 v[52:55], v[212:215], v[244:247], v[16:19]
	v_mfma_f32_16x16x32_bf16 v[16:19], v[216:219], v[240:243], v[56:59]
	v_mfma_f32_16x16x32_bf16 v[124:127], v[212:215], v[20:23], v[72:75]
	v_mfma_f32_16x16x32_bf16 v[48:51], v[220:223], v[244:247], v[16:19]
	s_barrier
; #define PG8_WAIT_V(n) asm volatile("s_waitcnt vmcnt(" #n ")" ::: "memory")
; #define PG8_WAIT_VP() asm volatile("s_waitcnt vmcnt(%0)" :: "n"(8 + Epi::NST) : "memory")
; template <class Epi, class Sched>
; __device__ __forceinline__ void gemm_phase(PG8_LAS unsigned char* lds, const Sched& S, const Epi& E, int tid_in) {
;     ...
;         { const int t = 0; PG8_KITER(PG8_WAIT_VP()); }
;         for (int t = 2; t < nt; t += 2) PG8_KITER(PG8_WAIT_V(8));
	s_mov_b64 s[24:25], 0x180
	s_add_i32 s73, s73, s34
	s_nop 1
	v_lshl_add_u64 v[16:17], v[186:187], 0, s[24:25]
	s_mov_b32 m0, s73
	s_mov_b64 s[86:87], 0x40180
	s_add_i32 s74, s73, 0x2000
	ds_read_b128 v[56:59], v138 offset:49152
	ds_read_b128 v[88:91], v138 offset:50176
	ds_read_b128 v[140:143], v138 offset:51200
	ds_read_b128 v[224:227], v138 offset:52224
	ds_read_b128 v[228:231], v138 offset:53248
	ds_read_b128 v[232:235], v138 offset:54272
	ds_read_b128 v[236:239], v138 offset:55296
	ds_read_b128 v[240:243], v138 offset:56320
	global_load_lds_dwordx4 v[16:17], off
	v_lshl_add_u64 v[16:17], v[186:187], 0, s[86:87]
	s_mov_b32 m0, s74
	s_mov_b64 s[62:63], 0x80180
	s_add_i32 s75, s75, s34
	global_load_lds_dwordx4 v[16:17], off
	v_lshl_add_u64 v[16:17], v[186:187], 0, s[62:63]
	s_mov_b32 m0, s75
	s_mov_b64 s[4:5], 0xc0180
	s_add_i32 s76, s75, 0x2000
	global_load_lds_dwordx4 v[16:17], off
	v_lshl_add_u64 v[16:17], v[186:187], 0, s[4:5]
	s_mov_b32 m0, s76
	s_nop 0
	global_load_lds_dwordx4 v[16:17], off
	v_lshl_add_u64 v[16:17], v[132:133], 0, s[24:25]
	s_mov_b32 m0, s48
	s_nop 0
	global_load_lds_dwordx4 v[16:17], off
	v_lshl_add_u64 v[16:17], v[132:133], 0, s[86:87]
	s_mov_b32 m0, s51
	s_nop 0
	global_load_lds_dwordx4 v[16:17], off
	s_waitcnt vmcnt(8)
	s_waitcnt lgkmcnt(0)
	s_barrier
	s_waitcnt lgkmcnt(0)
	v_mfma_f32_16x16x32_bf16 v[16:19], v[4:7], v[56:59], v[144:147]
	v_mfma_f32_16x16x32_bf16 v[76:79], v[24:27], v[88:91], v[16:19]
	v_mfma_f32_16x16x32_bf16 v[16:19], v[28:31], v[56:59], v[148:151]
	v_mfma_f32_16x16x32_bf16 v[72:75], v[60:63], v[88:91], v[16:19]
	v_mfma_f32_16x16x32_bf16 v[16:19], v[4:7], v[140:143], v[152:155]
	v_mfma_f32_16x16x32_bf16 v[44:47], v[24:27], v[224:227], v[16:19]
	v_mfma_f32_16x16x32_bf16 v[16:19], v[28:31], v[140:143], v[156:159]
	v_mfma_f32_16x16x32_bf16 v[40:43], v[60:63], v[224:227], v[16:19]
	v_mfma_f32_16x16x32_bf16 v[16:19], v[4:7], v[228:231], v[160:163]
	v_mfma_f32_16x16x32_bf16 v[0:3], v[4:7], v[236:239], v[0:3]
	v_mfma_f32_16x16x32_bf16 v[20:23], v[24:27], v[232:235], v[16:19]
	v_mfma_f32_16x16x32_bf16 v[16:19], v[28:31], v[228:231], v[164:167]
	v_mfma_f32_16x16x32_bf16 v[4:7], v[24:27], v[240:243], v[0:3]
	v_mfma_f32_16x16x32_bf16 v[0:3], v[28:31], v[236:239], v[8:11]
	v_mfma_f32_16x16x32_bf16 v[16:19], v[60:63], v[232:235], v[16:19]
	v_mfma_f32_16x16x32_bf16 v[0:3], v[60:63], v[240:243], v[0:3]
	v_mfma_f32_16x16x32_bf16 v[8:11], v[200:203], v[56:59], v[12:15]
	v_mfma_f32_16x16x32_bf16 v[92:95], v[212:215], v[88:91], v[8:11]
	v_mfma_f32_16x16x32_bf16 v[8:11], v[216:219], v[56:59], v[168:171]
	v_mfma_f32_16x16x32_bf16 v[88:91], v[220:223], v[88:91], v[8:11]
	v_mfma_f32_16x16x32_bf16 v[8:11], v[200:203], v[140:143], v[172:175]
	v_mfma_f32_16x16x32_bf16 v[60:63], v[212:215], v[224:227], v[8:11]
	v_mfma_f32_16x16x32_bf16 v[8:11], v[216:219], v[140:143], v[176:179]
	v_mfma_f32_16x16x32_bf16 v[56:59], v[220:223], v[224:227], v[8:11]
	v_mfma_f32_16x16x32_bf16 v[8:11], v[200:203], v[228:231], v[180:183]
	v_mfma_f32_16x16x32_bf16 v[28:31], v[212:215], v[232:235], v[8:11]
	v_mfma_f32_16x16x32_bf16 v[8:11], v[216:219], v[228:231], v[188:191]
	v_mfma_f32_16x16x32_bf16 v[24:27], v[220:223], v[232:235], v[8:11]
	v_mfma_f32_16x16x32_bf16 v[8:11], v[200:203], v[236:239], v[192:195]
	v_mfma_f32_16x16x32_bf16 v[12:15], v[212:215], v[240:243], v[8:11]
	v_mfma_f32_16x16x32_bf16 v[8:11], v[216:219], v[236:239], v[196:199]
	v_mfma_f32_16x16x32_bf16 v[8:11], v[220:223], v[240:243], v[8:11]
	s_barrier
	s_add_u32 s68, s22, 0x200
	s_addc_u32 s77, s23, 0
	s_mov_b32 s82, 0
	s_mov_b64 s[22:23], 0
.LBB0_1079:
	ds_read_b128 v[140:143], v136
	ds_read_b128 v[144:147], v136 offset:1024
	ds_read_b128 v[148:151], v136 offset:2048
	ds_read_b128 v[152:155], v136 offset:3072
	ds_read_b128 v[156:159], v137
	ds_read_b128 v[160:163], v137 offset:1024
	ds_read_b128 v[164:167], v137 offset:2048
	ds_read_b128 v[168:171], v137 offset:3072
	s_add_u32 s24, s20, s22
	s_addc_u32 s25, s21, s23
	s_add_u32 s86, s24, 0x200
	s_addc_u32 s87, s25, 0
	s_add_u32 s92, s68, s22
	s_addc_u32 s93, s77, s23
	s_cmpk_eq_i32 s22, 0xe00
	s_cselect_b64 vcc, -1, 0
	s_and_b64 s[24:25], vcc, exec
	v_cndmask_b32_e32 v186, v130, v134, vcc
	s_cselect_b32 s25, s15, s87
	s_cselect_b32 s24, s14, s86
	s_cselect_b32 s87, s17, s93
	s_cselect_b32 s86, s16, s92
	v_cndmask_b32_e32 v184, v128, v135, vcc
	v_lshl_add_u64 v[206:207], v[132:133], 0, s[22:23]
	s_mov_b32 m0, s65
	v_lshl_add_u64 v[210:211], v[206:207], 0, s[62:63]
	ds_read_b128 v[172:175], v138
	ds_read_b128 v[176:179], v138 offset:1024
	ds_read_b128 v[180:183], v138 offset:2048
	ds_read_b128 v[188:191], v138 offset:3072
	ds_read_b128 v[192:195], v138 offset:4096
	ds_read_b128 v[196:199], v138 offset:5120
	ds_read_b128 v[200:203], v138 offset:6144
	ds_read_b128 v[212:215], v138 offset:7168
	global_load_lds_dwordx4 v[210:211], off
	v_lshl_add_u64 v[206:207], v[206:207], 0, s[4:5]
	s_mov_b32 m0, s66
	s_nop 0
	global_load_lds_dwordx4 v[206:207], off
	s_waitcnt vmcnt(8)
	s_waitcnt lgkmcnt(0)
	s_barrier
	s_waitcnt lgkmcnt(0)
	v_mfma_f32_16x16x32_bf16 v[116:119], v[140:143], v[172:175], v[116:119]
	v_mfma_f32_16x16x32_bf16 v[112:115], v[148:151], v[172:175], v[112:115]
	v_mfma_f32_16x16x32_bf16 v[100:103], v[140:143], v[180:183], v[100:103]
	v_mfma_f32_16x16x32_bf16 v[96:99], v[148:151], v[180:183], v[96:99]
	v_mfma_f32_16x16x32_bf16 v[68:71], v[140:143], v[192:195], v[68:71]
	v_mfma_f32_16x16x32_bf16 v[64:67], v[148:151], v[192:195], v[64:67]
	v_mfma_f32_16x16x32_bf16 v[36:39], v[140:143], v[200:203], v[36:39]
	v_mfma_f32_16x16x32_bf16 v[32:35], v[148:151], v[200:203], v[32:35]
	v_mfma_f32_16x16x32_bf16 v[116:119], v[144:147], v[176:179], v[116:119]
	v_mfma_f32_16x16x32_bf16 v[112:115], v[152:155], v[176:179], v[112:115]
	v_mfma_f32_16x16x32_bf16 v[100:103], v[144:147], v[188:191], v[100:103]
	v_mfma_f32_16x16x32_bf16 v[96:99], v[152:155], v[188:191], v[96:99]
	v_mfma_f32_16x16x32_bf16 v[68:71], v[144:147], v[196:199], v[68:71]
	v_mfma_f32_16x16x32_bf16 v[64:67], v[152:155], v[196:199], v[64:67]
	v_mfma_f32_16x16x32_bf16 v[36:39], v[144:147], v[212:215], v[36:39]
	v_mfma_f32_16x16x32_bf16 v[32:35], v[152:155], v[212:215], v[32:35]
	v_mfma_f32_16x16x32_bf16 v[124:127], v[156:159], v[172:175], v[124:127]
	v_mfma_f32_16x16x32_bf16 v[120:123], v[164:167], v[172:175], v[120:123]
	v_mfma_f32_16x16x32_bf16 v[108:111], v[156:159], v[180:183], v[108:111]
	v_mfma_f32_16x16x32_bf16 v[104:107], v[164:167], v[180:183], v[104:107]
	v_mfma_f32_16x16x32_bf16 v[84:87], v[156:159], v[192:195], v[84:87]
	v_mfma_f32_16x16x32_bf16 v[80:83], v[164:167], v[192:195], v[80:83]
	v_mfma_f32_16x16x32_bf16 v[52:55], v[156:159], v[200:203], v[52:55]
	v_mfma_f32_16x16x32_bf16 v[48:51], v[164:167], v[200:203], v[48:51]
	v_mfma_f32_16x16x32_bf16 v[124:127], v[160:163], v[176:179], v[124:127]
	v_mfma_f32_16x16x32_bf16 v[120:123], v[168:171], v[176:179], v[120:123]
	v_mfma_f32_16x16x32_bf16 v[108:111], v[160:163], v[188:191], v[108:111]
	v_mfma_f32_16x16x32_bf16 v[104:107], v[168:171], v[188:191], v[104:107]
	v_mfma_f32_16x16x32_bf16 v[84:87], v[160:163], v[196:199], v[84:87]
	v_mfma_f32_16x16x32_bf16 v[80:83], v[168:171], v[196:199], v[80:83]
	v_mfma_f32_16x16x32_bf16 v[52:55], v[160:163], v[212:215], v[52:55]
	v_mfma_f32_16x16x32_bf16 v[48:51], v[168:171], v[212:215], v[48:51]
	s_barrier
	s_mov_b32 m0, s67
	v_lshl_add_u64 v[206:207], s[86:87], 0, v[184:185]
	ds_read_b128 v[172:175], v138 offset:16384
	ds_read_b128 v[176:179], v138 offset:17408
	ds_read_b128 v[180:183], v138 offset:18432
	ds_read_b128 v[188:191], v138 offset:19456
	ds_read_b128 v[192:195], v138 offset:20480
	ds_read_b128 v[196:199], v138 offset:21504
	ds_read_b128 v[200:203], v138 offset:22528
	ds_read_b128 v[212:215], v138 offset:23552
	global_load_lds_dwordx4 v184, s[86:87]
	v_lshl_add_u64 v[210:211], v[206:207], 0, s[88:89]
	s_mov_b32 m0, s70
	v_mov_b32_e32 v187, v185
	global_load_lds_dwordx4 v[210:211], off
	v_lshl_add_u64 v[210:211], v[206:207], 0, s[90:91]
	s_mov_b32 m0, s71
	s_nop 0
	global_load_lds_dwordx4 v[210:211], off
	v_lshl_add_u64 v[210:211], v[206:207], 0, s[96:97]
	s_mov_b32 m0, s72
	s_nop 0
	global_load_lds_dwordx4 v[210:211], off
	v_lshl_add_u64 v[210:211], s[24:25], 0, v[186:187]
	s_mov_b32 m0, s35
	s_nop 0
	global_load_lds_dwordx4 v186, s[24:25]
	v_lshl_add_u64 v[186:187], v[210:211], 0, s[88:89]
	s_mov_b32 m0, s44
	s_nop 0
	global_load_lds_dwordx4 v[186:187], off
	s_waitcnt vmcnt(8)
	s_waitcnt lgkmcnt(0)
	s_barrier
	s_waitcnt lgkmcnt(0)
	v_mfma_f32_16x16x32_bf16 v[76:79], v[140:143], v[172:175], v[76:79]
	v_mfma_f32_16x16x32_bf16 v[72:75], v[148:151], v[172:175], v[72:75]
	v_mfma_f32_16x16x32_bf16 v[44:47], v[140:143], v[180:183], v[44:47]
	v_mfma_f32_16x16x32_bf16 v[40:43], v[148:151], v[180:183], v[40:43]
	v_mfma_f32_16x16x32_bf16 v[20:23], v[140:143], v[192:195], v[20:23]
	v_mfma_f32_16x16x32_bf16 v[16:19], v[148:151], v[192:195], v[16:19]
	v_mfma_f32_16x16x32_bf16 v[4:7], v[140:143], v[200:203], v[4:7]
	v_mfma_f32_16x16x32_bf16 v[0:3], v[148:151], v[200:203], v[0:3]
	v_mfma_f32_16x16x32_bf16 v[76:79], v[144:147], v[176:179], v[76:79]
	v_mfma_f32_16x16x32_bf16 v[72:75], v[152:155], v[176:179], v[72:75]
	v_mfma_f32_16x16x32_bf16 v[44:47], v[144:147], v[188:191], v[44:47]
	v_mfma_f32_16x16x32_bf16 v[40:43], v[152:155], v[188:191], v[40:43]
	v_mfma_f32_16x16x32_bf16 v[20:23], v[144:147], v[196:199], v[20:23]
	v_mfma_f32_16x16x32_bf16 v[16:19], v[152:155], v[196:199], v[16:19]
	v_mfma_f32_16x16x32_bf16 v[4:7], v[144:147], v[212:215], v[4:7]
	v_mfma_f32_16x16x32_bf16 v[0:3], v[152:155], v[212:215], v[0:3]
	v_mfma_f32_16x16x32_bf16 v[92:95], v[156:159], v[172:175], v[92:95]
	v_mfma_f32_16x16x32_bf16 v[88:91], v[164:167], v[172:175], v[88:91]
	v_mfma_f32_16x16x32_bf16 v[60:63], v[156:159], v[180:183], v[60:63]
	v_mfma_f32_16x16x32_bf16 v[56:59], v[164:167], v[180:183], v[56:59]
	v_mfma_f32_16x16x32_bf16 v[28:31], v[156:159], v[192:195], v[28:31]
	v_mfma_f32_16x16x32_bf16 v[24:27], v[164:167], v[192:195], v[24:27]
	v_mfma_f32_16x16x32_bf16 v[12:15], v[156:159], v[200:203], v[12:15]
	v_mfma_f32_16x16x32_bf16 v[8:11], v[164:167], v[200:203], v[8:11]
	v_mfma_f32_16x16x32_bf16 v[92:95], v[160:163], v[176:179], v[92:95]
	v_mfma_f32_16x16x32_bf16 v[88:91], v[168:171], v[176:179], v[88:91]
	v_mfma_f32_16x16x32_bf16 v[60:63], v[160:163], v[188:191], v[60:63]
	v_mfma_f32_16x16x32_bf16 v[56:59], v[168:171], v[188:191], v[56:59]
	v_mfma_f32_16x16x32_bf16 v[28:31], v[160:163], v[196:199], v[28:31]
	v_mfma_f32_16x16x32_bf16 v[24:27], v[168:171], v[196:199], v[24:27]
	v_mfma_f32_16x16x32_bf16 v[12:15], v[160:163], v[212:215], v[12:15]
	v_mfma_f32_16x16x32_bf16 v[8:11], v[168:171], v[212:215], v[8:11]
	s_barrier
; #define PG8_WAIT_V(n) asm volatile("s_waitcnt vmcnt(" #n ")" ::: "memory")
; #define PG8_WAIT_VP() asm volatile("s_waitcnt vmcnt(%0)" :: "n"(8 + Epi::NST) : "memory")
; #define PG8_BAR __builtin_amdgcn_s_barrier()
; template <class Epi, class Sched>
; __device__ __forceinline__ void gemm_phase(PG8_LAS unsigned char* lds, const Sched& S, const Epi& E, int tid_in) {
;     ...
;         { const int t = 0; PG8_KITER(PG8_WAIT_VP()); }
;         for (int t = 2; t < nt; t += 2) PG8_KITER(PG8_WAIT_V(8));
;     ...
;         if (wr == 0) PG8_BAR;
	ds_read_b128 v[140:143], v129
	ds_read_b128 v[144:147], v129 offset:1024
	ds_read_b128 v[148:151], v129 offset:2048
	ds_read_b128 v[152:155], v129 offset:3072
	ds_read_b128 v[156:159], v131
	ds_read_b128 v[160:163], v131 offset:1024
	ds_read_b128 v[164:167], v131 offset:2048
	ds_read_b128 v[168:171], v131 offset:3072
	s_mov_b32 m0, s45
	v_lshl_add_u64 v[186:187], v[210:211], 0, s[90:91]
	ds_read_b128 v[172:175], v138 offset:32768
	ds_read_b128 v[176:179], v138 offset:33792
	ds_read_b128 v[180:183], v138 offset:34816
	ds_read_b128 v[188:191], v138 offset:35840
	ds_read_b128 v[192:195], v138 offset:36864
	ds_read_b128 v[196:199], v138 offset:37888
	ds_read_b128 v[200:203], v138 offset:38912
	ds_read_b128 v[212:215], v138 offset:39936
	global_load_lds_dwordx4 v[186:187], off
	v_lshl_add_u64 v[186:187], v[210:211], 0, s[96:97]
	s_mov_b32 m0, s46
	s_nop 0
	global_load_lds_dwordx4 v[186:187], off
	s_waitcnt vmcnt(8)
	s_waitcnt lgkmcnt(0)
	s_barrier
	s_waitcnt lgkmcnt(0)
	v_mfma_f32_16x16x32_bf16 v[116:119], v[140:143], v[172:175], v[116:119]
	v_mfma_f32_16x16x32_bf16 v[112:115], v[148:151], v[172:175], v[112:115]
	v_mfma_f32_16x16x32_bf16 v[100:103], v[140:143], v[180:183], v[100:103]
	v_mfma_f32_16x16x32_bf16 v[96:99], v[148:151], v[180:183], v[96:99]
	v_mfma_f32_16x16x32_bf16 v[68:71], v[140:143], v[192:195], v[68:71]
	v_mfma_f32_16x16x32_bf16 v[64:67], v[148:151], v[192:195], v[64:67]
	v_mfma_f32_16x16x32_bf16 v[36:39], v[140:143], v[200:203], v[36:39]
	v_mfma_f32_16x16x32_bf16 v[32:35], v[148:151], v[200:203], v[32:35]
	v_mfma_f32_16x16x32_bf16 v[116:119], v[144:147], v[176:179], v[116:119]
	v_mfma_f32_16x16x32_bf16 v[112:115], v[152:155], v[176:179], v[112:115]
	v_mfma_f32_16x16x32_bf16 v[100:103], v[144:147], v[188:191], v[100:103]
	v_mfma_f32_16x16x32_bf16 v[96:99], v[152:155], v[188:191], v[96:99]
	v_mfma_f32_16x16x32_bf16 v[68:71], v[144:147], v[196:199], v[68:71]
	v_mfma_f32_16x16x32_bf16 v[64:67], v[152:155], v[196:199], v[64:67]
	v_mfma_f32_16x16x32_bf16 v[36:39], v[144:147], v[212:215], v[36:39]
	v_mfma_f32_16x16x32_bf16 v[32:35], v[152:155], v[212:215], v[32:35]
	v_mfma_f32_16x16x32_bf16 v[124:127], v[156:159], v[172:175], v[124:127]
	v_mfma_f32_16x16x32_bf16 v[120:123], v[164:167], v[172:175], v[120:123]
	v_mfma_f32_16x16x32_bf16 v[108:111], v[156:159], v[180:183], v[108:111]
	v_mfma_f32_16x16x32_bf16 v[104:107], v[164:167], v[180:183], v[104:107]
	v_mfma_f32_16x16x32_bf16 v[84:87], v[156:159], v[192:195], v[84:87]
	v_mfma_f32_16x16x32_bf16 v[80:83], v[164:167], v[192:195], v[80:83]
	v_mfma_f32_16x16x32_bf16 v[52:55], v[156:159], v[200:203], v[52:55]
	v_mfma_f32_16x16x32_bf16 v[48:51], v[164:167], v[200:203], v[48:51]
	v_mfma_f32_16x16x32_bf16 v[124:127], v[160:163], v[176:179], v[124:127]
	v_mfma_f32_16x16x32_bf16 v[120:123], v[168:171], v[176:179], v[120:123]
	v_mfma_f32_16x16x32_bf16 v[108:111], v[160:163], v[188:191], v[108:111]
	v_mfma_f32_16x16x32_bf16 v[104:107], v[168:171], v[188:191], v[104:107]
	v_mfma_f32_16x16x32_bf16 v[84:87], v[160:163], v[196:199], v[84:87]
	v_mfma_f32_16x16x32_bf16 v[80:83], v[168:171], v[196:199], v[80:83]
	v_mfma_f32_16x16x32_bf16 v[52:55], v[160:163], v[212:215], v[52:55]
	v_mfma_f32_16x16x32_bf16 v[48:51], v[168:171], v[212:215], v[48:51]
	s_barrier
	s_mov_b32 m0, s73
	v_lshl_add_u64 v[186:187], v[206:207], 0, s[84:85]
	ds_read_b128 v[172:175], v138 offset:49152
	ds_read_b128 v[176:179], v138 offset:50176
	ds_read_b128 v[180:183], v138 offset:51200
	ds_read_b128 v[188:191], v138 offset:52224
	ds_read_b128 v[192:195], v138 offset:53248
	ds_read_b128 v[196:199], v138 offset:54272
	ds_read_b128 v[200:203], v138 offset:55296
	ds_read_b128 v[212:215], v138 offset:56320
	global_load_lds_dwordx4 v[186:187], off
	v_lshl_add_u64 v[186:187], v[206:207], 0, s[94:95]
	s_mov_b32 m0, s74
	s_nop 0
	global_load_lds_dwordx4 v[186:187], off
	v_lshl_add_u64 v[186:187], v[206:207], 0, s[80:81]
	s_mov_b32 m0, s75
	s_nop 0
	global_load_lds_dwordx4 v[186:187], off
	v_lshl_add_u64 v[186:187], v[206:207], 0, s[78:79]
	s_mov_b32 m0, s76
	s_nop 0
	global_load_lds_dwordx4 v[186:187], off
	v_lshl_add_u64 v[186:187], v[210:211], 0, s[84:85]
	s_mov_b32 m0, s48
	s_nop 0
	global_load_lds_dwordx4 v[186:187], off
	v_lshl_add_u64 v[186:187], v[210:211], 0, s[94:95]
	s_mov_b32 m0, s51
	s_nop 0
	global_load_lds_dwordx4 v[186:187], off
	s_waitcnt vmcnt(8)
	s_waitcnt lgkmcnt(0)
	s_barrier
	s_waitcnt lgkmcnt(0)
	v_mfma_f32_16x16x32_bf16 v[76:79], v[140:143], v[172:175], v[76:79]
	v_mfma_f32_16x16x32_bf16 v[72:75], v[148:151], v[172:175], v[72:75]
	v_mfma_f32_16x16x32_bf16 v[44:47], v[140:143], v[180:183], v[44:47]
	v_mfma_f32_16x16x32_bf16 v[40:43], v[148:151], v[180:183], v[40:43]
	v_mfma_f32_16x16x32_bf16 v[20:23], v[140:143], v[192:195], v[20:23]
	v_mfma_f32_16x16x32_bf16 v[16:19], v[148:151], v[192:195], v[16:19]
	v_mfma_f32_16x16x32_bf16 v[4:7], v[140:143], v[200:203], v[4:7]
	v_mfma_f32_16x16x32_bf16 v[0:3], v[148:151], v[200:203], v[0:3]
	v_mfma_f32_16x16x32_bf16 v[76:79], v[144:147], v[176:179], v[76:79]
	v_mfma_f32_16x16x32_bf16 v[72:75], v[152:155], v[176:179], v[72:75]
	v_mfma_f32_16x16x32_bf16 v[44:47], v[144:147], v[188:191], v[44:47]
	v_mfma_f32_16x16x32_bf16 v[40:43], v[152:155], v[188:191], v[40:43]
	v_mfma_f32_16x16x32_bf16 v[20:23], v[144:147], v[196:199], v[20:23]
	v_mfma_f32_16x16x32_bf16 v[16:19], v[152:155], v[196:199], v[16:19]
	v_mfma_f32_16x16x32_bf16 v[4:7], v[144:147], v[212:215], v[4:7]
	v_mfma_f32_16x16x32_bf16 v[0:3], v[152:155], v[212:215], v[0:3]
	v_mfma_f32_16x16x32_bf16 v[92:95], v[156:159], v[172:175], v[92:95]
	v_mfma_f32_16x16x32_bf16 v[88:91], v[164:167], v[172:175], v[88:91]
	v_mfma_f32_16x16x32_bf16 v[60:63], v[156:159], v[180:183], v[60:63]
	v_mfma_f32_16x16x32_bf16 v[56:59], v[164:167], v[180:183], v[56:59]
	v_mfma_f32_16x16x32_bf16 v[28:31], v[156:159], v[192:195], v[28:31]
	v_mfma_f32_16x16x32_bf16 v[24:27], v[164:167], v[192:195], v[24:27]
	v_mfma_f32_16x16x32_bf16 v[12:15], v[156:159], v[200:203], v[12:15]
	v_mfma_f32_16x16x32_bf16 v[8:11], v[164:167], v[200:203], v[8:11]
	v_mfma_f32_16x16x32_bf16 v[92:95], v[160:163], v[176:179], v[92:95]
	v_mfma_f32_16x16x32_bf16 v[88:91], v[168:171], v[176:179], v[88:91]
	v_mfma_f32_16x16x32_bf16 v[60:63], v[160:163], v[188:191], v[60:63]
	v_mfma_f32_16x16x32_bf16 v[56:59], v[168:171], v[188:191], v[56:59]
	v_mfma_f32_16x16x32_bf16 v[28:31], v[160:163], v[196:199], v[28:31]
	v_mfma_f32_16x16x32_bf16 v[24:27], v[168:171], v[196:199], v[24:27]
	v_mfma_f32_16x16x32_bf16 v[12:15], v[160:163], v[212:215], v[12:15]
	v_mfma_f32_16x16x32_bf16 v[8:11], v[168:171], v[212:215], v[8:11]
	s_barrier
	s_add_i32 s82, s82, 2
	s_add_u32 s22, s22, 0x100
	s_addc_u32 s23, s23, 0
	s_cmp_gt_u32 s82, 29
	s_cbranch_scc0 .LBB0_1079
	s_and_b64 vcc, exec, s[10:11]
	s_cbranch_vccz .LBB0_1082
	s_barrier

; __device__ __forceinline__ int lane_id() { int l; asm volatile("v_mbcnt_lo_u32_b32 %0, -1, 0\n\tv_mbcnt_hi_u32_b32 %0, -1, %0" : "=v"(l)); return l; }
; #define PG8_WAIT_VP() asm volatile("s_waitcnt vmcnt(%0)" :: "n"(8 + Epi::NST) : "memory")
;     __device__ __forceinline__ bool next(int i, UnitG& u) const { if (!P.next(i, u)) return false; u.O = O + ((size_t)u.x0 * 256 * 2048 + (size_t)u.x1 * 256) * 2; u.ldo = 2048; u.kind = 0; return true; }
; template <class Epi, class Sched>
; __device__ __forceinline__ void gemm_phase(PG8_LAS unsigned char* lds, const Sched& S, const Epi& E, int tid_in) {
;     ...
;         int aoff, boff; { const int l3 = lane_id(), fr3 = l3 & 15, fq3 = l3 >> 4; aoff = lds_byte(wr * 64 + fr3, fq3 * 8); boff = lds_byte(wc * 32 + fr3, fq3 * 8); }
;         const bool has_next = S.next(ui + 1, nxt);
;         const char* nA = has_next ? nxt.A : cA; const char* nB = has_next ? nxt.B : cB;
;         const int nlda = has_next ? nxt.lda : cur.lda, nldb = has_next ? nxt.ldb : cur.ldb;
;         unsigned nvA, nvB; { int r2, c2; stage_rc((wid * 64 + lane_id()) * 16, r2, c2); const int rb2 = Epi::PERM ? ((r2 & ~31) + perm32(r2 & 31)) : r2;
;             nvA = (unsigned)(r2 * nlda + c2) * 2u; nvB = (unsigned)(rb2 * nldb + c2) * 2u; }
;         const unsigned nqA = (unsigned)nlda * 128u, nqB = (unsigned)nldb * 128u;
;         const int nt = cur.K / BK;
;     ...
;         { const int t = 0; PG8_KITER(PG8_WAIT_VP()); }
.LBB0_1273:
	v_and_b32_e32 v1, 15, v0
	v_or_b32_e32 v2, s77, v1
	v_lshlrev_b32_e32 v3, 6, v2
	v_and_b32_e32 v4, 48, v0
	s_movk_i32 s5, 0x3c0
	v_lshlrev_b32_e32 v5, 4, v0
	v_and_or_b32 v3, v3, s5, v4
	v_and_b32_e32 v5, 0xfffffc00, v5
	v_readlane_b32 s5, v255, 5
	v_lshlrev_b32_e32 v2, 2, v2
	v_and_b32_e32 v2, 32, v2
	v_add_u32_e32 v6, s5, v5
	v_readlane_b32 s5, v255, 7
	v_lshlrev_b32_e32 v0, 2, v0
	s_waitcnt vmcnt(0)
	v_bitop3_b32 v32, v3, v6, v2 bitop3:0xde
	v_lshl_or_b32 v1, v1, 6, v4
	v_add_u32_e32 v2, s5, v5
	v_and_b32_e32 v0, 32, v0
	v_bitop3_b32 v137, v1, v2, v0 bitop3:0xde
	v_mbcnt_lo_u32_b32 v0, -1, 0
	v_mbcnt_hi_u32_b32 v0, -1, v0
	v_readlane_b32 s5, v255, 9
	s_add_i32 s93, 0, 0x10000
	s_add_i32 s8, 0, 0x14000
	v_add_u32_e32 v0, s5, v0
	v_ashrrev_i32_e32 v2, 31, v0
	v_lshrrev_b32_e32 v2, 26, v2
	v_lshlrev_b32_e32 v1, 4, v0
	v_add_u32_e32 v2, v0, v2
	v_bfe_i32 v0, v0, 27, 1
	v_lshrrev_b32_e32 v0, 22, v0
	v_add_u32_e32 v0, v1, v0
	v_and_b32_e32 v0, 0xfffffc00, v0
	v_sub_u32_e32 v0, v1, v0
	v_lshrrev_b32_e32 v1, 4, v0
	v_bitop3_b32 v0, v1, v0, 32 bitop3:0x6c
	v_ashrrev_i32_e32 v3, 31, v0
	v_lshrrev_b32_e32 v3, 26, v3
	v_ashrrev_i32_e32 v2, 6, v2
	v_add_u32_e32 v3, v0, v3
	v_lshlrev_b32_e32 v1, 3, v2
	v_ashrrev_i32_e32 v4, 6, v3
	v_and_b32_e32 v3, 0xc0, v3
	v_and_b32_e32 v1, -16, v1
	v_lshlrev_b32_e32 v2, 5, v2
	v_sub_u32_e32 v0, v0, v3
	v_add_u32_e32 v1, v4, v1
	v_and_b32_e32 v2, 32, v2
	v_ashrrev_i16_sdwa v0, v205, sext(v0) dst_sel:DWORD dst_unused:UNUSED_PAD src0_sel:DWORD src1_sel:BYTE_0
	v_add_u32_sdwa v33, v2, sext(v0) dst_sel:DWORD dst_unused:UNUSED_PAD src0_sel:DWORD src1_sel:WORD_0
	v_lshlrev_b32_e32 v0, 1, v1
	v_lshrrev_b32_e32 v2, 2, v1
	v_and_b32_e32 v3, 3, v4
	s_mov_b32 s5, 0x7fffffe0
	v_and_b32_e32 v0, 24, v0
	v_and_b32_e32 v2, 4, v2
	v_and_or_b32 v3, v1, s5, v3
	v_or3_b32 v0, v3, v2, v0
	v_mul_lo_u32 v1, v1, s54
	v_add_u32_e32 v142, s93, v137
	v_add_u32_e32 v143, s8, v137
	v_add_lshl_u32 v136, v33, v1, 1
	v_mul_lo_u32 v34, v0, s54
	ds_read_b128 v[0:3], v142
	ds_read_b128 v[4:7], v142 offset:1024
	ds_read_b128 v[8:11], v142 offset:2048
	ds_read_b128 v[12:15], v142 offset:3072
	ds_read_b128 v[16:19], v143
	ds_read_b128 v[20:23], v143 offset:1024
	ds_read_b128 v[24:27], v143 offset:2048
	ds_read_b128 v[28:31], v143 offset:3072
	s_mov_b32 s86, 4
	s_lshl_b32 s34, s54, 7
	s_lshr_b32 s87, s71, 6
	s_lshl_b32 s82, s6, 1
	s_lshl_b32 s44, s54, 7
	v_add_lshl_u32 v138, v34, v33, 1
	s_add_u32 s10, s46, s82
	s_addc_u32 s11, s47, 0
	v_lshl_add_u64 v[124:125], s[10:11], 0, v[184:185]
	s_add_i32 s72, s14, 0xc000
	s_mov_b32 s7, s83
	v_add_u32_e32 v144, 0, v32
	v_lshl_add_u64 v[64:65], v[124:125], 0, s[84:85]
	s_mov_b32 m0, s72
	v_lshl_add_u64 v[126:127], v[124:125], 0, s[6:7]
	s_add_i32 s92, s14, 0xe000
	ds_read_b128 v[32:35], v144
	ds_read_b128 v[36:39], v144 offset:1024
	ds_read_b128 v[40:43], v144 offset:2048
	ds_read_b128 v[44:47], v144 offset:3072
	ds_read_b128 v[48:51], v144 offset:4096
	ds_read_b128 v[52:55], v144 offset:5120
	ds_read_b128 v[56:59], v144 offset:6144
	ds_read_b128 v[60:63], v144 offset:7168
	global_load_lds_dwordx4 v[64:65], off
	v_lshl_add_u64 v[64:65], v[126:127], 0, s[84:85]
	s_mov_b32 m0, s92
	s_nop 0
	global_load_lds_dwordx4 v[64:65], off
	s_waitcnt vmcnt(24)
	s_waitcnt lgkmcnt(0)
	s_barrier
	s_waitcnt lgkmcnt(0)
	v_mfma_f32_16x16x32_bf16 v[64:67], v[0:3], v[32:35], 0
	v_mfma_f32_16x16x32_bf16 v[68:71], v[8:11], v[32:35], 0
	v_mfma_f32_16x16x32_bf16 v[72:75], v[0:3], v[40:43], 0
	v_mfma_f32_16x16x32_bf16 v[76:79], v[8:11], v[40:43], 0
	v_mfma_f32_16x16x32_bf16 v[80:83], v[0:3], v[48:51], 0
	v_mfma_f32_16x16x32_bf16 v[84:87], v[8:11], v[48:51], 0
	v_mfma_f32_16x16x32_bf16 v[88:91], v[0:3], v[56:59], 0
	v_mfma_f32_16x16x32_bf16 v[92:95], v[8:11], v[56:59], 0
	v_mfma_f32_16x16x32_bf16 v[64:67], v[4:7], v[36:39], v[64:67]
	v_mfma_f32_16x16x32_bf16 v[68:71], v[12:15], v[36:39], v[68:71]
	v_mfma_f32_16x16x32_bf16 v[72:75], v[4:7], v[44:47], v[72:75]
	v_mfma_f32_16x16x32_bf16 v[76:79], v[12:15], v[44:47], v[76:79]
	v_mfma_f32_16x16x32_bf16 v[80:83], v[4:7], v[52:55], v[80:83]
	v_mfma_f32_16x16x32_bf16 v[84:87], v[12:15], v[52:55], v[84:87]
	v_mfma_f32_16x16x32_bf16 v[88:91], v[4:7], v[60:63], v[88:91]
	v_mfma_f32_16x16x32_bf16 v[92:95], v[12:15], v[60:63], v[92:95]
	v_mfma_f32_16x16x32_bf16 v[96:99], v[16:19], v[32:35], 0
	v_mfma_f32_16x16x32_bf16 v[32:35], v[24:27], v[32:35], 0
	v_mfma_f32_16x16x32_bf16 v[130:133], v[20:23], v[36:39], v[96:99]
	v_mfma_f32_16x16x32_bf16 v[32:35], v[28:31], v[36:39], v[32:35]
	v_mfma_f32_16x16x32_bf16 v[36:39], v[16:19], v[40:43], 0
	v_mfma_f32_16x16x32_bf16 v[40:43], v[24:27], v[40:43], 0
	v_mfma_f32_16x16x32_bf16 v[36:39], v[20:23], v[44:47], v[36:39]
	v_mfma_f32_16x16x32_bf16 v[40:43], v[28:31], v[44:47], v[40:43]
	v_mfma_f32_16x16x32_bf16 v[44:47], v[16:19], v[48:51], 0
	v_mfma_f32_16x16x32_bf16 v[48:51], v[24:27], v[48:51], 0
	v_mfma_f32_16x16x32_bf16 v[44:47], v[20:23], v[52:55], v[44:47]
	v_mfma_f32_16x16x32_bf16 v[52:55], v[28:31], v[52:55], v[48:51]
	v_mfma_f32_16x16x32_bf16 v[48:51], v[16:19], v[56:59], 0
	v_mfma_f32_16x16x32_bf16 v[148:151], v[20:23], v[60:63], v[48:51]
	v_mfma_f32_16x16x32_bf16 v[48:51], v[24:27], v[56:59], 0
	v_mfma_f32_16x16x32_bf16 v[56:59], v[28:31], v[60:63], v[48:51]
	s_barrier
	s_add_i32 s93, s93, s15
	v_mov_b32_e32 v129, v185
	s_add_i32 s10, s93, 0x2000
	s_lshl_b32 s50, s4, 1
	v_lshl_add_u64 v[134:135], s[48:49], 0, v[128:129]
	s_mov_b64 s[52:53], 0x100
	s_mov_b32 s5, s83
	s_add_u32 s16, s48, s50
	v_lshl_add_u64 v[120:121], v[134:135], 0, s[52:53]
	s_mov_b32 m0, s93
	v_lshl_add_u64 v[140:141], v[134:135], 0, s[4:5]
	s_addc_u32 s17, s49, 0
	ds_read_b128 v[48:51], v144 offset:16384
	ds_read_b128 v[60:63], v144 offset:17408
	ds_read_b128 v[96:99], v144 offset:18432
	ds_read_b128 v[100:103], v144 offset:19456
	ds_read_b128 v[104:107], v144 offset:20480
	ds_read_b128 v[108:111], v144 offset:21504
	ds_read_b128 v[112:115], v144 offset:22528
	ds_read_b128 v[116:119], v144 offset:23552
	global_load_lds_dwordx4 v[120:121], off
	v_lshl_add_u64 v[120:121], v[140:141], 0, s[52:53]
	s_mov_b32 m0, s10
	v_lshl_add_u64 v[186:187], s[16:17], 0, v[128:129]
	s_add_i32 s11, s8, s15
	global_load_lds_dwordx4 v[120:121], off
	v_lshl_add_u64 v[120:121], v[186:187], 0, s[52:53]
	s_mov_b32 m0, s11
	v_lshl_add_u64 v[206:207], v[186:187], 0, s[4:5]
	s_add_i32 s8, s11, 0x2000
	global_load_lds_dwordx4 v[120:121], off
	v_lshl_add_u64 v[120:121], v[206:207], 0, s[52:53]
	s_mov_b32 m0, s8
	v_lshl_add_u64 v[210:211], s[46:47], 0, v[184:185]
	global_load_lds_dwordx4 v[120:121], off
	v_lshl_add_u64 v[120:121], v[210:211], 0, s[52:53]
	s_mov_b32 m0, s14
	v_lshl_add_u64 v[252:253], v[210:211], 0, s[6:7]
	global_load_lds_dwordx4 v[120:121], off
	v_lshl_add_u64 v[120:121], v[252:253], 0, s[52:53]
	s_mov_b32 m0, s73
	s_mov_b32 s51, s83
	global_load_lds_dwordx4 v[120:121], off
	s_waitcnt vmcnt(24)
	s_waitcnt lgkmcnt(0)
	s_barrier
	s_waitcnt lgkmcnt(0)
	v_mfma_f32_16x16x32_bf16 v[120:123], v[0:3], v[48:51], 0
	v_mfma_f32_16x16x32_bf16 v[152:155], v[4:7], v[60:63], v[120:123]
	v_mfma_f32_16x16x32_bf16 v[120:123], v[8:11], v[48:51], 0
	v_mfma_f32_16x16x32_bf16 v[156:159], v[12:15], v[60:63], v[120:123]
	v_mfma_f32_16x16x32_bf16 v[120:123], v[0:3], v[96:99], 0
	v_mfma_f32_16x16x32_bf16 v[160:163], v[4:7], v[100:103], v[120:123]
	v_mfma_f32_16x16x32_bf16 v[120:123], v[8:11], v[96:99], 0
	v_mfma_f32_16x16x32_bf16 v[164:167], v[12:15], v[100:103], v[120:123]
	v_mfma_f32_16x16x32_bf16 v[120:123], v[0:3], v[104:107], 0
	v_mfma_f32_16x16x32_bf16 v[0:3], v[0:3], v[112:115], 0
	v_mfma_f32_16x16x32_bf16 v[168:171], v[4:7], v[108:111], v[120:123]
	v_mfma_f32_16x16x32_bf16 v[0:3], v[4:7], v[116:119], v[0:3]
	v_mfma_f32_16x16x32_bf16 v[4:7], v[8:11], v[112:115], 0
	v_mfma_f32_16x16x32_bf16 v[120:123], v[8:11], v[104:107], 0
	v_mfma_f32_16x16x32_bf16 v[4:7], v[12:15], v[116:119], v[4:7]
	v_mfma_f32_16x16x32_bf16 v[172:175], v[12:15], v[108:111], v[120:123]
	v_mfma_f32_16x16x32_bf16 v[8:11], v[16:19], v[48:51], 0
	v_mfma_f32_16x16x32_bf16 v[12:15], v[24:27], v[48:51], 0
	v_mfma_f32_16x16x32_bf16 v[48:51], v[16:19], v[96:99], 0
	v_mfma_f32_16x16x32_bf16 v[176:179], v[20:23], v[100:103], v[48:51]
	v_mfma_f32_16x16x32_bf16 v[48:51], v[24:27], v[96:99], 0
	v_mfma_f32_16x16x32_bf16 v[180:183], v[28:31], v[100:103], v[48:51]
	v_mfma_f32_16x16x32_bf16 v[48:51], v[16:19], v[104:107], 0
	v_mfma_f32_16x16x32_bf16 v[16:19], v[16:19], v[112:115], 0
	v_mfma_f32_16x16x32_bf16 v[8:11], v[20:23], v[60:63], v[8:11]
	v_mfma_f32_16x16x32_bf16 v[12:15], v[28:31], v[60:63], v[12:15]
	v_mfma_f32_16x16x32_bf16 v[188:191], v[20:23], v[108:111], v[48:51]
	v_mfma_f32_16x16x32_bf16 v[48:51], v[24:27], v[104:107], 0
	v_mfma_f32_16x16x32_bf16 v[196:199], v[20:23], v[116:119], v[16:19]
	v_mfma_f32_16x16x32_bf16 v[16:19], v[24:27], v[112:115], 0
	v_mfma_f32_16x16x32_bf16 v[192:195], v[28:31], v[108:111], v[48:51]
	v_mfma_f32_16x16x32_bf16 v[200:203], v[28:31], v[116:119], v[16:19]
	s_barrier
	s_add_i32 s16, 0, 0x18000
	s_add_i32 s24, 0, 0x1c000
	v_add_u32_e32 v145, s16, v137
	v_add_u32_e32 v146, s24, v137
	ds_read_b128 v[16:19], v145
	ds_read_b128 v[20:23], v145 offset:1024
	ds_read_b128 v[24:27], v145 offset:2048
	ds_read_b128 v[28:31], v145 offset:3072
	ds_read_b128 v[212:215], v146
	ds_read_b128 v[216:219], v146 offset:1024
	ds_read_b128 v[220:223], v146 offset:2048
	ds_read_b128 v[224:227], v146 offset:3072
	s_mov_b32 m0, s74
	v_lshl_add_u64 v[96:97], v[124:125], 0, s[52:53]
	ds_read_b128 v[48:51], v144 offset:32768
	ds_read_b128 v[60:63], v144 offset:33792
	ds_read_b128 v[228:231], v144 offset:34816
	ds_read_b128 v[232:235], v144 offset:35840
	ds_read_b128 v[236:239], v144 offset:36864
	ds_read_b128 v[240:243], v144 offset:37888
	ds_read_b128 v[244:247], v144 offset:38912
	ds_read_b128 v[248:251], v144 offset:39936
	global_load_lds_dwordx4 v[96:97], off
	v_lshl_add_u64 v[96:97], v[126:127], 0, s[52:53]
	s_mov_b32 m0, s75
	s_nop 0
	global_load_lds_dwordx4 v[96:97], off
	s_waitcnt vmcnt(8)
	s_waitcnt lgkmcnt(0)
	s_barrier
; #define PG8_WAIT_V(n) asm volatile("s_waitcnt vmcnt(" #n ")" ::: "memory")
; #define PG8_WAIT_VP() asm volatile("s_waitcnt vmcnt(%0)" :: "n"(8 + Epi::NST) : "memory")
; template <class Epi, class Sched>
; __device__ __forceinline__ void gemm_phase(PG8_LAS unsigned char* lds, const Sched& S, const Epi& E, int tid_in) {
;     ...
;         { const int t = 0; PG8_KITER(PG8_WAIT_VP()); }
;         for (int t = 2; t < nt; t += 2) PG8_KITER(PG8_WAIT_V(8));
	s_waitcnt lgkmcnt(0)
	v_mfma_f32_16x16x32_bf16 v[64:67], v[16:19], v[48:51], v[64:67]
	v_mfma_f32_16x16x32_bf16 v[120:123], v[20:23], v[60:63], v[64:67]
	v_mfma_f32_16x16x32_bf16 v[64:67], v[24:27], v[48:51], v[68:71]
	v_mfma_f32_16x16x32_bf16 v[124:127], v[28:31], v[60:63], v[64:67]
	v_mfma_f32_16x16x32_bf16 v[64:67], v[16:19], v[228:231], v[72:75]
	v_mfma_f32_16x16x32_bf16 v[112:115], v[20:23], v[232:235], v[64:67]
	v_mfma_f32_16x16x32_bf16 v[64:67], v[24:27], v[228:231], v[76:79]
	v_mfma_f32_16x16x32_bf16 v[116:119], v[28:31], v[232:235], v[64:67]
	v_mfma_f32_16x16x32_bf16 v[64:67], v[16:19], v[236:239], v[80:83]
	v_mfma_f32_16x16x32_bf16 v[104:107], v[20:23], v[240:243], v[64:67]
	v_mfma_f32_16x16x32_bf16 v[64:67], v[24:27], v[236:239], v[84:87]
	v_mfma_f32_16x16x32_bf16 v[108:111], v[28:31], v[240:243], v[64:67]
	v_mfma_f32_16x16x32_bf16 v[64:67], v[16:19], v[244:247], v[88:91]
	v_mfma_f32_16x16x32_bf16 v[96:99], v[20:23], v[248:251], v[64:67]
	v_mfma_f32_16x16x32_bf16 v[64:67], v[24:27], v[244:247], v[92:95]
	v_mfma_f32_16x16x32_bf16 v[100:103], v[28:31], v[248:251], v[64:67]
	v_mfma_f32_16x16x32_bf16 v[32:35], v[220:223], v[48:51], v[32:35]
	v_mfma_f32_16x16x32_bf16 v[64:67], v[212:215], v[48:51], v[130:133]
	v_mfma_f32_16x16x32_bf16 v[84:87], v[224:227], v[60:63], v[32:35]
	v_mfma_f32_16x16x32_bf16 v[32:35], v[212:215], v[228:231], v[36:39]
	v_mfma_f32_16x16x32_bf16 v[80:83], v[216:219], v[60:63], v[64:67]
	v_mfma_f32_16x16x32_bf16 v[64:67], v[216:219], v[232:235], v[32:35]
	v_mfma_f32_16x16x32_bf16 v[32:35], v[220:223], v[228:231], v[40:43]
	v_mfma_f32_16x16x32_bf16 v[68:71], v[224:227], v[232:235], v[32:35]
	v_mfma_f32_16x16x32_bf16 v[32:35], v[212:215], v[236:239], v[44:47]
	v_mfma_f32_16x16x32_bf16 v[48:51], v[216:219], v[240:243], v[32:35]
	v_mfma_f32_16x16x32_bf16 v[32:35], v[220:223], v[236:239], v[52:55]
	v_mfma_f32_16x16x32_bf16 v[52:55], v[224:227], v[240:243], v[32:35]
	v_mfma_f32_16x16x32_bf16 v[32:35], v[212:215], v[244:247], v[148:151]
	v_mfma_f32_16x16x32_bf16 v[36:39], v[220:223], v[244:247], v[56:59]
	v_mfma_f32_16x16x32_bf16 v[32:35], v[216:219], v[248:251], v[32:35]
	v_mfma_f32_16x16x32_bf16 v[36:39], v[224:227], v[248:251], v[36:39]
	s_barrier
	s_mov_b64 s[52:53], 0x180
	s_add_i32 s16, s16, s15
	v_lshl_add_u64 v[40:41], v[134:135], 0, s[52:53]
	s_mov_b32 m0, s16
	s_add_i32 s17, s16, 0x2000
	ds_read_b128 v[130:133], v144 offset:49152
	ds_read_b128 v[148:151], v144 offset:50176
	ds_read_b128 v[228:231], v144 offset:51200
	ds_read_b128 v[232:235], v144 offset:52224
	ds_read_b128 v[236:239], v144 offset:53248
	ds_read_b128 v[240:243], v144 offset:54272
	ds_read_b128 v[244:247], v144 offset:55296
	ds_read_b128 v[248:251], v144 offset:56320
	global_load_lds_dwordx4 v[40:41], off
	v_lshl_add_u64 v[40:41], v[140:141], 0, s[52:53]
	s_mov_b32 m0, s17
	s_add_i32 s24, s24, s15
	global_load_lds_dwordx4 v[40:41], off
	v_lshl_add_u64 v[40:41], v[186:187], 0, s[52:53]
	s_mov_b32 m0, s24
	s_add_i32 s25, s24, 0x2000
	global_load_lds_dwordx4 v[40:41], off
	v_lshl_add_u64 v[40:41], v[206:207], 0, s[52:53]
	s_mov_b32 m0, s25
	s_nop 0
	global_load_lds_dwordx4 v[40:41], off
	v_lshl_add_u64 v[40:41], v[210:211], 0, s[52:53]
	s_mov_b32 m0, s13
	s_nop 0
	global_load_lds_dwordx4 v[40:41], off
	v_lshl_add_u64 v[40:41], v[252:253], 0, s[52:53]
	s_mov_b32 m0, s76
	v_mov_b32_e32 v252, 0x3a27c5ac
	global_load_lds_dwordx4 v[40:41], off
	s_waitcnt vmcnt(8)
	s_waitcnt lgkmcnt(0)
	s_barrier
	s_waitcnt lgkmcnt(0)
	v_mfma_f32_16x16x32_bf16 v[40:43], v[16:19], v[130:133], v[152:155]
	v_mfma_f32_16x16x32_bf16 v[88:91], v[20:23], v[148:151], v[40:43]
	v_mfma_f32_16x16x32_bf16 v[40:43], v[24:27], v[130:133], v[156:159]
	v_mfma_f32_16x16x32_bf16 v[92:95], v[28:31], v[148:151], v[40:43]
	v_mfma_f32_16x16x32_bf16 v[40:43], v[16:19], v[228:231], v[160:163]
	v_mfma_f32_16x16x32_bf16 v[72:75], v[20:23], v[232:235], v[40:43]
	v_mfma_f32_16x16x32_bf16 v[40:43], v[24:27], v[228:231], v[164:167]
	v_mfma_f32_16x16x32_bf16 v[76:79], v[28:31], v[232:235], v[40:43]
	v_mfma_f32_16x16x32_bf16 v[40:43], v[16:19], v[236:239], v[168:171]
	v_mfma_f32_16x16x32_bf16 v[56:59], v[20:23], v[240:243], v[40:43]
	v_mfma_f32_16x16x32_bf16 v[40:43], v[24:27], v[236:239], v[172:175]
	v_mfma_f32_16x16x32_bf16 v[0:3], v[16:19], v[244:247], v[0:3]
	v_mfma_f32_16x16x32_bf16 v[60:63], v[28:31], v[240:243], v[40:43]
	v_mfma_f32_16x16x32_bf16 v[40:43], v[20:23], v[248:251], v[0:3]
	v_mfma_f32_16x16x32_bf16 v[0:3], v[24:27], v[244:247], v[4:7]
	v_mfma_f32_16x16x32_bf16 v[44:47], v[28:31], v[248:251], v[0:3]
	v_mfma_f32_16x16x32_bf16 v[0:3], v[212:215], v[130:133], v[8:11]
	v_mfma_f32_16x16x32_bf16 v[24:27], v[216:219], v[148:151], v[0:3]
	v_mfma_f32_16x16x32_bf16 v[0:3], v[220:223], v[130:133], v[12:15]
	v_mfma_f32_16x16x32_bf16 v[28:31], v[224:227], v[148:151], v[0:3]
	v_mfma_f32_16x16x32_bf16 v[0:3], v[212:215], v[228:231], v[176:179]
	v_mfma_f32_16x16x32_bf16 v[16:19], v[216:219], v[232:235], v[0:3]
	v_mfma_f32_16x16x32_bf16 v[0:3], v[220:223], v[228:231], v[180:183]
	v_mfma_f32_16x16x32_bf16 v[20:23], v[224:227], v[232:235], v[0:3]
	v_mfma_f32_16x16x32_bf16 v[0:3], v[212:215], v[236:239], v[188:191]
	v_mfma_f32_16x16x32_bf16 v[8:11], v[216:219], v[240:243], v[0:3]
	v_mfma_f32_16x16x32_bf16 v[0:3], v[220:223], v[236:239], v[192:195]
	v_mfma_f32_16x16x32_bf16 v[12:15], v[224:227], v[240:243], v[0:3]
	v_mfma_f32_16x16x32_bf16 v[0:3], v[212:215], v[244:247], v[196:199]
	v_mfma_f32_16x16x32_bf16 v[4:7], v[220:223], v[244:247], v[200:203]
	v_mfma_f32_16x16x32_bf16 v[0:3], v[216:219], v[248:251], v[0:3]
	v_mfma_f32_16x16x32_bf16 v[4:7], v[224:227], v[248:251], v[4:7]
	s_barrier
	s_lshl_b32 s52, s54, 8
	s_lshl_b32 s54, s54, 8
	s_add_u32 s46, s46, 0x180
	s_addc_u32 s47, s47, 0
	s_add_u32 s48, s48, 0x200
	v_mov_b32_e32 v137, v185
	s_mov_b32 s35, s83
	s_mov_b32 s53, s83
	v_mov_b32_e32 v139, v185
	s_mov_b32 s45, s83
	s_mov_b32 s55, s83
	s_addc_u32 s49, s49, 0
	v_lshl_add_u64 v[130:131], s[82:83], 0, v[184:185]
	v_mad_u64_u32 v[132:133], s[56:57], s6, 3, v[184:185]

.LBB0_1276:
	ds_read_b128 v[148:151], v142
	ds_read_b128 v[152:155], v142 offset:1024
	ds_read_b128 v[156:159], v142 offset:2048
	ds_read_b128 v[160:163], v142 offset:3072
	ds_read_b128 v[164:167], v143
	ds_read_b128 v[168:171], v143 offset:1024
	ds_read_b128 v[172:175], v143 offset:2048
	ds_read_b128 v[176:179], v143 offset:3072
	s_add_u32 s68, s46, 0x80
	s_addc_u32 vcc_lo, s47, 0
	s_and_b64 s[60:61], exec, s[60:61]
	s_cselect_b32 s61, s27, vcc_lo
	s_cselect_b32 s60, s26, s68
	s_mov_b32 m0, s72
	v_lshl_add_u64 v[186:187], s[46:47], 0, v[130:131]
	ds_read_b128 v[180:183], v144
	ds_read_b128 v[188:191], v144 offset:1024
	ds_read_b128 v[192:195], v144 offset:2048
	ds_read_b128 v[196:199], v144 offset:3072
	ds_read_b128 v[200:203], v144 offset:4096
	ds_read_b128 v[212:215], v144 offset:5120
	ds_read_b128 v[216:219], v144 offset:6144
	ds_read_b128 v[220:223], v144 offset:7168
	global_load_lds_dwordx4 v[186:187], off
	v_lshl_add_u64 v[186:187], s[46:47], 0, v[132:133]
	s_mov_b32 m0, s92
	s_nop 0
	global_load_lds_dwordx4 v[186:187], off
	s_waitcnt vmcnt(8)
	s_waitcnt lgkmcnt(0)
	s_barrier
	s_waitcnt lgkmcnt(0)
	v_mfma_f32_16x16x32_bf16 v[120:123], v[148:151], v[180:183], v[120:123]
	v_mfma_f32_16x16x32_bf16 v[124:127], v[156:159], v[180:183], v[124:127]
	v_mfma_f32_16x16x32_bf16 v[112:115], v[148:151], v[192:195], v[112:115]
	v_mfma_f32_16x16x32_bf16 v[116:119], v[156:159], v[192:195], v[116:119]
	v_mfma_f32_16x16x32_bf16 v[104:107], v[148:151], v[200:203], v[104:107]
	v_mfma_f32_16x16x32_bf16 v[108:111], v[156:159], v[200:203], v[108:111]
	v_mfma_f32_16x16x32_bf16 v[96:99], v[148:151], v[216:219], v[96:99]
	v_mfma_f32_16x16x32_bf16 v[100:103], v[156:159], v[216:219], v[100:103]
	v_mfma_f32_16x16x32_bf16 v[120:123], v[152:155], v[188:191], v[120:123]
	v_mfma_f32_16x16x32_bf16 v[124:127], v[160:163], v[188:191], v[124:127]
	v_mfma_f32_16x16x32_bf16 v[112:115], v[152:155], v[196:199], v[112:115]
	v_mfma_f32_16x16x32_bf16 v[116:119], v[160:163], v[196:199], v[116:119]
	v_mfma_f32_16x16x32_bf16 v[104:107], v[152:155], v[212:215], v[104:107]
	v_mfma_f32_16x16x32_bf16 v[108:111], v[160:163], v[212:215], v[108:111]
	v_mfma_f32_16x16x32_bf16 v[96:99], v[152:155], v[220:223], v[96:99]
	v_mfma_f32_16x16x32_bf16 v[100:103], v[160:163], v[220:223], v[100:103]
	v_mfma_f32_16x16x32_bf16 v[80:83], v[164:167], v[180:183], v[80:83]
	v_mfma_f32_16x16x32_bf16 v[84:87], v[172:175], v[180:183], v[84:87]
	v_mfma_f32_16x16x32_bf16 v[64:67], v[164:167], v[192:195], v[64:67]
	v_mfma_f32_16x16x32_bf16 v[68:71], v[172:175], v[192:195], v[68:71]
	v_mfma_f32_16x16x32_bf16 v[48:51], v[164:167], v[200:203], v[48:51]
	v_mfma_f32_16x16x32_bf16 v[52:55], v[172:175], v[200:203], v[52:55]
	v_mfma_f32_16x16x32_bf16 v[32:35], v[164:167], v[216:219], v[32:35]
	v_mfma_f32_16x16x32_bf16 v[36:39], v[172:175], v[216:219], v[36:39]
	v_mfma_f32_16x16x32_bf16 v[80:83], v[168:171], v[188:191], v[80:83]
	v_mfma_f32_16x16x32_bf16 v[84:87], v[176:179], v[188:191], v[84:87]
	v_mfma_f32_16x16x32_bf16 v[64:67], v[168:171], v[196:199], v[64:67]
	v_mfma_f32_16x16x32_bf16 v[68:71], v[176:179], v[196:199], v[68:71]
	v_mfma_f32_16x16x32_bf16 v[48:51], v[168:171], v[212:215], v[48:51]
	v_mfma_f32_16x16x32_bf16 v[52:55], v[176:179], v[212:215], v[52:55]
	v_mfma_f32_16x16x32_bf16 v[32:35], v[168:171], v[220:223], v[32:35]
	v_mfma_f32_16x16x32_bf16 v[36:39], v[176:179], v[220:223], v[36:39]
	s_barrier
	s_mov_b32 m0, s93
	v_lshl_add_u64 v[186:187], s[66:67], 0, v[140:141]
	s_add_u32 s64, s66, s64
	ds_read_b128 v[180:183], v144 offset:16384
	ds_read_b128 v[188:191], v144 offset:17408
	ds_read_b128 v[192:195], v144 offset:18432
	ds_read_b128 v[196:199], v144 offset:19456
	ds_read_b128 v[200:203], v144 offset:20480
	ds_read_b128 v[212:215], v144 offset:21504
	ds_read_b128 v[216:219], v144 offset:22528
	ds_read_b128 v[220:223], v144 offset:23552
	global_load_lds_dwordx4 v[186:187], off
	v_lshl_add_u64 v[206:207], v[186:187], 0, s[62:63]
	s_mov_b32 m0, s10
	s_addc_u32 s65, s67, s65
	global_load_lds_dwordx4 v[206:207], off
	v_lshl_add_u64 v[140:141], s[64:65], 0, v[140:141]
	s_mov_b32 m0, s11
	v_lshl_add_u64 v[210:211], v[140:141], 0, s[62:63]
	global_load_lds_dwordx4 v[140:141], off
	s_mov_b32 m0, s8
	v_lshl_add_u64 v[224:225], s[60:61], 0, v[134:135]
	global_load_lds_dwordx4 v[210:211], off
	s_mov_b32 m0, s14
	v_lshl_add_u64 v[226:227], v[224:225], 0, s[56:57]
	global_load_lds_dwordx4 v[224:225], off
	s_mov_b32 m0, s73
	s_nop 0
	global_load_lds_dwordx4 v[226:227], off
	s_waitcnt vmcnt(8)
	s_waitcnt lgkmcnt(0)
	s_barrier
	s_waitcnt lgkmcnt(0)
	v_mfma_f32_16x16x32_bf16 v[88:91], v[148:151], v[180:183], v[88:91]
	v_mfma_f32_16x16x32_bf16 v[92:95], v[156:159], v[180:183], v[92:95]
	v_mfma_f32_16x16x32_bf16 v[72:75], v[148:151], v[192:195], v[72:75]
	v_mfma_f32_16x16x32_bf16 v[76:79], v[156:159], v[192:195], v[76:79]
	v_mfma_f32_16x16x32_bf16 v[56:59], v[148:151], v[200:203], v[56:59]
	v_mfma_f32_16x16x32_bf16 v[60:63], v[156:159], v[200:203], v[60:63]
	v_mfma_f32_16x16x32_bf16 v[40:43], v[148:151], v[216:219], v[40:43]
	v_mfma_f32_16x16x32_bf16 v[44:47], v[156:159], v[216:219], v[44:47]
	v_mfma_f32_16x16x32_bf16 v[88:91], v[152:155], v[188:191], v[88:91]
	v_mfma_f32_16x16x32_bf16 v[92:95], v[160:163], v[188:191], v[92:95]
	v_mfma_f32_16x16x32_bf16 v[72:75], v[152:155], v[196:199], v[72:75]
	v_mfma_f32_16x16x32_bf16 v[76:79], v[160:163], v[196:199], v[76:79]
	v_mfma_f32_16x16x32_bf16 v[56:59], v[152:155], v[212:215], v[56:59]
	v_mfma_f32_16x16x32_bf16 v[60:63], v[160:163], v[212:215], v[60:63]
	v_mfma_f32_16x16x32_bf16 v[40:43], v[152:155], v[220:223], v[40:43]
	v_mfma_f32_16x16x32_bf16 v[44:47], v[160:163], v[220:223], v[44:47]
	v_mfma_f32_16x16x32_bf16 v[24:27], v[164:167], v[180:183], v[24:27]
	v_mfma_f32_16x16x32_bf16 v[28:31], v[172:175], v[180:183], v[28:31]
	v_mfma_f32_16x16x32_bf16 v[16:19], v[164:167], v[192:195], v[16:19]
	v_mfma_f32_16x16x32_bf16 v[20:23], v[172:175], v[192:195], v[20:23]
	v_mfma_f32_16x16x32_bf16 v[8:11], v[164:167], v[200:203], v[8:11]
	v_mfma_f32_16x16x32_bf16 v[12:15], v[172:175], v[200:203], v[12:15]
	v_mfma_f32_16x16x32_bf16 v[0:3], v[164:167], v[216:219], v[0:3]
	v_mfma_f32_16x16x32_bf16 v[4:7], v[172:175], v[216:219], v[4:7]
	v_mfma_f32_16x16x32_bf16 v[24:27], v[168:171], v[188:191], v[24:27]
	v_mfma_f32_16x16x32_bf16 v[28:31], v[176:179], v[188:191], v[28:31]
	v_mfma_f32_16x16x32_bf16 v[16:19], v[168:171], v[196:199], v[16:19]
	v_mfma_f32_16x16x32_bf16 v[20:23], v[176:179], v[196:199], v[20:23]
	v_mfma_f32_16x16x32_bf16 v[8:11], v[168:171], v[212:215], v[8:11]
	v_mfma_f32_16x16x32_bf16 v[12:15], v[176:179], v[212:215], v[12:15]
	v_mfma_f32_16x16x32_bf16 v[0:3], v[168:171], v[220:223], v[0:3]
	v_mfma_f32_16x16x32_bf16 v[4:7], v[176:179], v[220:223], v[4:7]
	s_barrier
	ds_read_b128 v[148:151], v145
	ds_read_b128 v[152:155], v145 offset:1024
	ds_read_b128 v[156:159], v145 offset:2048
	ds_read_b128 v[160:163], v145 offset:3072
	ds_read_b128 v[164:167], v146
	ds_read_b128 v[168:171], v146 offset:1024
	ds_read_b128 v[172:175], v146 offset:2048
	ds_read_b128 v[176:179], v146 offset:3072
	s_add_u32 s58, s60, s58
	s_addc_u32 s59, s61, s59
	s_mov_b32 m0, s74
	v_lshl_add_u64 v[134:135], s[58:59], 0, v[134:135]
	ds_read_b128 v[180:183], v144 offset:32768
	ds_read_b128 v[188:191], v144 offset:33792
	ds_read_b128 v[192:195], v144 offset:34816
	ds_read_b128 v[196:199], v144 offset:35840
	ds_read_b128 v[200:203], v144 offset:36864
	ds_read_b128 v[212:215], v144 offset:37888
	ds_read_b128 v[216:219], v144 offset:38912
	ds_read_b128 v[220:223], v144 offset:39936
	global_load_lds_dwordx4 v[134:135], off
	v_lshl_add_u64 v[134:135], v[134:135], 0, s[56:57]
	s_mov_b32 m0, s75
	s_nop 0
	global_load_lds_dwordx4 v[134:135], off
	s_waitcnt vmcnt(8)
	s_waitcnt lgkmcnt(0)
	s_barrier
	s_waitcnt lgkmcnt(0)
	v_mfma_f32_16x16x32_bf16 v[120:123], v[148:151], v[180:183], v[120:123]
	v_mfma_f32_16x16x32_bf16 v[124:127], v[156:159], v[180:183], v[124:127]
	v_mfma_f32_16x16x32_bf16 v[112:115], v[148:151], v[192:195], v[112:115]
	v_mfma_f32_16x16x32_bf16 v[116:119], v[156:159], v[192:195], v[116:119]
	v_mfma_f32_16x16x32_bf16 v[104:107], v[148:151], v[200:203], v[104:107]
	v_mfma_f32_16x16x32_bf16 v[108:111], v[156:159], v[200:203], v[108:111]
	v_mfma_f32_16x16x32_bf16 v[96:99], v[148:151], v[216:219], v[96:99]
	v_mfma_f32_16x16x32_bf16 v[100:103], v[156:159], v[216:219], v[100:103]
	v_mfma_f32_16x16x32_bf16 v[120:123], v[152:155], v[188:191], v[120:123]
	v_mfma_f32_16x16x32_bf16 v[124:127], v[160:163], v[188:191], v[124:127]
	v_mfma_f32_16x16x32_bf16 v[112:115], v[152:155], v[196:199], v[112:115]
	v_mfma_f32_16x16x32_bf16 v[116:119], v[160:163], v[196:199], v[116:119]
	v_mfma_f32_16x16x32_bf16 v[104:107], v[152:155], v[212:215], v[104:107]
	v_mfma_f32_16x16x32_bf16 v[108:111], v[160:163], v[212:215], v[108:111]
	v_mfma_f32_16x16x32_bf16 v[96:99], v[152:155], v[220:223], v[96:99]
	v_mfma_f32_16x16x32_bf16 v[100:103], v[160:163], v[220:223], v[100:103]
	v_mfma_f32_16x16x32_bf16 v[80:83], v[164:167], v[180:183], v[80:83]
	v_mfma_f32_16x16x32_bf16 v[84:87], v[172:175], v[180:183], v[84:87]
	v_mfma_f32_16x16x32_bf16 v[64:67], v[164:167], v[192:195], v[64:67]
	v_mfma_f32_16x16x32_bf16 v[68:71], v[172:175], v[192:195], v[68:71]
	v_mfma_f32_16x16x32_bf16 v[48:51], v[164:167], v[200:203], v[48:51]
	v_mfma_f32_16x16x32_bf16 v[52:55], v[172:175], v[200:203], v[52:55]
	v_mfma_f32_16x16x32_bf16 v[32:35], v[164:167], v[216:219], v[32:35]
	v_mfma_f32_16x16x32_bf16 v[36:39], v[172:175], v[216:219], v[36:39]
	v_mfma_f32_16x16x32_bf16 v[80:83], v[168:171], v[188:191], v[80:83]
	v_mfma_f32_16x16x32_bf16 v[84:87], v[176:179], v[188:191], v[84:87]
	v_mfma_f32_16x16x32_bf16 v[64:67], v[168:171], v[196:199], v[64:67]
	v_mfma_f32_16x16x32_bf16 v[68:71], v[176:179], v[196:199], v[68:71]
	v_mfma_f32_16x16x32_bf16 v[48:51], v[168:171], v[212:215], v[48:51]
	v_mfma_f32_16x16x32_bf16 v[52:55], v[176:179], v[212:215], v[52:55]
	v_mfma_f32_16x16x32_bf16 v[32:35], v[168:171], v[220:223], v[32:35]
	v_mfma_f32_16x16x32_bf16 v[36:39], v[176:179], v[220:223], v[36:39]
	s_barrier
; #define PG8_WAIT_V(n) asm volatile("s_waitcnt vmcnt(" #n ")" ::: "memory")
; #define PG8_WAIT_VP() asm volatile("s_waitcnt vmcnt(%0)" :: "n"(8 + Epi::NST) : "memory")
; template <class Epi, class Sched>
; __device__ __forceinline__ void gemm_phase(PG8_LAS unsigned char* lds, const Sched& S, const Epi& E, int tid_in) {
;     ...
;         { const int t = 0; PG8_KITER(PG8_WAIT_VP()); }
;         for (int t = 2; t < nt; t += 2) PG8_KITER(PG8_WAIT_V(8));
	s_mov_b32 m0, s16
	v_lshl_add_u64 v[134:135], v[186:187], 0, s[84:85]
	ds_read_b128 v[180:183], v144 offset:49152
	ds_read_b128 v[188:191], v144 offset:50176
	ds_read_b128 v[192:195], v144 offset:51200
	ds_read_b128 v[196:199], v144 offset:52224
	ds_read_b128 v[200:203], v144 offset:53248
	ds_read_b128 v[212:215], v144 offset:54272
	ds_read_b128 v[216:219], v144 offset:55296
	ds_read_b128 v[220:223], v144 offset:56320
	global_load_lds_dwordx4 v[134:135], off
	v_lshl_add_u64 v[134:135], v[206:207], 0, s[84:85]
	s_mov_b32 m0, s17
	s_nop 0
	global_load_lds_dwordx4 v[134:135], off
	v_lshl_add_u64 v[134:135], v[140:141], 0, s[84:85]
	s_mov_b32 m0, s24
	s_nop 0
	global_load_lds_dwordx4 v[134:135], off
	v_lshl_add_u64 v[134:135], v[210:211], 0, s[84:85]
	s_mov_b32 m0, s25
	s_nop 0
	global_load_lds_dwordx4 v[134:135], off
	v_lshl_add_u64 v[134:135], v[224:225], 0, s[84:85]
	s_mov_b32 m0, s13
	s_nop 0
	global_load_lds_dwordx4 v[134:135], off
	v_lshl_add_u64 v[134:135], v[226:227], 0, s[84:85]
	s_mov_b32 m0, s76
	s_nop 0
	global_load_lds_dwordx4 v[134:135], off
	s_waitcnt vmcnt(8)
	s_waitcnt lgkmcnt(0)
	s_barrier
	s_waitcnt lgkmcnt(0)
	v_mfma_f32_16x16x32_bf16 v[88:91], v[148:151], v[180:183], v[88:91]
	v_mfma_f32_16x16x32_bf16 v[92:95], v[156:159], v[180:183], v[92:95]
	v_mfma_f32_16x16x32_bf16 v[72:75], v[148:151], v[192:195], v[72:75]
	v_mfma_f32_16x16x32_bf16 v[76:79], v[156:159], v[192:195], v[76:79]
	v_mfma_f32_16x16x32_bf16 v[56:59], v[148:151], v[200:203], v[56:59]
	v_mfma_f32_16x16x32_bf16 v[60:63], v[156:159], v[200:203], v[60:63]
	v_mfma_f32_16x16x32_bf16 v[40:43], v[148:151], v[216:219], v[40:43]
	v_mfma_f32_16x16x32_bf16 v[44:47], v[156:159], v[216:219], v[44:47]
	v_mfma_f32_16x16x32_bf16 v[88:91], v[152:155], v[188:191], v[88:91]
	v_mfma_f32_16x16x32_bf16 v[92:95], v[160:163], v[188:191], v[92:95]
	v_mfma_f32_16x16x32_bf16 v[72:75], v[152:155], v[196:199], v[72:75]
	v_mfma_f32_16x16x32_bf16 v[76:79], v[160:163], v[196:199], v[76:79]
	v_mfma_f32_16x16x32_bf16 v[56:59], v[152:155], v[212:215], v[56:59]
	v_mfma_f32_16x16x32_bf16 v[60:63], v[160:163], v[212:215], v[60:63]
	v_mfma_f32_16x16x32_bf16 v[40:43], v[152:155], v[220:223], v[40:43]
	v_mfma_f32_16x16x32_bf16 v[44:47], v[160:163], v[220:223], v[44:47]
	v_mfma_f32_16x16x32_bf16 v[24:27], v[164:167], v[180:183], v[24:27]
	v_mfma_f32_16x16x32_bf16 v[28:31], v[172:175], v[180:183], v[28:31]
	v_mfma_f32_16x16x32_bf16 v[16:19], v[164:167], v[192:195], v[16:19]
	v_mfma_f32_16x16x32_bf16 v[20:23], v[172:175], v[192:195], v[20:23]
	v_mfma_f32_16x16x32_bf16 v[8:11], v[164:167], v[200:203], v[8:11]
	v_mfma_f32_16x16x32_bf16 v[12:15], v[172:175], v[200:203], v[12:15]
	v_mfma_f32_16x16x32_bf16 v[0:3], v[164:167], v[216:219], v[0:3]
	v_mfma_f32_16x16x32_bf16 v[4:7], v[172:175], v[216:219], v[4:7]
	v_mfma_f32_16x16x32_bf16 v[24:27], v[168:171], v[188:191], v[24:27]
	v_mfma_f32_16x16x32_bf16 v[28:31], v[176:179], v[188:191], v[28:31]
	v_mfma_f32_16x16x32_bf16 v[16:19], v[168:171], v[196:199], v[16:19]
	v_mfma_f32_16x16x32_bf16 v[20:23], v[176:179], v[196:199], v[20:23]
	v_mfma_f32_16x16x32_bf16 v[8:11], v[168:171], v[212:215], v[8:11]
	v_mfma_f32_16x16x32_bf16 v[12:15], v[176:179], v[212:215], v[12:15]
	v_mfma_f32_16x16x32_bf16 v[0:3], v[168:171], v[220:223], v[0:3]
	v_mfma_f32_16x16x32_bf16 v[4:7], v[176:179], v[220:223], v[4:7]
	s_barrier
	s_add_i32 s56, s86, 2
	s_add_u32 s46, s46, 0x100
	s_addc_u32 s47, s47, 0
	s_add_u32 s48, s48, 0x100
	s_addc_u32 s49, s49, 0
	s_cmp_ge_u32 s86, s87
	s_cbranch_scc1 .LBB0_1278
	s_mov_b32 s86, s56
	s_branch .LBB0_1274

; __device__ __forceinline__ int lane_id() { int l; asm volatile("v_mbcnt_lo_u32_b32 %0, -1, 0\n\tv_mbcnt_hi_u32_b32 %0, -1, %0" : "=v"(l)); return l; }
;     __device__ __forceinline__ bool next(int i, UnitG& u) const { if (!P.next(i, u)) return false; u.O = O + ((size_t)u.x0 * 256 * 2048 + (size_t)u.x1 * 256) * 2; u.ldo = 2048; u.kind = 0; return true; }
; template <class Epi, class Sched>
; __device__ __forceinline__ void gemm_phase(PG8_LAS unsigned char* lds, const Sched& S, const Epi& E, int tid_in) {
;     ...
;         int aoff, boff; { const int l3 = lane_id(), fr3 = l3 & 15, fq3 = l3 >> 4; aoff = lds_byte(wr * 64 + fr3, fq3 * 8); boff = lds_byte(wc * 32 + fr3, fq3 * 8); }
;         const bool has_next = S.next(ui + 1, nxt);
;         const char* nA = has_next ? nxt.A : cA; const char* nB = has_next ? nxt.B : cB;
;         const int nlda = has_next ? nxt.lda : cur.lda, nldb = has_next ? nxt.ldb : cur.ldb;
;         unsigned nvA, nvB; { int r2, c2; stage_rc((wid * 64 + lane_id()) * 16, r2, c2); const int rb2 = Epi::PERM ? ((r2 & ~31) + perm32(r2 & 31)) : r2;
;             nvA = (unsigned)(r2 * nlda + c2) * 2u; nvB = (unsigned)(rb2 * nldb + c2) * 2u; }
;         const unsigned nqA = (unsigned)nlda * 128u, nqB = (unsigned)nldb * 128u;
;         const int nt = cur.K / BK;
.LBB0_1445:
	v_and_b32_e32 v1, 15, v0
	v_or_b32_e32 v2, s46, v1
	v_ashrrev_i32_e32 v3, 6, v0
	v_lshlrev_b32_e32 v4, 6, v2
	v_and_b32_e32 v5, 48, v0
	s_movk_i32 s53, 0x3c0
	v_lshlrev_b32_e32 v2, 2, v2
	v_and_or_b32 v4, v4, s53, v5
	v_lshl_add_u32 v6, v3, 10, s47
	v_and_b32_e32 v2, 32, v2
	v_lshlrev_b32_e32 v0, 2, v0
	s_waitcnt vmcnt(0)
	v_bitop3_b32 v32, v4, v6, v2 bitop3:0xde
	v_lshl_or_b32 v1, v1, 6, v5
	v_add_lshl_u32 v2, v3, s49, 10
	v_and_b32_e32 v0, 32, v0
	v_bitop3_b32 v119, v1, v2, v0 bitop3:0xde
	v_mbcnt_lo_u32_b32 v0, -1, 0
	v_mbcnt_hi_u32_b32 v0, -1, v0
	s_mov_b32 s53, 0xfffe0
	v_add_u32_e32 v0, s50, v0
	v_ashrrev_i32_e32 v2, 31, v0
	v_lshrrev_b32_e32 v2, 26, v2
	v_lshlrev_b32_e32 v1, 4, v0
	v_add_u32_e32 v2, v0, v2
	v_bfe_i32 v0, v0, 27, 1
	v_lshrrev_b32_e32 v0, 22, v0
	v_add_u32_e32 v0, v1, v0
	v_and_b32_e32 v0, 0xfffffc00, v0
	v_sub_u32_e32 v0, v1, v0
	v_lshrrev_b32_e32 v1, 4, v0
	v_bitop3_b32 v0, v1, v0, 32 bitop3:0x6c
	v_ashrrev_i32_e32 v3, 31, v0
	v_lshrrev_b32_e32 v3, 26, v3
	v_ashrrev_i32_e32 v2, 6, v2
	v_add_u32_e32 v3, v0, v3
	v_lshlrev_b32_e32 v1, 3, v2
	v_ashrrev_i32_e32 v4, 6, v3
	v_and_b32_e32 v3, 0xc0, v3
	v_and_b32_e32 v1, -16, v1
	v_sub_u32_e32 v0, v0, v3
	v_add_u32_e32 v1, v4, v1
	v_lshlrev_b32_e32 v2, 5, v2
	v_ashrrev_i16_sdwa v0, v205, sext(v0) dst_sel:DWORD dst_unused:UNUSED_PAD src0_sel:DWORD src1_sel:BYTE_0
	v_and_b32_e32 v2, 32, v2
	v_bfe_i32 v0, v0, 0, 16
	v_lshlrev_b32_e32 v3, 1, v1
	v_lshrrev_b32_e32 v5, 2, v1
	v_and_b32_e32 v4, 3, v4
	s_add_i32 s55, 0, 0x10000
	s_add_i32 s57, 0, 0x14000
	v_and_b32_e32 v3, 24, v3
	v_and_b32_e32 v5, 4, v5
	v_and_or_b32 v4, v1, s53, v4
	v_add_lshl_u32 v34, v2, v0, 1
	v_add_u32_e32 v116, s55, v119
	v_add_u32_e32 v117, s57, v119
	v_or3_b32 v33, v4, v5, v3
	v_lshl_add_u32 v186, v1, 12, v34
	ds_read_b128 v[0:3], v116
	ds_read_b128 v[4:7], v116 offset:1024
	ds_read_b128 v[8:11], v116 offset:2048
	ds_read_b128 v[12:15], v116 offset:3072
	ds_read_b128 v[16:19], v117
	ds_read_b128 v[20:23], v117 offset:1024
	ds_read_b128 v[24:27], v117 offset:2048
	ds_read_b128 v[28:31], v117 offset:3072
	v_lshl_add_u32 v211, v33, 12, v34
	v_mov_b32_e32 v115, v185
	v_lshl_add_u64 v[206:207], s[20:21], 0, v[114:115]
	s_add_i32 s53, s7, 0xc000
	v_add_u32_e32 v118, 0, v32
	v_lshl_add_u64 v[64:65], v[206:207], 0, s[80:81]
	s_mov_b32 m0, s53
	s_add_i32 s54, s7, 0xe000
	ds_read_b128 v[32:35], v118
	ds_read_b128 v[36:39], v118 offset:1024
	ds_read_b128 v[40:43], v118 offset:2048
	ds_read_b128 v[44:47], v118 offset:3072
	ds_read_b128 v[48:51], v118 offset:4096
	ds_read_b128 v[52:55], v118 offset:5120
	ds_read_b128 v[56:59], v118 offset:6144
	ds_read_b128 v[60:63], v118 offset:7168
	global_load_lds_dwordx4 v[64:65], off
	v_lshl_add_u64 v[64:65], v[206:207], 0, s[78:79]
	s_mov_b32 m0, s54
	s_nop 0
	global_load_lds_dwordx4 v[64:65], off
	s_waitcnt vmcnt(24)
	s_waitcnt lgkmcnt(0)
	s_barrier
	s_waitcnt lgkmcnt(0)
	v_mfma_f32_16x16x32_bf16 v[88:91], v[0:3], v[56:59], 0
	v_mfma_f32_16x16x32_bf16 v[64:67], v[0:3], v[32:35], 0
	v_mfma_f32_16x16x32_bf16 v[68:71], v[8:11], v[32:35], 0
	v_mfma_f32_16x16x32_bf16 v[72:75], v[0:3], v[40:43], 0
	v_mfma_f32_16x16x32_bf16 v[76:79], v[8:11], v[40:43], 0
	v_mfma_f32_16x16x32_bf16 v[80:83], v[0:3], v[48:51], 0
	v_mfma_f32_16x16x32_bf16 v[84:87], v[8:11], v[48:51], 0
	v_mfma_f32_16x16x32_bf16 v[96:99], v[4:7], v[60:63], v[88:91]
	v_mfma_f32_16x16x32_bf16 v[88:91], v[8:11], v[56:59], 0
	v_mfma_f32_16x16x32_bf16 v[64:67], v[4:7], v[36:39], v[64:67]
	v_mfma_f32_16x16x32_bf16 v[68:71], v[12:15], v[36:39], v[68:71]
	v_mfma_f32_16x16x32_bf16 v[72:75], v[4:7], v[44:47], v[72:75]
	v_mfma_f32_16x16x32_bf16 v[76:79], v[12:15], v[44:47], v[76:79]
	v_mfma_f32_16x16x32_bf16 v[80:83], v[4:7], v[52:55], v[80:83]
	v_mfma_f32_16x16x32_bf16 v[84:87], v[12:15], v[52:55], v[84:87]
	v_mfma_f32_16x16x32_bf16 v[100:103], v[12:15], v[60:63], v[88:91]
	v_mfma_f32_16x16x32_bf16 v[88:91], v[16:19], v[32:35], 0
	v_mfma_f32_16x16x32_bf16 v[32:35], v[24:27], v[32:35], 0
	v_mfma_f32_16x16x32_bf16 v[120:123], v[20:23], v[36:39], v[88:91]
	v_mfma_f32_16x16x32_bf16 v[32:35], v[28:31], v[36:39], v[32:35]
	v_mfma_f32_16x16x32_bf16 v[36:39], v[16:19], v[40:43], 0
	v_mfma_f32_16x16x32_bf16 v[40:43], v[24:27], v[40:43], 0
	v_mfma_f32_16x16x32_bf16 v[36:39], v[20:23], v[44:47], v[36:39]
	v_mfma_f32_16x16x32_bf16 v[40:43], v[28:31], v[44:47], v[40:43]
	v_mfma_f32_16x16x32_bf16 v[44:47], v[16:19], v[48:51], 0
	v_mfma_f32_16x16x32_bf16 v[48:51], v[24:27], v[48:51], 0
	v_mfma_f32_16x16x32_bf16 v[44:47], v[20:23], v[52:55], v[44:47]
	v_mfma_f32_16x16x32_bf16 v[48:51], v[28:31], v[52:55], v[48:51]
	v_mfma_f32_16x16x32_bf16 v[52:55], v[16:19], v[56:59], 0
	v_mfma_f32_16x16x32_bf16 v[56:59], v[24:27], v[56:59], 0
	v_mfma_f32_16x16x32_bf16 v[52:55], v[20:23], v[60:63], v[52:55]
	v_mfma_f32_16x16x32_bf16 v[56:59], v[28:31], v[60:63], v[56:59]
	s_barrier
	v_mov_b32_e32 v113, v185
	v_lshl_add_u64 v[244:245], s[22:23], 0, v[112:113]
	s_mov_b64 s[60:61], 0x100
	s_add_i32 s55, s55, s30
	v_lshl_add_u64 v[136:137], v[244:245], 0, s[60:61]
	s_mov_b32 m0, s55
	s_mov_b64 s[62:63], 0x40100
	s_add_i32 s56, s55, 0x2000
	ds_read_b128 v[60:63], v118 offset:16384
	ds_read_b128 v[88:91], v118 offset:17408
	ds_read_b128 v[92:95], v118 offset:18432
	ds_read_b128 v[104:107], v118 offset:19456
	ds_read_b128 v[108:111], v118 offset:20480
	ds_read_b128 v[124:127], v118 offset:21504
	ds_read_b128 v[128:131], v118 offset:22528
	ds_read_b128 v[132:135], v118 offset:23552
	global_load_lds_dwordx4 v[136:137], off
	v_lshl_add_u64 v[136:137], v[244:245], 0, s[62:63]
	s_mov_b32 m0, s56
	s_mov_b64 s[64:65], 0x80100
	s_add_i32 s57, s57, s30
	global_load_lds_dwordx4 v[136:137], off
	v_lshl_add_u64 v[136:137], v[244:245], 0, s[64:65]
	s_mov_b32 m0, s57
	s_mov_b64 s[66:67], 0xc0100
	s_add_i32 s58, s57, 0x2000
	global_load_lds_dwordx4 v[136:137], off
	v_lshl_add_u64 v[136:137], v[244:245], 0, s[66:67]
	s_mov_b32 m0, s58
	s_nop 0
	global_load_lds_dwordx4 v[136:137], off
	v_lshl_add_u64 v[136:137], v[206:207], 0, s[60:61]
	s_mov_b32 m0, s7
	s_nop 0
	global_load_lds_dwordx4 v[136:137], off
	v_lshl_add_u64 v[136:137], v[206:207], 0, s[62:63]
	s_mov_b32 m0, s31
	s_nop 0
	global_load_lds_dwordx4 v[136:137], off
	s_waitcnt vmcnt(24)
	s_waitcnt lgkmcnt(0)
	s_barrier
	s_waitcnt lgkmcnt(0)
	v_mfma_f32_16x16x32_bf16 v[136:139], v[0:3], v[60:63], 0
	v_mfma_f32_16x16x32_bf16 v[144:147], v[0:3], v[92:95], 0
	v_mfma_f32_16x16x32_bf16 v[152:155], v[0:3], v[108:111], 0
	v_mfma_f32_16x16x32_bf16 v[0:3], v[0:3], v[128:131], 0
	v_mfma_f32_16x16x32_bf16 v[136:139], v[4:7], v[88:91], v[136:139]
	v_mfma_f32_16x16x32_bf16 v[144:147], v[4:7], v[104:107], v[144:147]
	v_mfma_f32_16x16x32_bf16 v[152:155], v[4:7], v[124:127], v[152:155]
	v_mfma_f32_16x16x32_bf16 v[0:3], v[4:7], v[132:135], v[0:3]
	v_mfma_f32_16x16x32_bf16 v[4:7], v[8:11], v[128:131], 0
	v_mfma_f32_16x16x32_bf16 v[140:143], v[8:11], v[60:63], 0
	v_mfma_f32_16x16x32_bf16 v[148:151], v[8:11], v[92:95], 0
	v_mfma_f32_16x16x32_bf16 v[156:159], v[8:11], v[108:111], 0
	v_mfma_f32_16x16x32_bf16 v[4:7], v[12:15], v[132:135], v[4:7]
	v_mfma_f32_16x16x32_bf16 v[140:143], v[12:15], v[88:91], v[140:143]
	v_mfma_f32_16x16x32_bf16 v[148:151], v[12:15], v[104:107], v[148:151]
	v_mfma_f32_16x16x32_bf16 v[156:159], v[12:15], v[124:127], v[156:159]
	v_mfma_f32_16x16x32_bf16 v[8:11], v[16:19], v[60:63], 0
	v_mfma_f32_16x16x32_bf16 v[160:163], v[20:23], v[88:91], v[8:11]
	v_mfma_f32_16x16x32_bf16 v[8:11], v[24:27], v[60:63], 0
	v_mfma_f32_16x16x32_bf16 v[180:183], v[28:31], v[88:91], v[8:11]
	v_mfma_f32_16x16x32_bf16 v[8:11], v[16:19], v[92:95], 0
	v_mfma_f32_16x16x32_bf16 v[188:191], v[20:23], v[104:107], v[8:11]
	v_mfma_f32_16x16x32_bf16 v[8:11], v[24:27], v[92:95], 0
	v_mfma_f32_16x16x32_bf16 v[192:195], v[28:31], v[104:107], v[8:11]
	v_mfma_f32_16x16x32_bf16 v[8:11], v[16:19], v[108:111], 0
	v_mfma_f32_16x16x32_bf16 v[196:199], v[20:23], v[124:127], v[8:11]
	v_mfma_f32_16x16x32_bf16 v[8:11], v[24:27], v[108:111], 0
	v_mfma_f32_16x16x32_bf16 v[124:127], v[28:31], v[124:127], v[8:11]
	v_mfma_f32_16x16x32_bf16 v[8:11], v[16:19], v[128:131], 0
	v_mfma_f32_16x16x32_bf16 v[200:203], v[20:23], v[132:135], v[8:11]
	v_mfma_f32_16x16x32_bf16 v[8:11], v[24:27], v[128:131], 0
	v_mfma_f32_16x16x32_bf16 v[128:131], v[28:31], v[132:135], v[8:11]
	s_barrier
	s_add_i32 s59, 0, 0x18000
	s_add_i32 s61, 0, 0x1c000
	v_add_u32_e32 v113, s59, v119
	v_add_u32_e32 v119, s61, v119
	s_nop 0
	ds_read_b128 v[8:11], v113
	ds_read_b128 v[12:15], v113 offset:1024
	ds_read_b128 v[16:19], v113 offset:2048
	ds_read_b128 v[20:23], v113 offset:3072
	ds_read_b128 v[132:135], v119
	ds_read_b128 v[212:215], v119 offset:1024
	ds_read_b128 v[216:219], v119 offset:2048
	ds_read_b128 v[220:223], v119 offset:3072
	s_mov_b32 m0, s34
	v_lshl_add_u64 v[88:89], v[206:207], 0, s[64:65]
	ds_read_b128 v[24:27], v118 offset:32768
	ds_read_b128 v[28:31], v118 offset:33792
	ds_read_b128 v[60:63], v118 offset:34816
	ds_read_b128 v[224:227], v118 offset:35840
	ds_read_b128 v[228:231], v118 offset:36864
	ds_read_b128 v[232:235], v118 offset:37888
	ds_read_b128 v[236:239], v118 offset:38912
	ds_read_b128 v[240:243], v118 offset:39936
	global_load_lds_dwordx4 v[88:89], off
	v_lshl_add_u64 v[88:89], v[206:207], 0, s[66:67]
	s_mov_b32 m0, s35
	s_nop 0
	global_load_lds_dwordx4 v[88:89], off
	s_waitcnt vmcnt(8)
	s_waitcnt lgkmcnt(0)
	s_barrier
	s_waitcnt lgkmcnt(0)
	v_mfma_f32_16x16x32_bf16 v[64:67], v[8:11], v[24:27], v[64:67]
	v_mfma_f32_16x16x32_bf16 v[172:175], v[12:15], v[28:31], v[64:67]
	v_mfma_f32_16x16x32_bf16 v[64:67], v[16:19], v[24:27], v[68:71]
	v_mfma_f32_16x16x32_bf16 v[164:167], v[20:23], v[28:31], v[64:67]
	v_mfma_f32_16x16x32_bf16 v[64:67], v[8:11], v[60:63], v[72:75]
	v_mfma_f32_16x16x32_bf16 v[108:111], v[12:15], v[224:227], v[64:67]
	v_mfma_f32_16x16x32_bf16 v[64:67], v[16:19], v[60:63], v[76:79]
	v_mfma_f32_16x16x32_bf16 v[104:107], v[20:23], v[224:227], v[64:67]
	v_mfma_f32_16x16x32_bf16 v[64:67], v[8:11], v[228:231], v[80:83]
	v_mfma_f32_16x16x32_bf16 v[92:95], v[12:15], v[232:235], v[64:67]
	v_mfma_f32_16x16x32_bf16 v[64:67], v[16:19], v[228:231], v[84:87]
	v_mfma_f32_16x16x32_bf16 v[88:91], v[20:23], v[232:235], v[64:67]
	v_mfma_f32_16x16x32_bf16 v[64:67], v[8:11], v[236:239], v[96:99]
	v_mfma_f32_16x16x32_bf16 v[76:79], v[12:15], v[240:243], v[64:67]
	v_mfma_f32_16x16x32_bf16 v[64:67], v[16:19], v[236:239], v[100:103]
	v_mfma_f32_16x16x32_bf16 v[68:71], v[20:23], v[240:243], v[64:67]
	v_mfma_f32_16x16x32_bf16 v[64:67], v[132:135], v[24:27], v[120:123]
	v_mfma_f32_16x16x32_bf16 v[24:27], v[216:219], v[24:27], v[32:35]
	v_mfma_f32_16x16x32_bf16 v[168:171], v[220:223], v[28:31], v[24:27]
	v_mfma_f32_16x16x32_bf16 v[24:27], v[132:135], v[60:63], v[36:39]
	v_mfma_f32_16x16x32_bf16 v[100:103], v[212:215], v[224:227], v[24:27]
	v_mfma_f32_16x16x32_bf16 v[24:27], v[216:219], v[60:63], v[40:43]
	v_mfma_f32_16x16x32_bf16 v[96:99], v[220:223], v[224:227], v[24:27]
	v_mfma_f32_16x16x32_bf16 v[24:27], v[132:135], v[228:231], v[44:47]
	v_mfma_f32_16x16x32_bf16 v[84:87], v[212:215], v[232:235], v[24:27]
	v_mfma_f32_16x16x32_bf16 v[24:27], v[216:219], v[228:231], v[48:51]
	v_mfma_f32_16x16x32_bf16 v[80:83], v[220:223], v[232:235], v[24:27]
	v_mfma_f32_16x16x32_bf16 v[24:27], v[132:135], v[236:239], v[52:55]
	v_mfma_f32_16x16x32_bf16 v[176:179], v[212:215], v[28:31], v[64:67]
	v_mfma_f32_16x16x32_bf16 v[64:67], v[212:215], v[240:243], v[24:27]
	v_mfma_f32_16x16x32_bf16 v[24:27], v[216:219], v[236:239], v[56:59]
	v_mfma_f32_16x16x32_bf16 v[52:55], v[220:223], v[240:243], v[24:27]
	s_barrier
; #define PG8_WAIT_V(n) asm volatile("s_waitcnt vmcnt(" #n ")" ::: "memory")
; #define PG8_WAIT_VP() asm volatile("s_waitcnt vmcnt(%0)" :: "n"(8 + Epi::NST) : "memory")
; template <class Epi, class Sched>
; __device__ __forceinline__ void gemm_phase(PG8_LAS unsigned char* lds, const Sched& S, const Epi& E, int tid_in) {
;     ...
;         { const int t = 0; PG8_KITER(PG8_WAIT_VP()); }
;         for (int t = 2; t < nt; t += 2) PG8_KITER(PG8_WAIT_V(8));
	s_mov_b64 s[64:65], 0x180
	s_add_i32 s59, s59, s30
	s_nop 2
	v_lshl_add_u64 v[24:25], v[244:245], 0, s[64:65]
	s_mov_b32 m0, s59
	s_mov_b64 s[66:67], 0x40180
	s_add_i32 s60, s59, 0x2000
	ds_read_b128 v[32:35], v118 offset:49152
	ds_read_b128 v[36:39], v118 offset:50176
	ds_read_b128 v[120:123], v118 offset:51200
	ds_read_b128 v[224:227], v118 offset:52224
	ds_read_b128 v[228:231], v118 offset:53248
	ds_read_b128 v[232:235], v118 offset:54272
	ds_read_b128 v[236:239], v118 offset:55296
	ds_read_b128 v[240:243], v118 offset:56320
	global_load_lds_dwordx4 v[24:25], off
	v_lshl_add_u64 v[24:25], v[244:245], 0, s[66:67]
	s_mov_b32 m0, s60
	s_add_i32 s61, s61, s30
	global_load_lds_dwordx4 v[24:25], off
	v_lshl_add_u64 v[24:25], v[244:245], 0, s[70:71]
	s_mov_b32 m0, s61
	s_add_i32 s62, s61, 0x2000
	global_load_lds_dwordx4 v[24:25], off
	v_lshl_add_u64 v[24:25], v[244:245], 0, s[72:73]
	s_mov_b32 m0, s62
	s_nop 0
	global_load_lds_dwordx4 v[24:25], off
	v_lshl_add_u64 v[24:25], v[206:207], 0, s[64:65]
	s_mov_b32 m0, s44
	s_nop 0
	global_load_lds_dwordx4 v[24:25], off
	v_lshl_add_u64 v[24:25], v[206:207], 0, s[66:67]
	s_mov_b32 m0, s45
	s_nop 0
	global_load_lds_dwordx4 v[24:25], off
	s_waitcnt vmcnt(8)
	s_waitcnt lgkmcnt(0)
	s_barrier
	s_waitcnt lgkmcnt(0)
	v_mfma_f32_16x16x32_bf16 v[24:27], v[8:11], v[32:35], v[136:139]
	v_mfma_f32_16x16x32_bf16 v[72:75], v[12:15], v[36:39], v[24:27]
	v_mfma_f32_16x16x32_bf16 v[24:27], v[16:19], v[32:35], v[140:143]
	v_mfma_f32_16x16x32_bf16 v[60:63], v[20:23], v[36:39], v[24:27]
	v_mfma_f32_16x16x32_bf16 v[24:27], v[8:11], v[120:123], v[144:147]
	v_mfma_f32_16x16x32_bf16 v[44:47], v[12:15], v[224:227], v[24:27]
	v_mfma_f32_16x16x32_bf16 v[24:27], v[16:19], v[120:123], v[148:151]
	v_mfma_f32_16x16x32_bf16 v[40:43], v[20:23], v[224:227], v[24:27]
	v_mfma_f32_16x16x32_bf16 v[24:27], v[8:11], v[228:231], v[152:155]
	v_mfma_f32_16x16x32_bf16 v[0:3], v[8:11], v[236:239], v[0:3]
	v_mfma_f32_16x16x32_bf16 v[28:31], v[12:15], v[232:235], v[24:27]
	v_mfma_f32_16x16x32_bf16 v[24:27], v[16:19], v[228:231], v[156:159]
	v_mfma_f32_16x16x32_bf16 v[12:15], v[12:15], v[240:243], v[0:3]
	v_mfma_f32_16x16x32_bf16 v[0:3], v[16:19], v[236:239], v[4:7]
	v_mfma_f32_16x16x32_bf16 v[24:27], v[20:23], v[232:235], v[24:27]
	v_mfma_f32_16x16x32_bf16 v[8:11], v[20:23], v[240:243], v[0:3]
	v_mfma_f32_16x16x32_bf16 v[0:3], v[132:135], v[32:35], v[160:163]
	v_mfma_f32_16x16x32_bf16 v[56:59], v[212:215], v[36:39], v[0:3]
	v_mfma_f32_16x16x32_bf16 v[0:3], v[216:219], v[32:35], v[180:183]
	v_mfma_f32_16x16x32_bf16 v[48:51], v[220:223], v[36:39], v[0:3]
	v_mfma_f32_16x16x32_bf16 v[0:3], v[132:135], v[120:123], v[188:191]
	v_mfma_f32_16x16x32_bf16 v[36:39], v[212:215], v[224:227], v[0:3]
	v_mfma_f32_16x16x32_bf16 v[0:3], v[216:219], v[120:123], v[192:195]
	v_mfma_f32_16x16x32_bf16 v[32:35], v[220:223], v[224:227], v[0:3]
	v_mfma_f32_16x16x32_bf16 v[0:3], v[132:135], v[228:231], v[196:199]
	v_mfma_f32_16x16x32_bf16 v[20:23], v[212:215], v[232:235], v[0:3]
	v_mfma_f32_16x16x32_bf16 v[0:3], v[216:219], v[228:231], v[124:127]
	v_mfma_f32_16x16x32_bf16 v[16:19], v[220:223], v[232:235], v[0:3]
	v_mfma_f32_16x16x32_bf16 v[0:3], v[132:135], v[236:239], v[200:203]
	v_mfma_f32_16x16x32_bf16 v[4:7], v[212:215], v[240:243], v[0:3]
	v_mfma_f32_16x16x32_bf16 v[0:3], v[216:219], v[236:239], v[128:131]
	v_mfma_f32_16x16x32_bf16 v[0:3], v[220:223], v[240:243], v[0:3]
	s_barrier
	s_add_u32 s20, s20, 0x80180
	s_addc_u32 s21, s21, 0
	s_add_u32 s63, s22, 0x200
	s_addc_u32 s64, s23, 0
	s_mov_b32 s65, 0
.LBB0_1446:
	ds_read_b128 v[120:123], v116
	ds_read_b128 v[124:127], v116 offset:1024
	ds_read_b128 v[128:131], v116 offset:2048
	ds_read_b128 v[132:135], v116 offset:3072
	ds_read_b128 v[136:139], v117
	ds_read_b128 v[140:143], v117 offset:1024
	ds_read_b128 v[144:147], v117 offset:2048
	ds_read_b128 v[148:151], v117 offset:3072
	s_add_u32 s66, s20, 0xfff80080
	s_addc_u32 s67, s21, -1
	s_cmp_eq_u32 s65, 28
	s_cselect_b64 vcc, -1, 0
	s_and_b64 s[22:23], vcc, exec
	v_cndmask_b32_e32 v184, v114, v186, vcc
	s_cselect_b32 s23, s15, s67
	s_cselect_b32 s22, s14, s66
	v_cndmask_b32_e32 v206, v112, v211, vcc
	s_cselect_b32 s67, s17, s64
	s_cselect_b32 s66, s16, s63
	s_mov_b32 m0, s53
	v_lshl_add_u64 v[212:213], s[20:21], 0, v[114:115]
	ds_read_b128 v[152:155], v118
	ds_read_b128 v[156:159], v118 offset:1024
	ds_read_b128 v[160:163], v118 offset:2048
	ds_read_b128 v[180:183], v118 offset:3072
	ds_read_b128 v[188:191], v118 offset:4096
	ds_read_b128 v[192:195], v118 offset:5120
	ds_read_b128 v[196:199], v118 offset:6144
	ds_read_b128 v[200:203], v118 offset:7168
	global_load_lds_dwordx4 v[212:213], off
	v_lshl_add_u64 v[212:213], v[212:213], 0, s[88:89]
	s_mov_b32 m0, s54
	s_nop 0
	global_load_lds_dwordx4 v[212:213], off
	s_waitcnt vmcnt(8)
	s_waitcnt lgkmcnt(0)
	s_barrier
	s_waitcnt lgkmcnt(0)
	v_mfma_f32_16x16x32_bf16 v[172:175], v[120:123], v[152:155], v[172:175]
	v_mfma_f32_16x16x32_bf16 v[164:167], v[128:131], v[152:155], v[164:167]
	v_mfma_f32_16x16x32_bf16 v[108:111], v[120:123], v[160:163], v[108:111]
	v_mfma_f32_16x16x32_bf16 v[104:107], v[128:131], v[160:163], v[104:107]
	v_mfma_f32_16x16x32_bf16 v[92:95], v[120:123], v[188:191], v[92:95]
	v_mfma_f32_16x16x32_bf16 v[88:91], v[128:131], v[188:191], v[88:91]
	v_mfma_f32_16x16x32_bf16 v[76:79], v[120:123], v[196:199], v[76:79]
	v_mfma_f32_16x16x32_bf16 v[68:71], v[128:131], v[196:199], v[68:71]
	v_mfma_f32_16x16x32_bf16 v[172:175], v[124:127], v[156:159], v[172:175]
	v_mfma_f32_16x16x32_bf16 v[164:167], v[132:135], v[156:159], v[164:167]
	v_mfma_f32_16x16x32_bf16 v[108:111], v[124:127], v[180:183], v[108:111]
	v_mfma_f32_16x16x32_bf16 v[104:107], v[132:135], v[180:183], v[104:107]
	v_mfma_f32_16x16x32_bf16 v[92:95], v[124:127], v[192:195], v[92:95]
	v_mfma_f32_16x16x32_bf16 v[88:91], v[132:135], v[192:195], v[88:91]
	v_mfma_f32_16x16x32_bf16 v[76:79], v[124:127], v[200:203], v[76:79]
	v_mfma_f32_16x16x32_bf16 v[68:71], v[132:135], v[200:203], v[68:71]
	v_mfma_f32_16x16x32_bf16 v[176:179], v[136:139], v[152:155], v[176:179]
	v_mfma_f32_16x16x32_bf16 v[100:103], v[136:139], v[160:163], v[100:103]
	v_mfma_f32_16x16x32_bf16 v[96:99], v[144:147], v[160:163], v[96:99]
	v_mfma_f32_16x16x32_bf16 v[84:87], v[136:139], v[188:191], v[84:87]
	v_mfma_f32_16x16x32_bf16 v[80:83], v[144:147], v[188:191], v[80:83]
	v_mfma_f32_16x16x32_bf16 v[64:67], v[136:139], v[196:199], v[64:67]
	v_mfma_f32_16x16x32_bf16 v[52:55], v[144:147], v[196:199], v[52:55]
	v_mfma_f32_16x16x32_bf16 v[176:179], v[140:143], v[156:159], v[176:179]
	v_mfma_f32_16x16x32_bf16 v[152:155], v[144:147], v[152:155], v[168:171]
	v_mfma_f32_16x16x32_bf16 v[100:103], v[140:143], v[180:183], v[100:103]
	v_mfma_f32_16x16x32_bf16 v[96:99], v[148:151], v[180:183], v[96:99]
	v_mfma_f32_16x16x32_bf16 v[84:87], v[140:143], v[192:195], v[84:87]
	v_mfma_f32_16x16x32_bf16 v[80:83], v[148:151], v[192:195], v[80:83]
	v_mfma_f32_16x16x32_bf16 v[64:67], v[140:143], v[200:203], v[64:67]
	v_mfma_f32_16x16x32_bf16 v[52:55], v[148:151], v[200:203], v[52:55]
	v_mfma_f32_16x16x32_bf16 v[152:155], v[148:151], v[156:159], v[152:155]
	s_barrier
	v_mov_b32_e32 v207, v185
	s_mov_b32 m0, s55
	v_lshl_add_u64 v[216:217], s[66:67], 0, v[206:207]
	ds_read_b128 v[156:159], v118 offset:16384
	ds_read_b128 v[160:163], v118 offset:17408
	ds_read_b128 v[168:171], v118 offset:18432
	ds_read_b128 v[180:183], v118 offset:19456
	ds_read_b128 v[188:191], v118 offset:20480
	ds_read_b128 v[192:195], v118 offset:21504
	ds_read_b128 v[196:199], v118 offset:22528
	ds_read_b128 v[200:203], v118 offset:23552
	global_load_lds_dwordx4 v206, s[66:67]
	v_lshl_add_u64 v[206:207], v[216:217], 0, s[88:89]
	s_mov_b32 m0, s56
	s_nop 0
	global_load_lds_dwordx4 v[206:207], off
	v_lshl_add_u64 v[206:207], v[216:217], 0, s[90:91]
	s_mov_b32 m0, s57
	s_nop 0
	global_load_lds_dwordx4 v[206:207], off
	v_lshl_add_u64 v[206:207], v[216:217], 0, s[96:97]
	s_mov_b32 m0, s58
	s_nop 0
	global_load_lds_dwordx4 v[206:207], off
	v_lshl_add_u64 v[206:207], s[22:23], 0, v[184:185]
	s_mov_b32 m0, s7
	v_lshl_add_u64 v[212:213], v[206:207], 0, s[88:89]
	global_load_lds_dwordx4 v[206:207], off
	s_mov_b32 m0, s31
	s_nop 0
	global_load_lds_dwordx4 v[212:213], off
	s_waitcnt vmcnt(8)
	s_waitcnt lgkmcnt(0)
	s_barrier
	s_waitcnt lgkmcnt(0)
	v_mfma_f32_16x16x32_bf16 v[72:75], v[120:123], v[156:159], v[72:75]
	v_mfma_f32_16x16x32_bf16 v[60:63], v[128:131], v[156:159], v[60:63]
	v_mfma_f32_16x16x32_bf16 v[44:47], v[120:123], v[168:171], v[44:47]
	v_mfma_f32_16x16x32_bf16 v[40:43], v[128:131], v[168:171], v[40:43]
	v_mfma_f32_16x16x32_bf16 v[28:31], v[120:123], v[188:191], v[28:31]
	v_mfma_f32_16x16x32_bf16 v[24:27], v[128:131], v[188:191], v[24:27]
	v_mfma_f32_16x16x32_bf16 v[12:15], v[120:123], v[196:199], v[12:15]
	v_mfma_f32_16x16x32_bf16 v[8:11], v[128:131], v[196:199], v[8:11]
	v_mfma_f32_16x16x32_bf16 v[72:75], v[124:127], v[160:163], v[72:75]
	v_mfma_f32_16x16x32_bf16 v[60:63], v[132:135], v[160:163], v[60:63]
	v_mfma_f32_16x16x32_bf16 v[44:47], v[124:127], v[180:183], v[44:47]
	v_mfma_f32_16x16x32_bf16 v[40:43], v[132:135], v[180:183], v[40:43]
	v_mfma_f32_16x16x32_bf16 v[28:31], v[124:127], v[192:195], v[28:31]
	v_mfma_f32_16x16x32_bf16 v[24:27], v[132:135], v[192:195], v[24:27]
	v_mfma_f32_16x16x32_bf16 v[12:15], v[124:127], v[200:203], v[12:15]
	v_mfma_f32_16x16x32_bf16 v[8:11], v[132:135], v[200:203], v[8:11]
	v_mfma_f32_16x16x32_bf16 v[56:59], v[136:139], v[156:159], v[56:59]
	v_mfma_f32_16x16x32_bf16 v[48:51], v[144:147], v[156:159], v[48:51]
	v_mfma_f32_16x16x32_bf16 v[36:39], v[136:139], v[168:171], v[36:39]
	v_mfma_f32_16x16x32_bf16 v[32:35], v[144:147], v[168:171], v[32:35]
	v_mfma_f32_16x16x32_bf16 v[20:23], v[136:139], v[188:191], v[20:23]
	v_mfma_f32_16x16x32_bf16 v[16:19], v[144:147], v[188:191], v[16:19]
	v_mfma_f32_16x16x32_bf16 v[4:7], v[136:139], v[196:199], v[4:7]
	v_mfma_f32_16x16x32_bf16 v[0:3], v[144:147], v[196:199], v[0:3]
	v_mfma_f32_16x16x32_bf16 v[56:59], v[140:143], v[160:163], v[56:59]
	v_mfma_f32_16x16x32_bf16 v[48:51], v[148:151], v[160:163], v[48:51]
	v_mfma_f32_16x16x32_bf16 v[36:39], v[140:143], v[180:183], v[36:39]
	v_mfma_f32_16x16x32_bf16 v[32:35], v[148:151], v[180:183], v[32:35]
	v_mfma_f32_16x16x32_bf16 v[20:23], v[140:143], v[192:195], v[20:23]
	v_mfma_f32_16x16x32_bf16 v[16:19], v[148:151], v[192:195], v[16:19]
	v_mfma_f32_16x16x32_bf16 v[4:7], v[140:143], v[200:203], v[4:7]
	v_mfma_f32_16x16x32_bf16 v[0:3], v[148:151], v[200:203], v[0:3]
	s_barrier
; #define PG8_WAIT_V(n) asm volatile("s_waitcnt vmcnt(" #n ")" ::: "memory")
; #define PG8_WAIT_VP() asm volatile("s_waitcnt vmcnt(%0)" :: "n"(8 + Epi::NST) : "memory")
; #define PG8_BAR __builtin_amdgcn_s_barrier()
; template <class Epi, class Sched>
; __device__ __forceinline__ void gemm_phase(PG8_LAS unsigned char* lds, const Sched& S, const Epi& E, int tid_in) {
;     ...
;         { const int t = 0; PG8_KITER(PG8_WAIT_VP()); }
;         for (int t = 2; t < nt; t += 2) PG8_KITER(PG8_WAIT_V(8));
;     ...
;         if (wr == 0) PG8_BAR;
	ds_read_b128 v[120:123], v113
	ds_read_b128 v[124:127], v113 offset:1024
	ds_read_b128 v[128:131], v113 offset:2048
	ds_read_b128 v[132:135], v113 offset:3072
	ds_read_b128 v[136:139], v119
	ds_read_b128 v[140:143], v119 offset:1024
	ds_read_b128 v[144:147], v119 offset:2048
	ds_read_b128 v[148:151], v119 offset:3072
	s_mov_b32 m0, s34
	v_lshl_add_u64 v[168:169], v[206:207], 0, s[90:91]
	ds_read_b128 v[156:159], v118 offset:32768
	ds_read_b128 v[160:163], v118 offset:33792
	ds_read_b128 v[180:183], v118 offset:34816
	ds_read_b128 v[188:191], v118 offset:35840
	ds_read_b128 v[192:195], v118 offset:36864
	ds_read_b128 v[196:199], v118 offset:37888
	ds_read_b128 v[200:203], v118 offset:38912
	ds_read_b128 v[212:215], v118 offset:39936
	global_load_lds_dwordx4 v[168:169], off
	v_lshl_add_u64 v[168:169], v[206:207], 0, s[96:97]
	s_mov_b32 m0, s35
	s_nop 0
	global_load_lds_dwordx4 v[168:169], off
	s_waitcnt vmcnt(8)
	s_waitcnt lgkmcnt(0)
	s_barrier
	s_waitcnt lgkmcnt(0)
	v_mfma_f32_16x16x32_bf16 v[168:171], v[120:123], v[156:159], v[172:175]
	v_mfma_f32_16x16x32_bf16 v[164:167], v[128:131], v[156:159], v[164:167]
	v_mfma_f32_16x16x32_bf16 v[108:111], v[120:123], v[180:183], v[108:111]
	v_mfma_f32_16x16x32_bf16 v[104:107], v[128:131], v[180:183], v[104:107]
	v_mfma_f32_16x16x32_bf16 v[92:95], v[120:123], v[192:195], v[92:95]
	v_mfma_f32_16x16x32_bf16 v[88:91], v[128:131], v[192:195], v[88:91]
	v_mfma_f32_16x16x32_bf16 v[76:79], v[120:123], v[200:203], v[76:79]
	v_mfma_f32_16x16x32_bf16 v[68:71], v[128:131], v[200:203], v[68:71]
	v_mfma_f32_16x16x32_bf16 v[172:175], v[124:127], v[160:163], v[168:171]
	v_mfma_f32_16x16x32_bf16 v[164:167], v[132:135], v[160:163], v[164:167]
	v_mfma_f32_16x16x32_bf16 v[108:111], v[124:127], v[188:191], v[108:111]
	v_mfma_f32_16x16x32_bf16 v[104:107], v[132:135], v[188:191], v[104:107]
	v_mfma_f32_16x16x32_bf16 v[92:95], v[124:127], v[196:199], v[92:95]
	v_mfma_f32_16x16x32_bf16 v[88:91], v[132:135], v[196:199], v[88:91]
	v_mfma_f32_16x16x32_bf16 v[76:79], v[124:127], v[212:215], v[76:79]
	v_mfma_f32_16x16x32_bf16 v[68:71], v[132:135], v[212:215], v[68:71]
	v_mfma_f32_16x16x32_bf16 v[168:171], v[136:139], v[156:159], v[176:179]
	v_mfma_f32_16x16x32_bf16 v[152:155], v[144:147], v[156:159], v[152:155]
	v_mfma_f32_16x16x32_bf16 v[100:103], v[136:139], v[180:183], v[100:103]
	v_mfma_f32_16x16x32_bf16 v[96:99], v[144:147], v[180:183], v[96:99]
	v_mfma_f32_16x16x32_bf16 v[84:87], v[136:139], v[192:195], v[84:87]
	v_mfma_f32_16x16x32_bf16 v[80:83], v[144:147], v[192:195], v[80:83]
	v_mfma_f32_16x16x32_bf16 v[64:67], v[136:139], v[200:203], v[64:67]
	v_mfma_f32_16x16x32_bf16 v[52:55], v[144:147], v[200:203], v[52:55]
	v_mfma_f32_16x16x32_bf16 v[176:179], v[140:143], v[160:163], v[168:171]
	v_mfma_f32_16x16x32_bf16 v[168:171], v[148:151], v[160:163], v[152:155]
	v_mfma_f32_16x16x32_bf16 v[100:103], v[140:143], v[188:191], v[100:103]
	v_mfma_f32_16x16x32_bf16 v[96:99], v[148:151], v[188:191], v[96:99]
	v_mfma_f32_16x16x32_bf16 v[84:87], v[140:143], v[196:199], v[84:87]
	v_mfma_f32_16x16x32_bf16 v[80:83], v[148:151], v[196:199], v[80:83]
	v_mfma_f32_16x16x32_bf16 v[64:67], v[140:143], v[212:215], v[64:67]
	v_mfma_f32_16x16x32_bf16 v[52:55], v[148:151], v[212:215], v[52:55]
	s_barrier
	s_mov_b32 m0, s59
	v_lshl_add_u64 v[212:213], v[216:217], 0, s[84:85]
	ds_read_b128 v[152:155], v118 offset:49152
	ds_read_b128 v[156:159], v118 offset:50176
	ds_read_b128 v[160:163], v118 offset:51200
	ds_read_b128 v[180:183], v118 offset:52224
	ds_read_b128 v[188:191], v118 offset:53248
	ds_read_b128 v[192:195], v118 offset:54272
	ds_read_b128 v[196:199], v118 offset:55296
	ds_read_b128 v[200:203], v118 offset:56320
	global_load_lds_dwordx4 v[212:213], off
	v_lshl_add_u64 v[212:213], v[216:217], 0, s[94:95]
	s_mov_b32 m0, s60
	s_nop 0
	global_load_lds_dwordx4 v[212:213], off
	v_lshl_add_u64 v[212:213], v[216:217], 0, s[80:81]
	s_mov_b32 m0, s61
	s_nop 0
	global_load_lds_dwordx4 v[212:213], off
	v_lshl_add_u64 v[212:213], v[216:217], 0, s[78:79]
	s_mov_b32 m0, s62
	s_nop 0
	global_load_lds_dwordx4 v[212:213], off
	v_lshl_add_u64 v[212:213], v[206:207], 0, s[84:85]
	s_mov_b32 m0, s44
	v_lshl_add_u64 v[206:207], v[206:207], 0, s[94:95]
	global_load_lds_dwordx4 v[212:213], off
	s_mov_b32 m0, s45
	s_nop 0
	global_load_lds_dwordx4 v[206:207], off
	s_waitcnt vmcnt(8)
	s_waitcnt lgkmcnt(0)
	s_barrier
	s_waitcnt lgkmcnt(0)
	v_mfma_f32_16x16x32_bf16 v[72:75], v[120:123], v[152:155], v[72:75]
	v_mfma_f32_16x16x32_bf16 v[60:63], v[128:131], v[152:155], v[60:63]
	v_mfma_f32_16x16x32_bf16 v[44:47], v[120:123], v[160:163], v[44:47]
	v_mfma_f32_16x16x32_bf16 v[40:43], v[128:131], v[160:163], v[40:43]
	v_mfma_f32_16x16x32_bf16 v[28:31], v[120:123], v[188:191], v[28:31]
	v_mfma_f32_16x16x32_bf16 v[24:27], v[128:131], v[188:191], v[24:27]
	v_mfma_f32_16x16x32_bf16 v[12:15], v[120:123], v[196:199], v[12:15]
	v_mfma_f32_16x16x32_bf16 v[8:11], v[128:131], v[196:199], v[8:11]
	v_mfma_f32_16x16x32_bf16 v[72:75], v[124:127], v[156:159], v[72:75]
	v_mfma_f32_16x16x32_bf16 v[60:63], v[132:135], v[156:159], v[60:63]
	v_mfma_f32_16x16x32_bf16 v[44:47], v[124:127], v[180:183], v[44:47]
	v_mfma_f32_16x16x32_bf16 v[40:43], v[132:135], v[180:183], v[40:43]
	v_mfma_f32_16x16x32_bf16 v[28:31], v[124:127], v[192:195], v[28:31]
	v_mfma_f32_16x16x32_bf16 v[24:27], v[132:135], v[192:195], v[24:27]
	v_mfma_f32_16x16x32_bf16 v[12:15], v[124:127], v[200:203], v[12:15]
	v_mfma_f32_16x16x32_bf16 v[8:11], v[132:135], v[200:203], v[8:11]
	v_mfma_f32_16x16x32_bf16 v[56:59], v[136:139], v[152:155], v[56:59]
	v_mfma_f32_16x16x32_bf16 v[48:51], v[144:147], v[152:155], v[48:51]
	v_mfma_f32_16x16x32_bf16 v[36:39], v[136:139], v[160:163], v[36:39]
	v_mfma_f32_16x16x32_bf16 v[32:35], v[144:147], v[160:163], v[32:35]
	v_mfma_f32_16x16x32_bf16 v[20:23], v[136:139], v[188:191], v[20:23]
	v_mfma_f32_16x16x32_bf16 v[16:19], v[144:147], v[188:191], v[16:19]
	v_mfma_f32_16x16x32_bf16 v[4:7], v[136:139], v[196:199], v[4:7]
	v_mfma_f32_16x16x32_bf16 v[0:3], v[144:147], v[196:199], v[0:3]
	v_mfma_f32_16x16x32_bf16 v[56:59], v[140:143], v[156:159], v[56:59]
	v_mfma_f32_16x16x32_bf16 v[48:51], v[148:151], v[156:159], v[48:51]
	v_mfma_f32_16x16x32_bf16 v[36:39], v[140:143], v[180:183], v[36:39]
	v_mfma_f32_16x16x32_bf16 v[32:35], v[148:151], v[180:183], v[32:35]
	v_mfma_f32_16x16x32_bf16 v[20:23], v[140:143], v[192:195], v[20:23]
	v_mfma_f32_16x16x32_bf16 v[16:19], v[148:151], v[192:195], v[16:19]
	v_mfma_f32_16x16x32_bf16 v[4:7], v[140:143], v[200:203], v[4:7]
	v_mfma_f32_16x16x32_bf16 v[0:3], v[148:151], v[200:203], v[0:3]
	s_barrier
	s_add_i32 s65, s65, 2
	s_add_u32 s20, s20, 0x100
	s_addc_u32 s21, s21, 0
	s_add_u32 s63, s63, 0x100
	s_addc_u32 s64, s64, 0
	s_cmp_gt_u32 s65, 29
	s_cbranch_scc0 .LBB0_1446
	s_and_b64 vcc, exec, s[12:13]
	s_cbranch_vccz .LBB0_1449
	s_barrier
